# remove all s_setprio from the GEMM K-loops (equal priority for compute and load wave halves) on top of v54
# speedup vs baseline: 1.0025x; 1.0025x over previous
; #define PG8_STAGE(bufoff, gbase, voff) do { _Pragma("unroll") for (int _i = 0; _i < 2; ++_i) \
;         __builtin_amdgcn_global_load_lds((const unsigned*)((const char*)(gbase) + (voff)[_i]), (PG8_LAS unsigned*)(lds + (bufoff) + ldsw + _i * 8192), 16, 0, 0); } while (0)
; #define PG8_LDA(dst, b, h) do { _Pragma("unroll") for (int m = 0; m < 4; ++m) _Pragma("unroll") for (int k = 0; k < 2; ++k) dst[m][k] = *(const PG8_LAS bf16x8*)(lds + PG8_SA(b, h) + aoff + m * 2048 + k * 1024); } while (0)
; #define PG8_MMA(ai, bj, At, Bt) do { __builtin_amdgcn_s_setprio(3); _Pragma("unroll") for (int m = 0; m < 4; ++m) _Pragma("unroll") for (int n = 0; n < 2; ++n) _Pragma("unroll") for (int k = 0; k < 2; ++k) \
;         acc[ai][bj][m][n] = __builtin_amdgcn_mfma_f32_16x16x32_bf16(Bt[n][k], At[m][k], acc[ai][bj][m][n], 0, 0, 0); __builtin_amdgcn_s_setprio(0); } while (0)
; #define PG8_WAIT_V(n) asm volatile("s_waitcnt vmcnt(" #n ")" ::: "memory")
; #define PG8_WAIT_L(n) asm volatile("s_waitcnt lgkmcnt(" #n ")" ::: "memory")
; #define PG8_BAR __builtin_amdgcn_s_barrier()
; #define PG8_SCHED __builtin_amdgcn_sched_barrier(0)
; template <class Epi, class Sched, bool ALIGN_EPI = false, bool SP2 = false>
; __device__ __forceinline__ void gemm_phase(PG8_LAS unsigned char* lds, const Gemm g, const Sched& S, const Epi& E) {
;     ...
;             PG8_WAIT_V(8); PG8_WAIT_L(0); PG8_BAR; PG8_MMA(0, 0, At, B0); PG8_MMA(0, 1, At, B1); PG8_BAR; PG8_SCHED;
;             PG8_LDA(At, 0, 1); PG8_STAGE(PG8_SB(0, 0), b2, voffB); PG8_STAGE(PG8_SB(0, 1), b2 + hstepB, voffB); PG8_STAGE(PG8_SA(0, 0), a2, voffA);
;             PG8_WAIT_V(8); PG8_WAIT_L(0); PG8_BAR; PG8_MMA(1, 0, At, B0); PG8_MMA(1, 1, At, B1); PG8_BAR; PG8_SCHED;
.Lengw1_e:
	s_waitcnt lgkmcnt(0)
	s_barrier
	v_mfma_f32_16x16x32_bf16 v[126:129], v[130:133], v[192:195], v[126:129]
	v_mfma_f32_16x16x32_bf16 v[126:129], v[134:137], v[196:199], v[126:129]
	v_mfma_f32_16x16x32_bf16 v[118:121], v[156:159], v[192:195], v[118:121]
	v_mfma_f32_16x16x32_bf16 v[118:121], v[172:175], v[196:199], v[118:121]
	v_mfma_f32_16x16x32_bf16 v[102:105], v[156:159], v[200:203], v[102:105]
	v_mfma_f32_16x16x32_bf16 v[102:105], v[172:175], v[204:207], v[102:105]
	v_mfma_f32_16x16x32_bf16 v[110:113], v[130:133], v[200:203], v[110:113]
	v_mfma_f32_16x16x32_bf16 v[110:113], v[134:137], v[204:207], v[110:113]
	v_mfma_f32_16x16x32_bf16 v[94:97], v[130:133], v[208:211], v[94:97]
	v_mfma_f32_16x16x32_bf16 v[94:97], v[134:137], v[212:215], v[94:97]
	v_mfma_f32_16x16x32_bf16 v[86:89], v[156:159], v[208:211], v[86:89]
	v_mfma_f32_16x16x32_bf16 v[86:89], v[172:175], v[212:215], v[86:89]
	v_mfma_f32_16x16x32_bf16 v[70:73], v[156:159], v[216:219], v[70:73]
	v_mfma_f32_16x16x32_bf16 v[70:73], v[172:175], v[220:223], v[70:73]
	v_mfma_f32_16x16x32_bf16 v[78:81], v[130:133], v[216:219], v[78:81]
	v_mfma_f32_16x16x32_bf16 v[78:81], v[134:137], v[220:223], v[78:81]
	v_mfma_f32_16x16x32_bf16 v[122:125], v[176:179], v[192:195], v[122:125]
	v_mfma_f32_16x16x32_bf16 v[122:125], v[180:183], v[196:199], v[122:125]
	v_mfma_f32_16x16x32_bf16 v[114:117], v[184:187], v[192:195], v[114:117]
	v_mfma_f32_16x16x32_bf16 v[114:117], v[188:191], v[196:199], v[114:117]
	v_mfma_f32_16x16x32_bf16 v[98:101], v[184:187], v[200:203], v[98:101]
	v_mfma_f32_16x16x32_bf16 v[98:101], v[188:191], v[204:207], v[98:101]
	v_mfma_f32_16x16x32_bf16 v[106:109], v[176:179], v[200:203], v[106:109]
	v_mfma_f32_16x16x32_bf16 v[106:109], v[180:183], v[204:207], v[106:109]
	v_mfma_f32_16x16x32_bf16 v[90:93], v[176:179], v[208:211], v[90:93]
	v_mfma_f32_16x16x32_bf16 v[90:93], v[180:183], v[212:215], v[90:93]
	v_mfma_f32_16x16x32_bf16 v[82:85], v[184:187], v[208:211], v[82:85]
	v_mfma_f32_16x16x32_bf16 v[82:85], v[188:191], v[212:215], v[82:85]
	v_mfma_f32_16x16x32_bf16 v[66:69], v[184:187], v[216:219], v[66:69]
	v_mfma_f32_16x16x32_bf16 v[66:69], v[188:191], v[220:223], v[66:69]
	v_mfma_f32_16x16x32_bf16 v[74:77], v[176:179], v[216:219], v[74:77]
	v_mfma_f32_16x16x32_bf16 v[74:77], v[180:183], v[220:223], v[74:77]
	s_barrier
	s_add_i32 s56, s83, s66
	v_lshl_add_u64 v[160:161], s[8:9], 0, v[140:141]
	s_mov_b32 m0, s56
	ds_read_b128 v[192:195], v169 offset:16384
	ds_read_b128 v[196:199], v169 offset:17408
	ds_read_b128 v[200:203], v169 offset:18432
	ds_read_b128 v[204:207], v169 offset:19456
	ds_read_b128 v[208:211], v169 offset:20480
	ds_read_b128 v[212:215], v169 offset:21504
	ds_read_b128 v[216:219], v169 offset:22528
	ds_read_b128 v[220:223], v169 offset:23552
	global_load_lds_dwordx4 v[160:161], off
	s_add_i32 m0, s56, 0x2000
	s_add_u32 s56, s8, 0x100000
	v_lshl_add_u64 v[224:225], s[8:9], 0, v[144:145]
	s_addc_u32 s57, s9, 0
	s_add_i32 s58, s89, s66
	global_load_lds_dwordx4 v[224:225], off
	v_lshl_add_u64 v[226:227], s[56:57], 0, v[140:141]
	s_mov_b32 m0, s58
	v_lshl_add_u64 v[228:229], s[36:37], 0, v[142:143]
	global_load_lds_dwordx4 v[226:227], off
	v_lshl_add_u64 v[226:227], s[56:57], 0, v[144:145]
	s_add_i32 m0, s58, 0x2000
	s_nop 0
	global_load_lds_dwordx4 v[226:227], off
	v_lshl_add_u64 v[226:227], s[36:37], 0, v[138:139]
	s_mov_b32 m0, s55
	s_nop 0
	global_load_lds_dwordx4 v[226:227], off
	s_mov_b32 m0, s67
	s_nop 0
	global_load_lds_dwordx4 v[228:229], off
	s_cmp_eq_u32 s97, 0
	s_cbranch_scc1 .Lengw2_a
	s_cmp_eq_u32 s97, 2
	s_cbranch_scc1 .Lengw2_b
	s_cmp_eq_u32 s97, 4
	s_cbranch_scc1 .Lengw2_c
	s_waitcnt vmcnt(16)
	s_branch .Lengw2_e

; #define PG8_STAGE(bufoff, gbase, voff) do { _Pragma("unroll") for (int _i = 0; _i < 2; ++_i) \
;         __builtin_amdgcn_global_load_lds((const unsigned*)((const char*)(gbase) + (voff)[_i]), (PG8_LAS unsigned*)(lds + (bufoff) + ldsw + _i * 8192), 16, 0, 0); } while (0)
; #define PG8_LDA(dst, b, h) do { _Pragma("unroll") for (int m = 0; m < 4; ++m) _Pragma("unroll") for (int k = 0; k < 2; ++k) dst[m][k] = *(const PG8_LAS bf16x8*)(lds + PG8_SA(b, h) + aoff + m * 2048 + k * 1024); } while (0)
; #define PG8_LDB(dst, b, h) do { _Pragma("unroll") for (int n = 0; n < 2; ++n) _Pragma("unroll") for (int k = 0; k < 2; ++k) dst[n][k] = *(const PG8_LAS bf16x8*)(lds + PG8_SB(b, h) + boff + n * 2048 + k * 1024); } while (0)
; #define PG8_MMA(ai, bj, At, Bt) do { __builtin_amdgcn_s_setprio(3); _Pragma("unroll") for (int m = 0; m < 4; ++m) _Pragma("unroll") for (int n = 0; n < 2; ++n) _Pragma("unroll") for (int k = 0; k < 2; ++k) \
;         acc[ai][bj][m][n] = __builtin_amdgcn_mfma_f32_16x16x32_bf16(Bt[n][k], At[m][k], acc[ai][bj][m][n], 0, 0, 0); __builtin_amdgcn_s_setprio(0); } while (0)
; #define PG8_WAIT_V(n) asm volatile("s_waitcnt vmcnt(" #n ")" ::: "memory")
; #define PG8_WAIT_L(n) asm volatile("s_waitcnt lgkmcnt(" #n ")" ::: "memory")
; #define PG8_BAR __builtin_amdgcn_s_barrier()
; #define PG8_SCHED __builtin_amdgcn_sched_barrier(0)
; template <class Epi, class Sched, bool ALIGN_EPI = false, bool SP2 = false>
; __device__ __forceinline__ void gemm_phase(PG8_LAS unsigned char* lds, const Gemm g, const Sched& S, const Epi& E) {
;     ...
;             PG8_WAIT_V(8); PG8_WAIT_L(0); PG8_BAR; PG8_MMA(1, 0, At, B0); PG8_MMA(1, 1, At, B1); PG8_BAR; PG8_SCHED;
;             PG8_LDB(B0, 1, 0); PG8_LDB(B1, 1, 1); PG8_SCHED; PG8_LDA(At, 1, 0); PG8_STAGE(PG8_SA(0, 1), a2 + hstepA, voffA);
;             PG8_WAIT_V(8); PG8_WAIT_L(0); PG8_BAR; PG8_MMA(0, 0, At, B0); PG8_MMA(0, 1, At, B1); PG8_BAR; PG8_SCHED;
.Lengw2_e:
	s_waitcnt lgkmcnt(0)
	s_barrier
	v_mfma_f32_16x16x32_bf16 v[62:65], v[130:133], v[192:195], v[62:65]
	v_mfma_f32_16x16x32_bf16 v[62:65], v[134:137], v[196:199], v[62:65]
	v_mfma_f32_16x16x32_bf16 v[54:57], v[156:159], v[192:195], v[54:57]
	v_mfma_f32_16x16x32_bf16 v[54:57], v[172:175], v[196:199], v[54:57]
	v_mfma_f32_16x16x32_bf16 v[38:41], v[156:159], v[200:203], v[38:41]
	v_mfma_f32_16x16x32_bf16 v[38:41], v[172:175], v[204:207], v[38:41]
	v_mfma_f32_16x16x32_bf16 v[46:49], v[130:133], v[200:203], v[46:49]
	v_mfma_f32_16x16x32_bf16 v[46:49], v[134:137], v[204:207], v[46:49]
	v_mfma_f32_16x16x32_bf16 v[30:33], v[130:133], v[208:211], v[30:33]
	v_mfma_f32_16x16x32_bf16 v[30:33], v[134:137], v[212:215], v[30:33]
	v_mfma_f32_16x16x32_bf16 v[22:25], v[156:159], v[208:211], v[22:25]
	v_mfma_f32_16x16x32_bf16 v[22:25], v[172:175], v[212:215], v[22:25]
	v_mfma_f32_16x16x32_bf16 v[6:9], v[156:159], v[216:219], v[6:9]
	v_mfma_f32_16x16x32_bf16 v[6:9], v[172:175], v[220:223], v[6:9]
	v_mfma_f32_16x16x32_bf16 v[14:17], v[130:133], v[216:219], v[14:17]
	v_mfma_f32_16x16x32_bf16 v[14:17], v[134:137], v[220:223], v[14:17]
	v_mfma_f32_16x16x32_bf16 v[58:61], v[176:179], v[192:195], v[58:61]
	v_mfma_f32_16x16x32_bf16 v[58:61], v[180:183], v[196:199], v[58:61]
	v_mfma_f32_16x16x32_bf16 v[50:53], v[184:187], v[192:195], v[50:53]
	v_mfma_f32_16x16x32_bf16 v[50:53], v[188:191], v[196:199], v[50:53]
	v_mfma_f32_16x16x32_bf16 v[34:37], v[184:187], v[200:203], v[34:37]
	v_mfma_f32_16x16x32_bf16 v[34:37], v[188:191], v[204:207], v[34:37]
	v_mfma_f32_16x16x32_bf16 v[42:45], v[176:179], v[200:203], v[42:45]
	v_mfma_f32_16x16x32_bf16 v[42:45], v[180:183], v[204:207], v[42:45]
	v_mfma_f32_16x16x32_bf16 v[26:29], v[176:179], v[208:211], v[26:29]
	v_mfma_f32_16x16x32_bf16 v[26:29], v[180:183], v[212:215], v[26:29]
	v_mfma_f32_16x16x32_bf16 v[18:21], v[184:187], v[208:211], v[18:21]
	v_mfma_f32_16x16x32_bf16 v[18:21], v[188:191], v[212:215], v[18:21]
	v_mfma_f32_16x16x32_bf16 v[2:5], v[184:187], v[216:219], v[2:5]
	v_mfma_f32_16x16x32_bf16 v[2:5], v[188:191], v[220:223], v[2:5]
	v_mfma_f32_16x16x32_bf16 v[10:13], v[176:179], v[216:219], v[10:13]
	v_mfma_f32_16x16x32_bf16 v[10:13], v[180:183], v[220:223], v[10:13]
	s_barrier
	s_add_i32 s56, 0, 0x18000
	v_add_u32_e32 v146, s56, v164
	s_add_i32 s57, 0, 0x1c000
	ds_read_b128 v[130:133], v146
	ds_read_b128 v[134:137], v146 offset:1024
	ds_read_b128 v[156:159], v146 offset:2048
	ds_read_b128 v[172:175], v146 offset:3072
	v_add_u32_e32 v146, s57, v164
	ds_read_b128 v[176:179], v146
	ds_read_b128 v[180:183], v146 offset:1024
	ds_read_b128 v[184:187], v146 offset:2048
	ds_read_b128 v[188:191], v146 offset:3072
	s_add_u32 s36, s36, 0x100000
	s_addc_u32 s37, s37, 0
	s_mov_b32 m0, s72
	v_lshl_add_u64 v[230:231], s[36:37], 0, v[138:139]
	ds_read_b128 v[192:195], v169 offset:32768
	ds_read_b128 v[196:199], v169 offset:33792
	ds_read_b128 v[200:203], v169 offset:34816
	ds_read_b128 v[204:207], v169 offset:35840
	ds_read_b128 v[208:211], v169 offset:36864
	ds_read_b128 v[212:215], v169 offset:37888
	ds_read_b128 v[216:219], v169 offset:38912
	ds_read_b128 v[220:223], v169 offset:39936
	global_load_lds_dwordx4 v[230:231], off
	v_lshl_add_u64 v[230:231], s[36:37], 0, v[142:143]
	s_mov_b32 m0, s73
	s_nop 0
	global_load_lds_dwordx4 v[230:231], off
	s_cmp_eq_u32 s97, 4
	s_cbranch_scc1 .Lengw3_c
	s_cmp_eq_u32 s97, 8
	s_cbranch_scc1 .Lengw3_d
	s_waitcnt vmcnt(8)
	s_branch .Lengw3_e

; #define PG8_STAGE(bufoff, gbase, voff) do { _Pragma("unroll") for (int _i = 0; _i < 2; ++_i) \
;         __builtin_amdgcn_global_load_lds((const unsigned*)((const char*)(gbase) + (voff)[_i]), (PG8_LAS unsigned*)(lds + (bufoff) + ldsw + _i * 8192), 16, 0, 0); } while (0)
; #define PG8_LDA(dst, b, h) do { _Pragma("unroll") for (int m = 0; m < 4; ++m) _Pragma("unroll") for (int k = 0; k < 2; ++k) dst[m][k] = *(const PG8_LAS bf16x8*)(lds + PG8_SA(b, h) + aoff + m * 2048 + k * 1024); } while (0)
; #define PG8_MMA(ai, bj, At, Bt) do { __builtin_amdgcn_s_setprio(3); _Pragma("unroll") for (int m = 0; m < 4; ++m) _Pragma("unroll") for (int n = 0; n < 2; ++n) _Pragma("unroll") for (int k = 0; k < 2; ++k) \
;         acc[ai][bj][m][n] = __builtin_amdgcn_mfma_f32_16x16x32_bf16(Bt[n][k], At[m][k], acc[ai][bj][m][n], 0, 0, 0); __builtin_amdgcn_s_setprio(0); } while (0)
; #define PG8_WAIT_V(n) asm volatile("s_waitcnt vmcnt(" #n ")" ::: "memory")
; #define PG8_WAIT_L(n) asm volatile("s_waitcnt lgkmcnt(" #n ")" ::: "memory")
; #define PG8_BAR __builtin_amdgcn_s_barrier()
; #define PG8_SCHED __builtin_amdgcn_sched_barrier(0)
; template <class Epi, class Sched, bool ALIGN_EPI = false, bool SP2 = false>
; __device__ __forceinline__ void gemm_phase(PG8_LAS unsigned char* lds, const Gemm g, const Sched& S, const Epi& E) {
;     ...
;             PG8_WAIT_V(8); PG8_WAIT_L(0); PG8_BAR; PG8_MMA(0, 0, At, B0); PG8_MMA(0, 1, At, B1); PG8_BAR; PG8_SCHED;
;             PG8_LDA(At, 1, 1); PG8_STAGE(PG8_SB(1, 0), b3, voffB); PG8_STAGE(PG8_SB(1, 1), b3 + hstepB, voffB); PG8_STAGE(PG8_SA(1, 0), a3, voffA);
;             PG8_WAIT_V(8); PG8_WAIT_L(0); PG8_BAR; PG8_MMA(1, 0, At, B0); PG8_MMA(1, 1, At, B1); PG8_BAR; PG8_SCHED;
;     ...
;         if constexpr (ALIGN_EPI) { if (wr == 0) PG8_BAR; }
;         if constexpr (!Epi::AFTER_DRAIN) { E(acc, cur, wr, wc, fr, fq); S.done(cur); }
.Lengw3_e:
	s_waitcnt lgkmcnt(0)
	s_barrier
	v_mfma_f32_16x16x32_bf16 v[126:129], v[130:133], v[192:195], v[126:129]
	v_mfma_f32_16x16x32_bf16 v[126:129], v[134:137], v[196:199], v[126:129]
	v_mfma_f32_16x16x32_bf16 v[118:121], v[156:159], v[192:195], v[118:121]
	v_mfma_f32_16x16x32_bf16 v[118:121], v[172:175], v[196:199], v[118:121]
	v_mfma_f32_16x16x32_bf16 v[102:105], v[156:159], v[200:203], v[102:105]
	v_mfma_f32_16x16x32_bf16 v[102:105], v[172:175], v[204:207], v[102:105]
	v_mfma_f32_16x16x32_bf16 v[110:113], v[130:133], v[200:203], v[110:113]
	v_mfma_f32_16x16x32_bf16 v[110:113], v[134:137], v[204:207], v[110:113]
	v_mfma_f32_16x16x32_bf16 v[94:97], v[130:133], v[208:211], v[94:97]
	v_mfma_f32_16x16x32_bf16 v[94:97], v[134:137], v[212:215], v[94:97]
	v_mfma_f32_16x16x32_bf16 v[86:89], v[156:159], v[208:211], v[86:89]
	v_mfma_f32_16x16x32_bf16 v[86:89], v[172:175], v[212:215], v[86:89]
	v_mfma_f32_16x16x32_bf16 v[70:73], v[156:159], v[216:219], v[70:73]
	v_mfma_f32_16x16x32_bf16 v[70:73], v[172:175], v[220:223], v[70:73]
	v_mfma_f32_16x16x32_bf16 v[78:81], v[130:133], v[216:219], v[78:81]
	v_mfma_f32_16x16x32_bf16 v[78:81], v[134:137], v[220:223], v[78:81]
	v_mfma_f32_16x16x32_bf16 v[122:125], v[176:179], v[192:195], v[122:125]
	v_mfma_f32_16x16x32_bf16 v[122:125], v[180:183], v[196:199], v[122:125]
	v_mfma_f32_16x16x32_bf16 v[114:117], v[184:187], v[192:195], v[114:117]
	v_mfma_f32_16x16x32_bf16 v[114:117], v[188:191], v[196:199], v[114:117]
	v_mfma_f32_16x16x32_bf16 v[98:101], v[184:187], v[200:203], v[98:101]
	v_mfma_f32_16x16x32_bf16 v[98:101], v[188:191], v[204:207], v[98:101]
	v_mfma_f32_16x16x32_bf16 v[106:109], v[176:179], v[200:203], v[106:109]
	v_mfma_f32_16x16x32_bf16 v[106:109], v[180:183], v[204:207], v[106:109]
	v_mfma_f32_16x16x32_bf16 v[90:93], v[176:179], v[208:211], v[90:93]
	v_mfma_f32_16x16x32_bf16 v[90:93], v[180:183], v[212:215], v[90:93]
	v_mfma_f32_16x16x32_bf16 v[82:85], v[184:187], v[208:211], v[82:85]
	v_mfma_f32_16x16x32_bf16 v[82:85], v[188:191], v[212:215], v[82:85]
	v_mfma_f32_16x16x32_bf16 v[66:69], v[184:187], v[216:219], v[66:69]
	v_mfma_f32_16x16x32_bf16 v[66:69], v[188:191], v[220:223], v[66:69]
	v_mfma_f32_16x16x32_bf16 v[74:77], v[176:179], v[216:219], v[74:77]
	v_mfma_f32_16x16x32_bf16 v[74:77], v[180:183], v[220:223], v[74:77]
	s_barrier
	s_add_i32 s36, s56, s66
	v_lshl_add_u64 v[160:161], v[160:161], 0, s[18:19]
	s_mov_b32 m0, s36
	ds_read_b128 v[192:195], v169 offset:49152
	ds_read_b128 v[196:199], v169 offset:50176
	ds_read_b128 v[200:203], v169 offset:51200
	ds_read_b128 v[204:207], v169 offset:52224
	ds_read_b128 v[208:211], v169 offset:53248
	ds_read_b128 v[212:215], v169 offset:54272
	ds_read_b128 v[216:219], v169 offset:55296
	ds_read_b128 v[220:223], v169 offset:56320
	global_load_lds_dwordx4 v[160:161], off
	s_add_i32 m0, s36, 0x2000
	s_add_u32 s8, s8, 0x100080
	v_lshl_add_u64 v[160:161], v[224:225], 0, s[18:19]
	s_addc_u32 s9, s9, 0
	s_add_i32 s36, s57, s66
	global_load_lds_dwordx4 v[160:161], off
	v_lshl_add_u64 v[160:161], s[8:9], 0, v[140:141]
	s_mov_b32 m0, s36
	s_nop 0
	global_load_lds_dwordx4 v[160:161], off
	v_lshl_add_u64 v[160:161], s[8:9], 0, v[144:145]
	s_add_i32 m0, s36, 0x2000
	s_nop 0
	global_load_lds_dwordx4 v[160:161], off
	v_lshl_add_u64 v[160:161], v[226:227], 0, s[18:19]
	s_mov_b32 m0, s75
	s_nop 0
	global_load_lds_dwordx4 v[160:161], off
	v_lshl_add_u64 v[160:161], v[228:229], 0, s[18:19]
	s_mov_b32 m0, s76
	s_nop 0
	global_load_lds_dwordx4 v[160:161], off
	s_waitcnt vmcnt(8)
	s_waitcnt lgkmcnt(0)
	s_barrier
	v_mfma_f32_16x16x32_bf16 v[62:65], v[130:133], v[192:195], v[62:65]
	v_mfma_f32_16x16x32_bf16 v[62:65], v[134:137], v[196:199], v[62:65]
	v_mfma_f32_16x16x32_bf16 v[54:57], v[156:159], v[192:195], v[54:57]
	v_mfma_f32_16x16x32_bf16 v[54:57], v[172:175], v[196:199], v[54:57]
	v_mfma_f32_16x16x32_bf16 v[38:41], v[156:159], v[200:203], v[38:41]
	v_mfma_f32_16x16x32_bf16 v[38:41], v[172:175], v[204:207], v[38:41]
	v_mfma_f32_16x16x32_bf16 v[46:49], v[130:133], v[200:203], v[46:49]
	v_mfma_f32_16x16x32_bf16 v[46:49], v[134:137], v[204:207], v[46:49]
	v_mfma_f32_16x16x32_bf16 v[30:33], v[130:133], v[208:211], v[30:33]
	v_mfma_f32_16x16x32_bf16 v[30:33], v[134:137], v[212:215], v[30:33]
	v_mfma_f32_16x16x32_bf16 v[22:25], v[156:159], v[208:211], v[22:25]
	v_mfma_f32_16x16x32_bf16 v[22:25], v[172:175], v[212:215], v[22:25]
	v_mfma_f32_16x16x32_bf16 v[6:9], v[156:159], v[216:219], v[6:9]
	v_mfma_f32_16x16x32_bf16 v[6:9], v[172:175], v[220:223], v[6:9]
	v_mfma_f32_16x16x32_bf16 v[14:17], v[130:133], v[216:219], v[14:17]
	v_mfma_f32_16x16x32_bf16 v[14:17], v[134:137], v[220:223], v[14:17]
	v_mfma_f32_16x16x32_bf16 v[58:61], v[176:179], v[192:195], v[58:61]
	v_mfma_f32_16x16x32_bf16 v[58:61], v[180:183], v[196:199], v[58:61]
	v_mfma_f32_16x16x32_bf16 v[50:53], v[184:187], v[192:195], v[50:53]
	v_mfma_f32_16x16x32_bf16 v[50:53], v[188:191], v[196:199], v[50:53]
	v_mfma_f32_16x16x32_bf16 v[34:37], v[184:187], v[200:203], v[34:37]
	v_mfma_f32_16x16x32_bf16 v[34:37], v[188:191], v[204:207], v[34:37]
	v_mfma_f32_16x16x32_bf16 v[42:45], v[176:179], v[200:203], v[42:45]
	v_mfma_f32_16x16x32_bf16 v[42:45], v[180:183], v[204:207], v[42:45]
	v_mfma_f32_16x16x32_bf16 v[26:29], v[176:179], v[208:211], v[26:29]
	v_mfma_f32_16x16x32_bf16 v[26:29], v[180:183], v[212:215], v[26:29]
	v_mfma_f32_16x16x32_bf16 v[18:21], v[184:187], v[208:211], v[18:21]
	v_mfma_f32_16x16x32_bf16 v[18:21], v[188:191], v[212:215], v[18:21]
	v_mfma_f32_16x16x32_bf16 v[2:5], v[184:187], v[216:219], v[2:5]
	v_mfma_f32_16x16x32_bf16 v[2:5], v[188:191], v[220:223], v[2:5]
	v_mfma_f32_16x16x32_bf16 v[10:13], v[176:179], v[216:219], v[10:13]
	v_mfma_f32_16x16x32_bf16 v[10:13], v[180:183], v[220:223], v[10:13]
	s_barrier
	s_add_i32 s45, s45, 2
	s_add_u32 s6, s6, 0x100
	s_addc_u32 s7, s7, 0
	s_add_u32 s33, s33, 0x100
	s_addc_u32 s44, s44, 0
	s_cmp_gt_u32 s45, 61
	s_cbranch_scc0 .LBB0_143
	s_and_b64 vcc, exec, s[20:21]
	s_cbranch_vccz .LBB0_148
	s_barrier
	v_lshl_add_u32 v156, s0, 8, v163
	s_cmp_lt_i32 s54, 40
	s_mov_b64 s[0:1], -1
	s_cbranch_scc1 .LBB0_149

; #define PG8_STAGE(bufoff, gbase, voff) do { _Pragma("unroll") for (int _i = 0; _i < 2; ++_i) \
;         __builtin_amdgcn_global_load_lds((const unsigned*)((const char*)(gbase) + (voff)[_i]), (PG8_LAS unsigned*)(lds + (bufoff) + ldsw + _i * 8192), 16, 0, 0); } while (0)
; #define PG8_LDA(dst, b, h) do { _Pragma("unroll") for (int m = 0; m < 4; ++m) _Pragma("unroll") for (int k = 0; k < 2; ++k) dst[m][k] = *(const PG8_LAS bf16x8*)(lds + PG8_SA(b, h) + aoff + m * 2048 + k * 1024); } while (0)
; #define PG8_LDB(dst, b, h) do { _Pragma("unroll") for (int n = 0; n < 2; ++n) _Pragma("unroll") for (int k = 0; k < 2; ++k) dst[n][k] = *(const PG8_LAS bf16x8*)(lds + PG8_SB(b, h) + boff + n * 2048 + k * 1024); } while (0)
; #define PG8_MMA(ai, bj, At, Bt) do { __builtin_amdgcn_s_setprio(3); _Pragma("unroll") for (int m = 0; m < 4; ++m) _Pragma("unroll") for (int n = 0; n < 2; ++n) _Pragma("unroll") for (int k = 0; k < 2; ++k) \
;         acc[ai][bj][m][n] = __builtin_amdgcn_mfma_f32_16x16x32_bf16(Bt[n][k], At[m][k], acc[ai][bj][m][n], 0, 0, 0); __builtin_amdgcn_s_setprio(0); } while (0)
; #define PG8_WAIT_V(n) asm volatile("s_waitcnt vmcnt(" #n ")" ::: "memory")
; #define PG8_WAIT_L(n) asm volatile("s_waitcnt lgkmcnt(" #n ")" ::: "memory")
; #define PG8_BAR __builtin_amdgcn_s_barrier()
; template <class Epi, class Sched, bool ALIGN_EPI = false, bool SP2 = false>
; __device__ __forceinline__ void gemm_phase(PG8_LAS unsigned char* lds, const Gemm g, const Sched& S, const Epi& E) {
;     ...
;             const bool last = (t == nt - 2);
;             const char* a1 = cA + (size_t)(t + 1) * kstep;
;             const char* a2 = last ? nA : cA + (size_t)(t + 2) * kstep; const char* b2 = last ? nB : cB + (size_t)(t + 2) * kstep;
;             const char* a3 = a2 + kstep; const char* b3 = b2 + kstep;
;             if (last && has_next) S.a_ready(nxt);
;             if constexpr (Epi::MIDK) { if (t == E.midk_step(nt)) E.midk(acc, cur, wr, wc, fr, fq); }
;             if constexpr (SP2) {
;             PG8_LDB(B0, 0, 0); PG8_LDB(B1, 0, 1); PG8_SCHED; PG8_LDA(At, 0, 0); PG8_STAGE(PG8_SA(1, 1), a1 + hstepA, voffA);
;             PG8_WAIT_V(8); PG8_WAIT_L(0); PG8_BAR; PG8_MMA(0, 0, At, B0); PG8_MMA(0, 1, At, B1); PG8_BAR; PG8_SCHED;
;             PG8_LDA(At, 0, 1); PG8_STAGE(PG8_SB(0, 0), b2, voffB); PG8_STAGE(PG8_SB(0, 1), b2 + hstepB, voffB); PG8_STAGE(PG8_SA(0, 0), a2, voffA);
.LBB0_478:
	ds_read_b128 v[130:133], v170
	ds_read_b128 v[134:137], v170 offset:1024
	ds_read_b128 v[138:141], v170 offset:2048
	ds_read_b128 v[142:145], v170 offset:3072
	ds_read_b128 v[164:167], v171
	ds_read_b128 v[174:177], v171 offset:1024
	ds_read_b128 v[178:181], v171 offset:2048
	ds_read_b128 v[182:185], v171 offset:3072
	s_add_u32 s36, s6, 0xfff80080
	s_addc_u32 s37, s7, -1
	s_cmp_eq_u32 s79, 4
	s_cselect_b32 s59, s27, s37
	s_cselect_b32 s58, s26, s36
	s_cselect_b32 s37, s23, s78
	s_cselect_b32 s36, s25, s77
	v_lshl_add_u64 v[218:219], s[6:7], 0, v[154:155]
	s_add_i32 m0, s31, 0xc000
	ds_read_b128 v[186:189], v172
	ds_read_b128 v[190:193], v172 offset:1024
	ds_read_b128 v[194:197], v172 offset:2048
	ds_read_b128 v[198:201], v172 offset:3072
	ds_read_b128 v[202:205], v172 offset:4096
	ds_read_b128 v[206:209], v172 offset:5120
	ds_read_b128 v[210:213], v172 offset:6144
	ds_read_b128 v[214:217], v172 offset:7168
	global_load_lds_dwordx4 v[218:219], off
	v_lshl_add_u64 v[218:219], s[6:7], 0, v[156:157]
	s_add_i32 m0, s31, 0xe000
	s_nop 0
	global_load_lds_dwordx4 v[218:219], off
	s_waitcnt vmcnt(8)
	s_waitcnt lgkmcnt(0)
	s_barrier
	v_mfma_f32_16x16x32_bf16 v[126:129], v[130:133], v[186:189], v[126:129]
	v_mfma_f32_16x16x32_bf16 v[126:129], v[134:137], v[190:193], v[126:129]
	v_mfma_f32_16x16x32_bf16 v[122:125], v[138:141], v[186:189], v[122:125]
	v_mfma_f32_16x16x32_bf16 v[122:125], v[142:145], v[190:193], v[122:125]
	v_mfma_f32_16x16x32_bf16 v[114:117], v[138:141], v[194:197], v[114:117]
	v_mfma_f32_16x16x32_bf16 v[114:117], v[142:145], v[198:201], v[114:117]
	v_mfma_f32_16x16x32_bf16 v[118:121], v[130:133], v[194:197], v[118:121]
	v_mfma_f32_16x16x32_bf16 v[118:121], v[134:137], v[198:201], v[118:121]
	v_mfma_f32_16x16x32_bf16 v[110:113], v[130:133], v[202:205], v[110:113]
	v_mfma_f32_16x16x32_bf16 v[110:113], v[134:137], v[206:209], v[110:113]
	v_mfma_f32_16x16x32_bf16 v[102:105], v[138:141], v[202:205], v[102:105]
	v_mfma_f32_16x16x32_bf16 v[102:105], v[142:145], v[206:209], v[102:105]
	v_mfma_f32_16x16x32_bf16 v[74:77], v[138:141], v[210:213], v[74:77]
	v_mfma_f32_16x16x32_bf16 v[74:77], v[142:145], v[214:217], v[74:77]
	v_mfma_f32_16x16x32_bf16 v[78:81], v[130:133], v[210:213], v[78:81]
	v_mfma_f32_16x16x32_bf16 v[78:81], v[134:137], v[214:217], v[78:81]
	v_mfma_f32_16x16x32_bf16 v[106:109], v[164:167], v[186:189], v[106:109]
	v_mfma_f32_16x16x32_bf16 v[106:109], v[174:177], v[190:193], v[106:109]
	v_mfma_f32_16x16x32_bf16 v[98:101], v[178:181], v[186:189], v[98:101]
	v_mfma_f32_16x16x32_bf16 v[98:101], v[182:185], v[190:193], v[98:101]
	v_mfma_f32_16x16x32_bf16 v[90:93], v[178:181], v[194:197], v[90:93]
	v_mfma_f32_16x16x32_bf16 v[90:93], v[182:185], v[198:201], v[90:93]
	v_mfma_f32_16x16x32_bf16 v[94:97], v[164:167], v[194:197], v[94:97]
	v_mfma_f32_16x16x32_bf16 v[94:97], v[174:177], v[198:201], v[94:97]
	v_mfma_f32_16x16x32_bf16 v[86:89], v[164:167], v[202:205], v[86:89]
	v_mfma_f32_16x16x32_bf16 v[86:89], v[174:177], v[206:209], v[86:89]
	v_mfma_f32_16x16x32_bf16 v[82:85], v[178:181], v[202:205], v[82:85]
	v_mfma_f32_16x16x32_bf16 v[82:85], v[182:185], v[206:209], v[82:85]
	v_mfma_f32_16x16x32_bf16 v[66:69], v[178:181], v[210:213], v[66:69]
	v_mfma_f32_16x16x32_bf16 v[66:69], v[182:185], v[214:217], v[66:69]
	v_mfma_f32_16x16x32_bf16 v[70:73], v[164:167], v[210:213], v[70:73]
	v_mfma_f32_16x16x32_bf16 v[70:73], v[174:177], v[214:217], v[70:73]
	s_barrier
	s_add_i32 s83, s72, s44
	v_lshl_add_u64 v[218:219], s[36:37], 0, v[148:149]
	s_mov_b32 m0, s83
	ds_read_b128 v[186:189], v172 offset:16384
	ds_read_b128 v[190:193], v172 offset:17408
	ds_read_b128 v[194:197], v172 offset:18432
	ds_read_b128 v[198:201], v172 offset:19456
	ds_read_b128 v[202:205], v172 offset:20480
	ds_read_b128 v[206:209], v172 offset:21504
	ds_read_b128 v[210:213], v172 offset:22528
	ds_read_b128 v[214:217], v172 offset:23552
	global_load_lds_dwordx4 v[218:219], off
	s_add_i32 m0, s83, 0x2000
	s_add_u32 s84, s36, 0x20000
	v_lshl_add_u64 v[220:221], s[36:37], 0, v[152:153]
	s_addc_u32 s85, s37, 0
	s_add_i32 s83, s73, s44
	global_load_lds_dwordx4 v[220:221], off
	v_lshl_add_u64 v[222:223], s[84:85], 0, v[148:149]
	s_mov_b32 m0, s83
	v_lshl_add_u64 v[224:225], s[58:59], 0, v[150:151]
	global_load_lds_dwordx4 v[222:223], off
	v_lshl_add_u64 v[222:223], s[84:85], 0, v[152:153]
	s_add_i32 m0, s83, 0x2000
	s_nop 0
	global_load_lds_dwordx4 v[222:223], off
	v_lshl_add_u64 v[222:223], s[58:59], 0, v[146:147]
	s_mov_b32 m0, s31
	s_nop 0
	global_load_lds_dwordx4 v[222:223], off
	s_mov_b32 m0, s45
	s_nop 0
	global_load_lds_dwordx4 v[224:225], off
	s_waitcnt vmcnt(8)
	s_waitcnt lgkmcnt(0)
	s_barrier
; #define PG8_STAGE(bufoff, gbase, voff) do { _Pragma("unroll") for (int _i = 0; _i < 2; ++_i) \
;         __builtin_amdgcn_global_load_lds((const unsigned*)((const char*)(gbase) + (voff)[_i]), (PG8_LAS unsigned*)(lds + (bufoff) + ldsw + _i * 8192), 16, 0, 0); } while (0)
; #define PG8_LDA(dst, b, h) do { _Pragma("unroll") for (int m = 0; m < 4; ++m) _Pragma("unroll") for (int k = 0; k < 2; ++k) dst[m][k] = *(const PG8_LAS bf16x8*)(lds + PG8_SA(b, h) + aoff + m * 2048 + k * 1024); } while (0)
; #define PG8_LDB(dst, b, h) do { _Pragma("unroll") for (int n = 0; n < 2; ++n) _Pragma("unroll") for (int k = 0; k < 2; ++k) dst[n][k] = *(const PG8_LAS bf16x8*)(lds + PG8_SB(b, h) + boff + n * 2048 + k * 1024); } while (0)
; #define PG8_MMA(ai, bj, At, Bt) do { __builtin_amdgcn_s_setprio(3); _Pragma("unroll") for (int m = 0; m < 4; ++m) _Pragma("unroll") for (int n = 0; n < 2; ++n) _Pragma("unroll") for (int k = 0; k < 2; ++k) \
;         acc[ai][bj][m][n] = __builtin_amdgcn_mfma_f32_16x16x32_bf16(Bt[n][k], At[m][k], acc[ai][bj][m][n], 0, 0, 0); __builtin_amdgcn_s_setprio(0); } while (0)
; #define PG8_WAIT_V(n) asm volatile("s_waitcnt vmcnt(" #n ")" ::: "memory")
; #define PG8_WAIT_L(n) asm volatile("s_waitcnt lgkmcnt(" #n ")" ::: "memory")
; #define PG8_BAR __builtin_amdgcn_s_barrier()
; #define PG8_SCHED __builtin_amdgcn_sched_barrier(0)
; template <class Epi, class Sched, bool ALIGN_EPI = false, bool SP2 = false>
; __device__ __forceinline__ void gemm_phase(PG8_LAS unsigned char* lds, const Gemm g, const Sched& S, const Epi& E) {
;     ...
;             PG8_WAIT_V(8); PG8_WAIT_L(0); PG8_BAR; PG8_MMA(1, 0, At, B0); PG8_MMA(1, 1, At, B1); PG8_BAR; PG8_SCHED;
;             PG8_LDB(B0, 1, 0); PG8_LDB(B1, 1, 1); PG8_SCHED; PG8_LDA(At, 1, 0); PG8_STAGE(PG8_SA(0, 1), a2 + hstepA, voffA);
;             PG8_WAIT_V(8); PG8_WAIT_L(0); PG8_BAR; PG8_MMA(0, 0, At, B0); PG8_MMA(0, 1, At, B1); PG8_BAR; PG8_SCHED;
	v_mfma_f32_16x16x32_bf16 v[62:65], v[130:133], v[186:189], v[62:65]
	v_mfma_f32_16x16x32_bf16 v[62:65], v[134:137], v[190:193], v[62:65]
	v_mfma_f32_16x16x32_bf16 v[58:61], v[138:141], v[186:189], v[58:61]
	v_mfma_f32_16x16x32_bf16 v[58:61], v[142:145], v[190:193], v[58:61]
	v_mfma_f32_16x16x32_bf16 v[46:49], v[138:141], v[194:197], v[46:49]
	v_mfma_f32_16x16x32_bf16 v[46:49], v[142:145], v[198:201], v[46:49]
	v_mfma_f32_16x16x32_bf16 v[54:57], v[130:133], v[194:197], v[54:57]
	v_mfma_f32_16x16x32_bf16 v[54:57], v[134:137], v[198:201], v[54:57]
	v_mfma_f32_16x16x32_bf16 v[38:41], v[130:133], v[202:205], v[38:41]
	v_mfma_f32_16x16x32_bf16 v[38:41], v[134:137], v[206:209], v[38:41]
	v_mfma_f32_16x16x32_bf16 v[30:33], v[138:141], v[202:205], v[30:33]
	v_mfma_f32_16x16x32_bf16 v[30:33], v[142:145], v[206:209], v[30:33]
	v_mfma_f32_16x16x32_bf16 v[14:17], v[138:141], v[210:213], v[14:17]
	v_mfma_f32_16x16x32_bf16 v[14:17], v[142:145], v[214:217], v[14:17]
	v_mfma_f32_16x16x32_bf16 v[22:25], v[130:133], v[210:213], v[22:25]
	v_mfma_f32_16x16x32_bf16 v[22:25], v[134:137], v[214:217], v[22:25]
	v_mfma_f32_16x16x32_bf16 v[50:53], v[164:167], v[186:189], v[50:53]
	v_mfma_f32_16x16x32_bf16 v[50:53], v[174:177], v[190:193], v[50:53]
	v_mfma_f32_16x16x32_bf16 v[42:45], v[178:181], v[186:189], v[42:45]
	v_mfma_f32_16x16x32_bf16 v[42:45], v[182:185], v[190:193], v[42:45]
	v_mfma_f32_16x16x32_bf16 v[26:29], v[178:181], v[194:197], v[26:29]
	v_mfma_f32_16x16x32_bf16 v[26:29], v[182:185], v[198:201], v[26:29]
	v_mfma_f32_16x16x32_bf16 v[34:37], v[164:167], v[194:197], v[34:37]
	v_mfma_f32_16x16x32_bf16 v[34:37], v[174:177], v[198:201], v[34:37]
	v_mfma_f32_16x16x32_bf16 v[18:21], v[164:167], v[202:205], v[18:21]
	v_mfma_f32_16x16x32_bf16 v[18:21], v[174:177], v[206:209], v[18:21]
	v_mfma_f32_16x16x32_bf16 v[10:13], v[178:181], v[202:205], v[10:13]
	v_mfma_f32_16x16x32_bf16 v[10:13], v[182:185], v[206:209], v[10:13]
	v_mfma_f32_16x16x32_bf16 v[2:5], v[178:181], v[210:213], v[2:5]
	v_mfma_f32_16x16x32_bf16 v[2:5], v[182:185], v[214:217], v[2:5]
	v_mfma_f32_16x16x32_bf16 v[6:9], v[164:167], v[210:213], v[6:9]
	v_mfma_f32_16x16x32_bf16 v[6:9], v[174:177], v[214:217], v[6:9]
	s_barrier
	s_add_i32 s83, 0, 0x18000
	s_add_i32 s84, 0, 0x1c000
	v_add_u32_e32 v142, s83, v168
	v_add_u32_e32 v173, s84, v168
	ds_read_b128 v[130:133], v142
	ds_read_b128 v[134:137], v142 offset:1024
	ds_read_b128 v[138:141], v142 offset:2048
	ds_read_b128 v[142:145], v142 offset:3072
	ds_read_b128 v[164:167], v173
	ds_read_b128 v[174:177], v173 offset:1024
	ds_read_b128 v[178:181], v173 offset:2048
	ds_read_b128 v[182:185], v173 offset:3072
	s_add_u32 s58, s58, 0x80000
	s_addc_u32 s59, s59, 0
	s_mov_b32 m0, s54
	v_lshl_add_u64 v[226:227], s[58:59], 0, v[146:147]
	ds_read_b128 v[186:189], v172 offset:32768
	ds_read_b128 v[190:193], v172 offset:33792
	ds_read_b128 v[194:197], v172 offset:34816
	ds_read_b128 v[198:201], v172 offset:35840
	ds_read_b128 v[202:205], v172 offset:36864
	ds_read_b128 v[206:209], v172 offset:37888
	ds_read_b128 v[210:213], v172 offset:38912
	ds_read_b128 v[214:217], v172 offset:39936
	global_load_lds_dwordx4 v[226:227], off
	v_lshl_add_u64 v[226:227], s[58:59], 0, v[150:151]
	s_mov_b32 m0, s55
	s_nop 0
	global_load_lds_dwordx4 v[226:227], off
	s_waitcnt vmcnt(8)
	s_waitcnt lgkmcnt(0)
	s_barrier
	v_mfma_f32_16x16x32_bf16 v[126:129], v[130:133], v[186:189], v[126:129]
	v_mfma_f32_16x16x32_bf16 v[126:129], v[134:137], v[190:193], v[126:129]
	v_mfma_f32_16x16x32_bf16 v[122:125], v[138:141], v[186:189], v[122:125]
	v_mfma_f32_16x16x32_bf16 v[122:125], v[142:145], v[190:193], v[122:125]
	v_mfma_f32_16x16x32_bf16 v[114:117], v[138:141], v[194:197], v[114:117]
	v_mfma_f32_16x16x32_bf16 v[114:117], v[142:145], v[198:201], v[114:117]
	v_mfma_f32_16x16x32_bf16 v[118:121], v[130:133], v[194:197], v[118:121]
	v_mfma_f32_16x16x32_bf16 v[118:121], v[134:137], v[198:201], v[118:121]
	v_mfma_f32_16x16x32_bf16 v[110:113], v[130:133], v[202:205], v[110:113]
	v_mfma_f32_16x16x32_bf16 v[110:113], v[134:137], v[206:209], v[110:113]
	v_mfma_f32_16x16x32_bf16 v[102:105], v[138:141], v[202:205], v[102:105]
	v_mfma_f32_16x16x32_bf16 v[102:105], v[142:145], v[206:209], v[102:105]
	v_mfma_f32_16x16x32_bf16 v[74:77], v[138:141], v[210:213], v[74:77]
	v_mfma_f32_16x16x32_bf16 v[74:77], v[142:145], v[214:217], v[74:77]
	v_mfma_f32_16x16x32_bf16 v[78:81], v[130:133], v[210:213], v[78:81]
	v_mfma_f32_16x16x32_bf16 v[78:81], v[134:137], v[214:217], v[78:81]
	v_mfma_f32_16x16x32_bf16 v[106:109], v[164:167], v[186:189], v[106:109]
	v_mfma_f32_16x16x32_bf16 v[106:109], v[174:177], v[190:193], v[106:109]
	v_mfma_f32_16x16x32_bf16 v[98:101], v[178:181], v[186:189], v[98:101]
	v_mfma_f32_16x16x32_bf16 v[98:101], v[182:185], v[190:193], v[98:101]
	v_mfma_f32_16x16x32_bf16 v[90:93], v[178:181], v[194:197], v[90:93]
	v_mfma_f32_16x16x32_bf16 v[90:93], v[182:185], v[198:201], v[90:93]
	v_mfma_f32_16x16x32_bf16 v[94:97], v[164:167], v[194:197], v[94:97]
	v_mfma_f32_16x16x32_bf16 v[94:97], v[174:177], v[198:201], v[94:97]
	v_mfma_f32_16x16x32_bf16 v[86:89], v[164:167], v[202:205], v[86:89]
	v_mfma_f32_16x16x32_bf16 v[86:89], v[174:177], v[206:209], v[86:89]
	v_mfma_f32_16x16x32_bf16 v[82:85], v[178:181], v[202:205], v[82:85]
	v_mfma_f32_16x16x32_bf16 v[82:85], v[182:185], v[206:209], v[82:85]
	v_mfma_f32_16x16x32_bf16 v[66:69], v[178:181], v[210:213], v[66:69]
	v_mfma_f32_16x16x32_bf16 v[66:69], v[182:185], v[214:217], v[66:69]
	v_mfma_f32_16x16x32_bf16 v[70:73], v[164:167], v[210:213], v[70:73]
	v_mfma_f32_16x16x32_bf16 v[70:73], v[174:177], v[214:217], v[70:73]
	s_barrier
; #define PG8_STAGE(bufoff, gbase, voff) do { _Pragma("unroll") for (int _i = 0; _i < 2; ++_i) \
;         __builtin_amdgcn_global_load_lds((const unsigned*)((const char*)(gbase) + (voff)[_i]), (PG8_LAS unsigned*)(lds + (bufoff) + ldsw + _i * 8192), 16, 0, 0); } while (0)
; #define PG8_LDA(dst, b, h) do { _Pragma("unroll") for (int m = 0; m < 4; ++m) _Pragma("unroll") for (int k = 0; k < 2; ++k) dst[m][k] = *(const PG8_LAS bf16x8*)(lds + PG8_SA(b, h) + aoff + m * 2048 + k * 1024); } while (0)
; #define PG8_MMA(ai, bj, At, Bt) do { __builtin_amdgcn_s_setprio(3); _Pragma("unroll") for (int m = 0; m < 4; ++m) _Pragma("unroll") for (int n = 0; n < 2; ++n) _Pragma("unroll") for (int k = 0; k < 2; ++k) \
;         acc[ai][bj][m][n] = __builtin_amdgcn_mfma_f32_16x16x32_bf16(Bt[n][k], At[m][k], acc[ai][bj][m][n], 0, 0, 0); __builtin_amdgcn_s_setprio(0); } while (0)
; #define PG8_WAIT_V(n) asm volatile("s_waitcnt vmcnt(" #n ")" ::: "memory")
; #define PG8_WAIT_L(n) asm volatile("s_waitcnt lgkmcnt(" #n ")" ::: "memory")
; #define PG8_BAR __builtin_amdgcn_s_barrier()
; #define PG8_SCHED __builtin_amdgcn_sched_barrier(0)
; template <class Epi, class Sched, bool ALIGN_EPI = false, bool SP2 = false>
; __device__ __forceinline__ void gemm_phase(PG8_LAS unsigned char* lds, const Gemm g, const Sched& S, const Epi& E) {
;     ...
;             PG8_LDA(At, 1, 1); PG8_STAGE(PG8_SB(1, 0), b3, voffB); PG8_STAGE(PG8_SB(1, 1), b3 + hstepB, voffB); PG8_STAGE(PG8_SA(1, 0), a3, voffA);
;             PG8_WAIT_V(8); PG8_WAIT_L(0); PG8_BAR; PG8_MMA(1, 0, At, B0); PG8_MMA(1, 1, At, B1); PG8_BAR; PG8_SCHED;
	s_add_i32 s58, s83, s44
	v_lshl_add_u64 v[218:219], v[218:219], 0, s[18:19]
	s_mov_b32 m0, s58
	ds_read_b128 v[186:189], v172 offset:49152
	ds_read_b128 v[190:193], v172 offset:50176
	ds_read_b128 v[194:197], v172 offset:51200
	ds_read_b128 v[198:201], v172 offset:52224
	ds_read_b128 v[202:205], v172 offset:53248
	ds_read_b128 v[206:209], v172 offset:54272
	ds_read_b128 v[210:213], v172 offset:55296
	ds_read_b128 v[214:217], v172 offset:56320
	global_load_lds_dwordx4 v[218:219], off
	s_add_i32 m0, s58, 0x2000
	s_add_u32 s36, s36, 0x20080
	v_lshl_add_u64 v[218:219], v[220:221], 0, s[18:19]
	s_addc_u32 s37, s37, 0
	s_add_i32 s58, s84, s44
	global_load_lds_dwordx4 v[218:219], off
	v_lshl_add_u64 v[218:219], s[36:37], 0, v[148:149]
	s_mov_b32 m0, s58
	s_nop 0
	global_load_lds_dwordx4 v[218:219], off
	v_lshl_add_u64 v[218:219], s[36:37], 0, v[152:153]
	s_add_i32 m0, s58, 0x2000
	s_nop 0
	global_load_lds_dwordx4 v[218:219], off
	v_lshl_add_u64 v[218:219], v[222:223], 0, s[18:19]
	s_mov_b32 m0, s63
	s_nop 0
	global_load_lds_dwordx4 v[218:219], off
	v_lshl_add_u64 v[218:219], v[224:225], 0, s[18:19]
	s_mov_b32 m0, s66
	s_nop 0
	global_load_lds_dwordx4 v[218:219], off
	s_waitcnt vmcnt(8)
	s_waitcnt lgkmcnt(0)
	s_barrier
	v_mfma_f32_16x16x32_bf16 v[62:65], v[130:133], v[186:189], v[62:65]
	v_mfma_f32_16x16x32_bf16 v[62:65], v[134:137], v[190:193], v[62:65]
	v_mfma_f32_16x16x32_bf16 v[58:61], v[138:141], v[186:189], v[58:61]
	v_mfma_f32_16x16x32_bf16 v[58:61], v[142:145], v[190:193], v[58:61]
	v_mfma_f32_16x16x32_bf16 v[46:49], v[138:141], v[194:197], v[46:49]
	v_mfma_f32_16x16x32_bf16 v[46:49], v[142:145], v[198:201], v[46:49]
	v_mfma_f32_16x16x32_bf16 v[54:57], v[130:133], v[194:197], v[54:57]
	v_mfma_f32_16x16x32_bf16 v[54:57], v[134:137], v[198:201], v[54:57]
	v_mfma_f32_16x16x32_bf16 v[38:41], v[130:133], v[202:205], v[38:41]
	v_mfma_f32_16x16x32_bf16 v[38:41], v[134:137], v[206:209], v[38:41]
	v_mfma_f32_16x16x32_bf16 v[30:33], v[138:141], v[202:205], v[30:33]
	v_mfma_f32_16x16x32_bf16 v[30:33], v[142:145], v[206:209], v[30:33]
	v_mfma_f32_16x16x32_bf16 v[14:17], v[138:141], v[210:213], v[14:17]
	v_mfma_f32_16x16x32_bf16 v[14:17], v[142:145], v[214:217], v[14:17]
	v_mfma_f32_16x16x32_bf16 v[22:25], v[130:133], v[210:213], v[22:25]
	v_mfma_f32_16x16x32_bf16 v[22:25], v[134:137], v[214:217], v[22:25]
	v_mfma_f32_16x16x32_bf16 v[50:53], v[164:167], v[186:189], v[50:53]
	v_mfma_f32_16x16x32_bf16 v[50:53], v[174:177], v[190:193], v[50:53]
	v_mfma_f32_16x16x32_bf16 v[42:45], v[178:181], v[186:189], v[42:45]
	v_mfma_f32_16x16x32_bf16 v[42:45], v[182:185], v[190:193], v[42:45]
	v_mfma_f32_16x16x32_bf16 v[26:29], v[178:181], v[194:197], v[26:29]
	v_mfma_f32_16x16x32_bf16 v[26:29], v[182:185], v[198:201], v[26:29]
	v_mfma_f32_16x16x32_bf16 v[34:37], v[164:167], v[194:197], v[34:37]
	v_mfma_f32_16x16x32_bf16 v[34:37], v[174:177], v[198:201], v[34:37]
	v_mfma_f32_16x16x32_bf16 v[18:21], v[164:167], v[202:205], v[18:21]
	v_mfma_f32_16x16x32_bf16 v[18:21], v[174:177], v[206:209], v[18:21]
	v_mfma_f32_16x16x32_bf16 v[10:13], v[178:181], v[202:205], v[10:13]
	v_mfma_f32_16x16x32_bf16 v[10:13], v[182:185], v[206:209], v[10:13]
	v_mfma_f32_16x16x32_bf16 v[2:5], v[178:181], v[210:213], v[2:5]
	v_mfma_f32_16x16x32_bf16 v[2:5], v[182:185], v[214:217], v[2:5]
	v_mfma_f32_16x16x32_bf16 v[6:9], v[164:167], v[210:213], v[6:9]
	v_mfma_f32_16x16x32_bf16 v[6:9], v[174:177], v[214:217], v[6:9]
	s_barrier
	s_add_i32 s79, s79, 2
	s_add_u32 s6, s6, 0x100
	s_addc_u32 s7, s7, 0
	s_add_u32 s77, s77, 0x100
	s_addc_u32 s78, s78, 0
	s_cmp_gt_u32 s79, 5
	s_cbranch_scc0 .LBB0_478
	s_and_b64 vcc, exec, s[20:21]
	s_cbranch_vccz .LBB0_481
	s_barrier

; #define PG8_STAGE(bufoff, gbase, voff) do { _Pragma("unroll") for (int _i = 0; _i < 2; ++_i) \
;         __builtin_amdgcn_global_load_lds((const unsigned*)((const char*)(gbase) + (voff)[_i]), (PG8_LAS unsigned*)(lds + (bufoff) + ldsw + _i * 8192), 16, 0, 0); } while (0)
; #define PG8_LDA(dst, b, h) do { _Pragma("unroll") for (int m = 0; m < 4; ++m) _Pragma("unroll") for (int k = 0; k < 2; ++k) dst[m][k] = *(const PG8_LAS bf16x8*)(lds + PG8_SA(b, h) + aoff + m * 2048 + k * 1024); } while (0)
; #define PG8_LDB(dst, b, h) do { _Pragma("unroll") for (int n = 0; n < 2; ++n) _Pragma("unroll") for (int k = 0; k < 2; ++k) dst[n][k] = *(const PG8_LAS bf16x8*)(lds + PG8_SB(b, h) + boff + n * 2048 + k * 1024); } while (0)
; #define PG8_MMA(ai, bj, At, Bt) do { __builtin_amdgcn_s_setprio(3); _Pragma("unroll") for (int m = 0; m < 4; ++m) _Pragma("unroll") for (int n = 0; n < 2; ++n) _Pragma("unroll") for (int k = 0; k < 2; ++k) \
;         acc[ai][bj][m][n] = __builtin_amdgcn_mfma_f32_16x16x32_bf16(Bt[n][k], At[m][k], acc[ai][bj][m][n], 0, 0, 0); __builtin_amdgcn_s_setprio(0); } while (0)
; #define PG8_WAIT_V(n) asm volatile("s_waitcnt vmcnt(" #n ")" ::: "memory")
; #define PG8_WAIT_L(n) asm volatile("s_waitcnt lgkmcnt(" #n ")" ::: "memory")
; #define PG8_BAR __builtin_amdgcn_s_barrier()
; template <class Epi, class Sched, bool ALIGN_EPI = false, bool SP2 = false>
; __device__ __forceinline__ void gemm_phase(PG8_LAS unsigned char* lds, const Gemm g, const Sched& S, const Epi& E) {
;     ...
;             const bool last = (t == nt - 2);
;             const char* a1 = cA + (size_t)(t + 1) * kstep;
;             const char* a2 = last ? nA : cA + (size_t)(t + 2) * kstep; const char* b2 = last ? nB : cB + (size_t)(t + 2) * kstep;
;             const char* a3 = a2 + kstep; const char* b3 = b2 + kstep;
;             if (last && has_next) S.a_ready(nxt);
;             if constexpr (Epi::MIDK) { if (t == E.midk_step(nt)) E.midk(acc, cur, wr, wc, fr, fq); }
;             if constexpr (SP2) {
;             PG8_LDB(B0, 0, 0); PG8_LDB(B1, 0, 1); PG8_SCHED; PG8_LDA(At, 0, 0); PG8_STAGE(PG8_SA(1, 1), a1 + hstepA, voffA);
;             PG8_WAIT_V(8); PG8_WAIT_L(0); PG8_BAR; PG8_MMA(0, 0, At, B0); PG8_MMA(0, 1, At, B1); PG8_BAR; PG8_SCHED;
;             PG8_LDA(At, 0, 1); PG8_STAGE(PG8_SB(0, 0), b2, voffB); PG8_STAGE(PG8_SB(0, 1), b2 + hstepB, voffB); PG8_STAGE(PG8_SA(0, 0), a2, voffA);
.LBB0_727:
	v_add_u32_e32 v160, s66, v157
	ds_read_b128 v[130:133], v160
	ds_read_b128 v[164:167], v160 offset:1024
	ds_read_b128 v[168:171], v160 offset:2048
	ds_read_b128 v[172:175], v160 offset:3072
	v_add_u32_e32 v160, s67, v157
	s_add_u32 s0, s28, s30
	ds_read_b128 v[176:179], v160
	ds_read_b128 v[180:183], v160 offset:1024
	ds_read_b128 v[184:187], v160 offset:2048
	ds_read_b128 v[188:191], v160 offset:3072
	s_addc_u32 s1, s29, s31
	s_add_u32 s0, s0, 0x100
	s_addc_u32 s1, s1, 0
	s_add_u32 s84, s79, s30
	s_addc_u32 s85, s81, s31
	s_cmpk_eq_i32 s30, 0x1f00
	s_cselect_b32 s37, s23, s1
	s_cselect_b32 s36, s72, s0
	s_cselect_b32 s1, s75, s85
	s_cselect_b32 s0, s76, s84
	v_lshl_add_u64 v[160:161], v[150:151], 0, s[30:31]
	s_add_i32 m0, s44, 0xc000
	ds_read_b128 v[192:195], v159
	ds_read_b128 v[196:199], v159 offset:1024
	ds_read_b128 v[200:203], v159 offset:2048
	ds_read_b128 v[204:207], v159 offset:3072
	ds_read_b128 v[208:211], v159 offset:4096
	ds_read_b128 v[212:215], v159 offset:5120
	ds_read_b128 v[216:219], v159 offset:6144
	ds_read_b128 v[220:223], v159 offset:7168
	global_load_lds_dwordx4 v[160:161], off
	v_lshl_add_u64 v[160:161], v[152:153], 0, s[30:31]
	s_add_i32 m0, s44, 0xe000
	s_nop 0
	global_load_lds_dwordx4 v[160:161], off
	s_waitcnt vmcnt(8)
	s_waitcnt lgkmcnt(0)
	s_barrier
	v_mfma_f32_16x16x32_bf16 v[126:129], v[130:133], v[192:195], v[126:129]
	v_mfma_f32_16x16x32_bf16 v[126:129], v[164:167], v[196:199], v[126:129]
	v_mfma_f32_16x16x32_bf16 v[122:125], v[168:171], v[192:195], v[122:125]
	v_mfma_f32_16x16x32_bf16 v[122:125], v[172:175], v[196:199], v[122:125]
	v_mfma_f32_16x16x32_bf16 v[106:109], v[168:171], v[200:203], v[106:109]
	v_mfma_f32_16x16x32_bf16 v[106:109], v[172:175], v[204:207], v[106:109]
	v_mfma_f32_16x16x32_bf16 v[110:113], v[130:133], v[200:203], v[110:113]
	v_mfma_f32_16x16x32_bf16 v[110:113], v[164:167], v[204:207], v[110:113]
	v_mfma_f32_16x16x32_bf16 v[94:97], v[130:133], v[208:211], v[94:97]
	v_mfma_f32_16x16x32_bf16 v[94:97], v[164:167], v[212:215], v[94:97]
	v_mfma_f32_16x16x32_bf16 v[90:93], v[168:171], v[208:211], v[90:93]
	v_mfma_f32_16x16x32_bf16 v[90:93], v[172:175], v[212:215], v[90:93]
	v_mfma_f32_16x16x32_bf16 v[74:77], v[168:171], v[216:219], v[74:77]
	v_mfma_f32_16x16x32_bf16 v[74:77], v[172:175], v[220:223], v[74:77]
	v_mfma_f32_16x16x32_bf16 v[78:81], v[130:133], v[216:219], v[78:81]
	v_mfma_f32_16x16x32_bf16 v[78:81], v[164:167], v[220:223], v[78:81]
	v_mfma_f32_16x16x32_bf16 v[118:121], v[176:179], v[192:195], v[118:121]
	v_mfma_f32_16x16x32_bf16 v[118:121], v[180:183], v[196:199], v[118:121]
	v_mfma_f32_16x16x32_bf16 v[114:117], v[184:187], v[192:195], v[114:117]
	v_mfma_f32_16x16x32_bf16 v[114:117], v[188:191], v[196:199], v[114:117]
	v_mfma_f32_16x16x32_bf16 v[98:101], v[184:187], v[200:203], v[98:101]
	v_mfma_f32_16x16x32_bf16 v[98:101], v[188:191], v[204:207], v[98:101]
	v_mfma_f32_16x16x32_bf16 v[102:105], v[176:179], v[200:203], v[102:105]
	v_mfma_f32_16x16x32_bf16 v[102:105], v[180:183], v[204:207], v[102:105]
	v_mfma_f32_16x16x32_bf16 v[86:89], v[176:179], v[208:211], v[86:89]
	v_mfma_f32_16x16x32_bf16 v[86:89], v[180:183], v[212:215], v[86:89]
	v_mfma_f32_16x16x32_bf16 v[82:85], v[184:187], v[208:211], v[82:85]
	v_mfma_f32_16x16x32_bf16 v[82:85], v[188:191], v[212:215], v[82:85]
	v_mfma_f32_16x16x32_bf16 v[66:69], v[184:187], v[216:219], v[66:69]
	v_mfma_f32_16x16x32_bf16 v[66:69], v[188:191], v[220:223], v[66:69]
	v_mfma_f32_16x16x32_bf16 v[70:73], v[176:179], v[216:219], v[70:73]
	v_mfma_f32_16x16x32_bf16 v[70:73], v[180:183], v[220:223], v[70:73]
	s_barrier
	s_add_i32 s84, s66, s33
	v_lshl_add_u64 v[160:161], s[0:1], 0, v[136:137]
	s_mov_b32 m0, s84
	ds_read_b128 v[192:195], v159 offset:16384
	ds_read_b128 v[196:199], v159 offset:17408
	ds_read_b128 v[200:203], v159 offset:18432
	ds_read_b128 v[204:207], v159 offset:19456
	ds_read_b128 v[208:211], v159 offset:20480
	ds_read_b128 v[212:215], v159 offset:21504
	ds_read_b128 v[216:219], v159 offset:22528
	ds_read_b128 v[220:223], v159 offset:23552
	global_load_lds_dwordx4 v[160:161], off
	s_add_i32 m0, s84, 0x2000
	s_add_u32 s84, s0, 0x100000
	v_lshl_add_u64 v[224:225], s[0:1], 0, v[140:141]
	s_addc_u32 s85, s1, 0
	s_add_i32 s86, s67, s33
	global_load_lds_dwordx4 v[224:225], off
	v_lshl_add_u64 v[226:227], s[84:85], 0, v[136:137]
	s_mov_b32 m0, s86
	v_lshl_add_u64 v[228:229], s[36:37], 0, v[138:139]
	global_load_lds_dwordx4 v[226:227], off
	v_lshl_add_u64 v[226:227], s[84:85], 0, v[140:141]
	s_add_i32 m0, s86, 0x2000
	s_nop 0
	global_load_lds_dwordx4 v[226:227], off
	v_lshl_add_u64 v[226:227], s[36:37], 0, v[134:135]
	s_mov_b32 m0, s44
	s_nop 0
	global_load_lds_dwordx4 v[226:227], off
	s_mov_b32 m0, s45
	s_nop 0
	global_load_lds_dwordx4 v[228:229], off
	s_waitcnt vmcnt(8)
	s_waitcnt lgkmcnt(0)
	s_barrier
; #define PG8_STAGE(bufoff, gbase, voff) do { _Pragma("unroll") for (int _i = 0; _i < 2; ++_i) \
;         __builtin_amdgcn_global_load_lds((const unsigned*)((const char*)(gbase) + (voff)[_i]), (PG8_LAS unsigned*)(lds + (bufoff) + ldsw + _i * 8192), 16, 0, 0); } while (0)
; #define PG8_LDA(dst, b, h) do { _Pragma("unroll") for (int m = 0; m < 4; ++m) _Pragma("unroll") for (int k = 0; k < 2; ++k) dst[m][k] = *(const PG8_LAS bf16x8*)(lds + PG8_SA(b, h) + aoff + m * 2048 + k * 1024); } while (0)
; #define PG8_LDB(dst, b, h) do { _Pragma("unroll") for (int n = 0; n < 2; ++n) _Pragma("unroll") for (int k = 0; k < 2; ++k) dst[n][k] = *(const PG8_LAS bf16x8*)(lds + PG8_SB(b, h) + boff + n * 2048 + k * 1024); } while (0)
; #define PG8_MMA(ai, bj, At, Bt) do { __builtin_amdgcn_s_setprio(3); _Pragma("unroll") for (int m = 0; m < 4; ++m) _Pragma("unroll") for (int n = 0; n < 2; ++n) _Pragma("unroll") for (int k = 0; k < 2; ++k) \
;         acc[ai][bj][m][n] = __builtin_amdgcn_mfma_f32_16x16x32_bf16(Bt[n][k], At[m][k], acc[ai][bj][m][n], 0, 0, 0); __builtin_amdgcn_s_setprio(0); } while (0)
; #define PG8_WAIT_V(n) asm volatile("s_waitcnt vmcnt(" #n ")" ::: "memory")
; #define PG8_WAIT_L(n) asm volatile("s_waitcnt lgkmcnt(" #n ")" ::: "memory")
; #define PG8_BAR __builtin_amdgcn_s_barrier()
; #define PG8_SCHED __builtin_amdgcn_sched_barrier(0)
; template <class Epi, class Sched, bool ALIGN_EPI = false, bool SP2 = false>
; __device__ __forceinline__ void gemm_phase(PG8_LAS unsigned char* lds, const Gemm g, const Sched& S, const Epi& E) {
;     ...
;             PG8_WAIT_V(8); PG8_WAIT_L(0); PG8_BAR; PG8_MMA(1, 0, At, B0); PG8_MMA(1, 1, At, B1); PG8_BAR; PG8_SCHED;
;             PG8_LDB(B0, 1, 0); PG8_LDB(B1, 1, 1); PG8_SCHED; PG8_LDA(At, 1, 0); PG8_STAGE(PG8_SA(0, 1), a2 + hstepA, voffA);
;             PG8_WAIT_V(8); PG8_WAIT_L(0); PG8_BAR; PG8_MMA(0, 0, At, B0); PG8_MMA(0, 1, At, B1); PG8_BAR; PG8_SCHED;
	v_mfma_f32_16x16x32_bf16 v[62:65], v[130:133], v[192:195], v[62:65]
	v_mfma_f32_16x16x32_bf16 v[62:65], v[164:167], v[196:199], v[62:65]
	v_mfma_f32_16x16x32_bf16 v[58:61], v[168:171], v[192:195], v[58:61]
	v_mfma_f32_16x16x32_bf16 v[58:61], v[172:175], v[196:199], v[58:61]
	v_mfma_f32_16x16x32_bf16 v[42:45], v[168:171], v[200:203], v[42:45]
	v_mfma_f32_16x16x32_bf16 v[42:45], v[172:175], v[204:207], v[42:45]
	v_mfma_f32_16x16x32_bf16 v[46:49], v[130:133], v[200:203], v[46:49]
	v_mfma_f32_16x16x32_bf16 v[46:49], v[164:167], v[204:207], v[46:49]
	v_mfma_f32_16x16x32_bf16 v[30:33], v[130:133], v[208:211], v[30:33]
	v_mfma_f32_16x16x32_bf16 v[30:33], v[164:167], v[212:215], v[30:33]
	v_mfma_f32_16x16x32_bf16 v[26:29], v[168:171], v[208:211], v[26:29]
	v_mfma_f32_16x16x32_bf16 v[26:29], v[172:175], v[212:215], v[26:29]
	v_mfma_f32_16x16x32_bf16 v[10:13], v[168:171], v[216:219], v[10:13]
	v_mfma_f32_16x16x32_bf16 v[10:13], v[172:175], v[220:223], v[10:13]
	v_mfma_f32_16x16x32_bf16 v[14:17], v[130:133], v[216:219], v[14:17]
	v_mfma_f32_16x16x32_bf16 v[14:17], v[164:167], v[220:223], v[14:17]
	v_mfma_f32_16x16x32_bf16 v[54:57], v[176:179], v[192:195], v[54:57]
	v_mfma_f32_16x16x32_bf16 v[54:57], v[180:183], v[196:199], v[54:57]
	v_mfma_f32_16x16x32_bf16 v[50:53], v[184:187], v[192:195], v[50:53]
	v_mfma_f32_16x16x32_bf16 v[50:53], v[188:191], v[196:199], v[50:53]
	v_mfma_f32_16x16x32_bf16 v[34:37], v[184:187], v[200:203], v[34:37]
	v_mfma_f32_16x16x32_bf16 v[34:37], v[188:191], v[204:207], v[34:37]
	v_mfma_f32_16x16x32_bf16 v[38:41], v[176:179], v[200:203], v[38:41]
	v_mfma_f32_16x16x32_bf16 v[38:41], v[180:183], v[204:207], v[38:41]
	v_mfma_f32_16x16x32_bf16 v[22:25], v[176:179], v[208:211], v[22:25]
	v_mfma_f32_16x16x32_bf16 v[22:25], v[180:183], v[212:215], v[22:25]
	v_mfma_f32_16x16x32_bf16 v[18:21], v[184:187], v[208:211], v[18:21]
	v_mfma_f32_16x16x32_bf16 v[18:21], v[188:191], v[212:215], v[18:21]
	v_mfma_f32_16x16x32_bf16 v[2:5], v[184:187], v[216:219], v[2:5]
	v_mfma_f32_16x16x32_bf16 v[2:5], v[188:191], v[220:223], v[2:5]
	v_mfma_f32_16x16x32_bf16 v[6:9], v[176:179], v[216:219], v[6:9]
	v_mfma_f32_16x16x32_bf16 v[6:9], v[180:183], v[220:223], v[6:9]
	s_barrier
	s_add_i32 s84, 0, 0x18000
	v_add_u32_e32 v163, s84, v157
	s_add_i32 s85, 0, 0x1c000
	ds_read_b128 v[130:133], v163
	ds_read_b128 v[164:167], v163 offset:1024
	ds_read_b128 v[168:171], v163 offset:2048
	ds_read_b128 v[172:175], v163 offset:3072
	v_add_u32_e32 v163, s85, v157
	ds_read_b128 v[176:179], v163
	ds_read_b128 v[180:183], v163 offset:1024
	ds_read_b128 v[184:187], v163 offset:2048
	ds_read_b128 v[188:191], v163 offset:3072
	s_add_u32 s36, s36, 0x100000
	s_addc_u32 s37, s37, 0
	s_mov_b32 m0, s54
	v_lshl_add_u64 v[230:231], s[36:37], 0, v[134:135]
	ds_read_b128 v[192:195], v159 offset:32768
	ds_read_b128 v[196:199], v159 offset:33792
	ds_read_b128 v[200:203], v159 offset:34816
	ds_read_b128 v[204:207], v159 offset:35840
	ds_read_b128 v[208:211], v159 offset:36864
	ds_read_b128 v[212:215], v159 offset:37888
	ds_read_b128 v[216:219], v159 offset:38912
	ds_read_b128 v[220:223], v159 offset:39936
	global_load_lds_dwordx4 v[230:231], off
	v_lshl_add_u64 v[230:231], s[36:37], 0, v[138:139]
	s_mov_b32 m0, s55
	s_nop 0
	global_load_lds_dwordx4 v[230:231], off
	s_waitcnt vmcnt(8)
	s_waitcnt lgkmcnt(0)
	s_barrier
	v_mfma_f32_16x16x32_bf16 v[126:129], v[130:133], v[192:195], v[126:129]
	v_mfma_f32_16x16x32_bf16 v[126:129], v[164:167], v[196:199], v[126:129]
	v_mfma_f32_16x16x32_bf16 v[122:125], v[168:171], v[192:195], v[122:125]
	v_mfma_f32_16x16x32_bf16 v[122:125], v[172:175], v[196:199], v[122:125]
	v_mfma_f32_16x16x32_bf16 v[106:109], v[168:171], v[200:203], v[106:109]
	v_mfma_f32_16x16x32_bf16 v[106:109], v[172:175], v[204:207], v[106:109]
	v_mfma_f32_16x16x32_bf16 v[110:113], v[130:133], v[200:203], v[110:113]
	v_mfma_f32_16x16x32_bf16 v[110:113], v[164:167], v[204:207], v[110:113]
	v_mfma_f32_16x16x32_bf16 v[94:97], v[130:133], v[208:211], v[94:97]
	v_mfma_f32_16x16x32_bf16 v[94:97], v[164:167], v[212:215], v[94:97]
	v_mfma_f32_16x16x32_bf16 v[90:93], v[168:171], v[208:211], v[90:93]
	v_mfma_f32_16x16x32_bf16 v[90:93], v[172:175], v[212:215], v[90:93]
	v_mfma_f32_16x16x32_bf16 v[74:77], v[168:171], v[216:219], v[74:77]
	v_mfma_f32_16x16x32_bf16 v[74:77], v[172:175], v[220:223], v[74:77]
	v_mfma_f32_16x16x32_bf16 v[78:81], v[130:133], v[216:219], v[78:81]
	v_mfma_f32_16x16x32_bf16 v[78:81], v[164:167], v[220:223], v[78:81]
	v_mfma_f32_16x16x32_bf16 v[118:121], v[176:179], v[192:195], v[118:121]
	v_mfma_f32_16x16x32_bf16 v[118:121], v[180:183], v[196:199], v[118:121]
	v_mfma_f32_16x16x32_bf16 v[114:117], v[184:187], v[192:195], v[114:117]
	v_mfma_f32_16x16x32_bf16 v[114:117], v[188:191], v[196:199], v[114:117]
	v_mfma_f32_16x16x32_bf16 v[98:101], v[184:187], v[200:203], v[98:101]
	v_mfma_f32_16x16x32_bf16 v[98:101], v[188:191], v[204:207], v[98:101]
	v_mfma_f32_16x16x32_bf16 v[102:105], v[176:179], v[200:203], v[102:105]
	v_mfma_f32_16x16x32_bf16 v[102:105], v[180:183], v[204:207], v[102:105]
	v_mfma_f32_16x16x32_bf16 v[86:89], v[176:179], v[208:211], v[86:89]
	v_mfma_f32_16x16x32_bf16 v[86:89], v[180:183], v[212:215], v[86:89]
	v_mfma_f32_16x16x32_bf16 v[82:85], v[184:187], v[208:211], v[82:85]
	v_mfma_f32_16x16x32_bf16 v[82:85], v[188:191], v[212:215], v[82:85]
	v_mfma_f32_16x16x32_bf16 v[66:69], v[184:187], v[216:219], v[66:69]
	v_mfma_f32_16x16x32_bf16 v[66:69], v[188:191], v[220:223], v[66:69]
	v_mfma_f32_16x16x32_bf16 v[70:73], v[176:179], v[216:219], v[70:73]
	v_mfma_f32_16x16x32_bf16 v[70:73], v[180:183], v[220:223], v[70:73]
	s_barrier
; #define PG8_STAGE(bufoff, gbase, voff) do { _Pragma("unroll") for (int _i = 0; _i < 2; ++_i) \
;         __builtin_amdgcn_global_load_lds((const unsigned*)((const char*)(gbase) + (voff)[_i]), (PG8_LAS unsigned*)(lds + (bufoff) + ldsw + _i * 8192), 16, 0, 0); } while (0)
; #define PG8_LDA(dst, b, h) do { _Pragma("unroll") for (int m = 0; m < 4; ++m) _Pragma("unroll") for (int k = 0; k < 2; ++k) dst[m][k] = *(const PG8_LAS bf16x8*)(lds + PG8_SA(b, h) + aoff + m * 2048 + k * 1024); } while (0)
; #define PG8_MMA(ai, bj, At, Bt) do { __builtin_amdgcn_s_setprio(3); _Pragma("unroll") for (int m = 0; m < 4; ++m) _Pragma("unroll") for (int n = 0; n < 2; ++n) _Pragma("unroll") for (int k = 0; k < 2; ++k) \
;         acc[ai][bj][m][n] = __builtin_amdgcn_mfma_f32_16x16x32_bf16(Bt[n][k], At[m][k], acc[ai][bj][m][n], 0, 0, 0); __builtin_amdgcn_s_setprio(0); } while (0)
; #define PG8_WAIT_V(n) asm volatile("s_waitcnt vmcnt(" #n ")" ::: "memory")
; #define PG8_WAIT_L(n) asm volatile("s_waitcnt lgkmcnt(" #n ")" ::: "memory")
; #define PG8_BAR __builtin_amdgcn_s_barrier()
; #define PG8_SCHED __builtin_amdgcn_sched_barrier(0)
; template <class Epi, class Sched, bool ALIGN_EPI = false, bool SP2 = false>
; __device__ __forceinline__ void gemm_phase(PG8_LAS unsigned char* lds, const Gemm g, const Sched& S, const Epi& E) {
;     ...
;             PG8_LDA(At, 1, 1); PG8_STAGE(PG8_SB(1, 0), b3, voffB); PG8_STAGE(PG8_SB(1, 1), b3 + hstepB, voffB); PG8_STAGE(PG8_SA(1, 0), a3, voffA);
;             PG8_WAIT_V(8); PG8_WAIT_L(0); PG8_BAR; PG8_MMA(1, 0, At, B0); PG8_MMA(1, 1, At, B1); PG8_BAR; PG8_SCHED;
	s_add_i32 s36, s84, s33
	v_lshl_add_u64 v[160:161], v[160:161], 0, s[10:11]
	s_mov_b32 m0, s36
	ds_read_b128 v[192:195], v159 offset:49152
	ds_read_b128 v[196:199], v159 offset:50176
	ds_read_b128 v[200:203], v159 offset:51200
	ds_read_b128 v[204:207], v159 offset:52224
	ds_read_b128 v[208:211], v159 offset:53248
	ds_read_b128 v[212:215], v159 offset:54272
	ds_read_b128 v[216:219], v159 offset:55296
	ds_read_b128 v[220:223], v159 offset:56320
	global_load_lds_dwordx4 v[160:161], off
	s_add_i32 m0, s36, 0x2000
	s_add_u32 s0, s0, 0x100080
	v_lshl_add_u64 v[160:161], v[224:225], 0, s[10:11]
	s_addc_u32 s1, s1, 0
	s_add_i32 s36, s85, s33
	global_load_lds_dwordx4 v[160:161], off
	v_lshl_add_u64 v[160:161], s[0:1], 0, v[136:137]
	s_mov_b32 m0, s36
	s_nop 0
	global_load_lds_dwordx4 v[160:161], off
	v_lshl_add_u64 v[160:161], s[0:1], 0, v[140:141]
	s_add_i32 m0, s36, 0x2000
	s_nop 0
	global_load_lds_dwordx4 v[160:161], off
	v_lshl_add_u64 v[160:161], v[226:227], 0, s[10:11]
	s_mov_b32 m0, s61
	s_nop 0
	global_load_lds_dwordx4 v[160:161], off
	v_lshl_add_u64 v[160:161], v[228:229], 0, s[10:11]
	s_mov_b32 m0, s62
	s_nop 0
	global_load_lds_dwordx4 v[160:161], off
	s_waitcnt vmcnt(8)
	s_waitcnt lgkmcnt(0)
	s_barrier
	v_mfma_f32_16x16x32_bf16 v[62:65], v[130:133], v[192:195], v[62:65]
	v_mfma_f32_16x16x32_bf16 v[62:65], v[164:167], v[196:199], v[62:65]
	v_mfma_f32_16x16x32_bf16 v[58:61], v[168:171], v[192:195], v[58:61]
	v_mfma_f32_16x16x32_bf16 v[58:61], v[172:175], v[196:199], v[58:61]
	v_mfma_f32_16x16x32_bf16 v[42:45], v[168:171], v[200:203], v[42:45]
	v_mfma_f32_16x16x32_bf16 v[42:45], v[172:175], v[204:207], v[42:45]
	v_mfma_f32_16x16x32_bf16 v[46:49], v[130:133], v[200:203], v[46:49]
	v_mfma_f32_16x16x32_bf16 v[46:49], v[164:167], v[204:207], v[46:49]
	v_mfma_f32_16x16x32_bf16 v[30:33], v[130:133], v[208:211], v[30:33]
	v_mfma_f32_16x16x32_bf16 v[30:33], v[164:167], v[212:215], v[30:33]
	v_mfma_f32_16x16x32_bf16 v[26:29], v[168:171], v[208:211], v[26:29]
	v_mfma_f32_16x16x32_bf16 v[26:29], v[172:175], v[212:215], v[26:29]
	v_mfma_f32_16x16x32_bf16 v[10:13], v[168:171], v[216:219], v[10:13]
	v_mfma_f32_16x16x32_bf16 v[10:13], v[172:175], v[220:223], v[10:13]
	v_mfma_f32_16x16x32_bf16 v[14:17], v[130:133], v[216:219], v[14:17]
	v_mfma_f32_16x16x32_bf16 v[14:17], v[164:167], v[220:223], v[14:17]
	v_mfma_f32_16x16x32_bf16 v[54:57], v[176:179], v[192:195], v[54:57]
	v_mfma_f32_16x16x32_bf16 v[54:57], v[180:183], v[196:199], v[54:57]
	v_mfma_f32_16x16x32_bf16 v[50:53], v[184:187], v[192:195], v[50:53]
	v_mfma_f32_16x16x32_bf16 v[50:53], v[188:191], v[196:199], v[50:53]
	v_mfma_f32_16x16x32_bf16 v[34:37], v[184:187], v[200:203], v[34:37]
	v_mfma_f32_16x16x32_bf16 v[34:37], v[188:191], v[204:207], v[34:37]
	v_mfma_f32_16x16x32_bf16 v[38:41], v[176:179], v[200:203], v[38:41]
	v_mfma_f32_16x16x32_bf16 v[38:41], v[180:183], v[204:207], v[38:41]
	v_mfma_f32_16x16x32_bf16 v[22:25], v[176:179], v[208:211], v[22:25]
	v_mfma_f32_16x16x32_bf16 v[22:25], v[180:183], v[212:215], v[22:25]
	v_mfma_f32_16x16x32_bf16 v[18:21], v[184:187], v[208:211], v[18:21]
	v_mfma_f32_16x16x32_bf16 v[18:21], v[188:191], v[212:215], v[18:21]
	v_mfma_f32_16x16x32_bf16 v[2:5], v[184:187], v[216:219], v[2:5]
	v_mfma_f32_16x16x32_bf16 v[2:5], v[188:191], v[220:223], v[2:5]
	v_mfma_f32_16x16x32_bf16 v[6:9], v[176:179], v[216:219], v[6:9]
	v_mfma_f32_16x16x32_bf16 v[6:9], v[180:183], v[220:223], v[6:9]
	s_barrier
	s_add_i32 s83, s83, 2
	s_add_u32 s30, s30, 0x100
	s_addc_u32 s31, s31, 0
	s_cmp_gt_u32 s83, 61
	s_cbranch_scc1 .LBB0_730

; #define PG8_STAGE(bufoff, gbase, voff) do { _Pragma("unroll") for (int _i = 0; _i < 2; ++_i) \
;         __builtin_amdgcn_global_load_lds((const unsigned*)((const char*)(gbase) + (voff)[_i]), (PG8_LAS unsigned*)(lds + (bufoff) + ldsw + _i * 8192), 16, 0, 0); } while (0)
; #define PG8_LDA(dst, b, h) do { _Pragma("unroll") for (int m = 0; m < 4; ++m) _Pragma("unroll") for (int k = 0; k < 2; ++k) dst[m][k] = *(const PG8_LAS bf16x8*)(lds + PG8_SA(b, h) + aoff + m * 2048 + k * 1024); } while (0)
; #define PG8_LDB(dst, b, h) do { _Pragma("unroll") for (int n = 0; n < 2; ++n) _Pragma("unroll") for (int k = 0; k < 2; ++k) dst[n][k] = *(const PG8_LAS bf16x8*)(lds + PG8_SB(b, h) + boff + n * 2048 + k * 1024); } while (0)
; #define PG8_MMA(ai, bj, At, Bt) do { __builtin_amdgcn_s_setprio(3); _Pragma("unroll") for (int m = 0; m < 4; ++m) _Pragma("unroll") for (int n = 0; n < 2; ++n) _Pragma("unroll") for (int k = 0; k < 2; ++k) \
;         acc[ai][bj][m][n] = __builtin_amdgcn_mfma_f32_16x16x32_bf16(Bt[n][k], At[m][k], acc[ai][bj][m][n], 0, 0, 0); __builtin_amdgcn_s_setprio(0); } while (0)
; #define PG8_WAIT_V(n) asm volatile("s_waitcnt vmcnt(" #n ")" ::: "memory")
; #define PG8_WAIT_L(n) asm volatile("s_waitcnt lgkmcnt(" #n ")" ::: "memory")
; #define PG8_BAR __builtin_amdgcn_s_barrier()
; template <class Epi, class Sched, bool ALIGN_EPI = false, bool SP2 = false>
; __device__ __forceinline__ void gemm_phase(PG8_LAS unsigned char* lds, const Gemm g, const Sched& S, const Epi& E) {
;     ...
;             const bool last = (t == nt - 2);
;             const char* a1 = cA + (size_t)(t + 1) * kstep;
;             const char* a2 = last ? nA : cA + (size_t)(t + 2) * kstep; const char* b2 = last ? nB : cB + (size_t)(t + 2) * kstep;
;             const char* a3 = a2 + kstep; const char* b3 = b2 + kstep;
;             if (last && has_next) S.a_ready(nxt);
;             if constexpr (Epi::MIDK) { if (t == E.midk_step(nt)) E.midk(acc, cur, wr, wc, fr, fq); }
;             if constexpr (SP2) {
;             PG8_LDB(B0, 0, 0); PG8_LDB(B1, 0, 1); PG8_SCHED; PG8_LDA(At, 0, 0); PG8_STAGE(PG8_SA(1, 1), a1 + hstepA, voffA);
;             PG8_WAIT_V(8); PG8_WAIT_L(0); PG8_BAR; PG8_MMA(0, 0, At, B0); PG8_MMA(0, 1, At, B1); PG8_BAR; PG8_SCHED;
;             PG8_LDA(At, 0, 1); PG8_STAGE(PG8_SB(0, 0), b2, voffB); PG8_STAGE(PG8_SB(0, 1), b2 + hstepB, voffB); PG8_STAGE(PG8_SA(0, 0), a2, voffA);
.LBB0_808:
	v_add_u32_e32 v3, s65, v186
	ds_read_b128 v[134:137], v3
	ds_read_b128 v[138:141], v3 offset:1024
	ds_read_b128 v[142:145], v3 offset:2048
	ds_read_b128 v[146:149], v3 offset:3072
	v_add_u32_e32 v3, s66, v186
	s_add_u32 s36, s28, s30
	ds_read_b128 v[150:153], v3
	ds_read_b128 v[154:157], v3 offset:1024
	ds_read_b128 v[158:161], v3 offset:2048
	ds_read_b128 v[190:193], v3 offset:3072
	s_addc_u32 s37, s29, s31
	s_add_u32 s36, s36, 0x100
	s_addc_u32 s37, s37, 0
	s_add_u32 s86, s83, s30
	s_addc_u32 s87, s84, s31
	s_cmpk_eq_i32 s30, 0x1f00
	s_cselect_b32 s41, s23, s37
	s_cselect_b32 s40, s75, s36
	s_cselect_b32 s37, s77, s87
	s_cselect_b32 s36, s78, s86
	v_lshl_add_u64 v[4:5], v[180:181], 0, s[30:31]
	s_add_i32 m0, s42, 0xc000
	ds_read_b128 v[194:197], v188
	ds_read_b128 v[198:201], v188 offset:1024
	ds_read_b128 v[202:205], v188 offset:2048
	ds_read_b128 v[206:209], v188 offset:3072
	ds_read_b128 v[210:213], v188 offset:4096
	ds_read_b128 v[214:217], v188 offset:5120
	ds_read_b128 v[218:221], v188 offset:6144
	ds_read_b128 v[222:225], v188 offset:7168
	global_load_lds_dwordx4 v[4:5], off
	v_lshl_add_u64 v[4:5], v[182:183], 0, s[30:31]
	s_add_i32 m0, s42, 0xe000
	s_nop 0
	global_load_lds_dwordx4 v[4:5], off
	s_waitcnt vmcnt(8)
	s_waitcnt lgkmcnt(0)
	s_barrier
	v_mfma_f32_16x16x32_bf16 v[130:133], v[134:137], v[194:197], v[130:133]
	v_mfma_f32_16x16x32_bf16 v[130:133], v[138:141], v[198:201], v[130:133]
	v_mfma_f32_16x16x32_bf16 v[126:129], v[142:145], v[194:197], v[126:129]
	v_mfma_f32_16x16x32_bf16 v[126:129], v[146:149], v[198:201], v[126:129]
	v_mfma_f32_16x16x32_bf16 v[110:113], v[142:145], v[202:205], v[110:113]
	v_mfma_f32_16x16x32_bf16 v[110:113], v[146:149], v[206:209], v[110:113]
	v_mfma_f32_16x16x32_bf16 v[114:117], v[134:137], v[202:205], v[114:117]
	v_mfma_f32_16x16x32_bf16 v[114:117], v[138:141], v[206:209], v[114:117]
	v_mfma_f32_16x16x32_bf16 v[98:101], v[134:137], v[210:213], v[98:101]
	v_mfma_f32_16x16x32_bf16 v[98:101], v[138:141], v[214:217], v[98:101]
	v_mfma_f32_16x16x32_bf16 v[94:97], v[142:145], v[210:213], v[94:97]
	v_mfma_f32_16x16x32_bf16 v[94:97], v[146:149], v[214:217], v[94:97]
	v_mfma_f32_16x16x32_bf16 v[78:81], v[142:145], v[218:221], v[78:81]
	v_mfma_f32_16x16x32_bf16 v[78:81], v[146:149], v[222:225], v[78:81]
	v_mfma_f32_16x16x32_bf16 v[82:85], v[134:137], v[218:221], v[82:85]
	v_mfma_f32_16x16x32_bf16 v[82:85], v[138:141], v[222:225], v[82:85]
	v_mfma_f32_16x16x32_bf16 v[122:125], v[150:153], v[194:197], v[122:125]
	v_mfma_f32_16x16x32_bf16 v[122:125], v[154:157], v[198:201], v[122:125]
	v_mfma_f32_16x16x32_bf16 v[118:121], v[158:161], v[194:197], v[118:121]
	v_mfma_f32_16x16x32_bf16 v[118:121], v[190:193], v[198:201], v[118:121]
	v_mfma_f32_16x16x32_bf16 v[102:105], v[158:161], v[202:205], v[102:105]
	v_mfma_f32_16x16x32_bf16 v[102:105], v[190:193], v[206:209], v[102:105]
	v_mfma_f32_16x16x32_bf16 v[106:109], v[150:153], v[202:205], v[106:109]
	v_mfma_f32_16x16x32_bf16 v[106:109], v[154:157], v[206:209], v[106:109]
	v_mfma_f32_16x16x32_bf16 v[90:93], v[150:153], v[210:213], v[90:93]
	v_mfma_f32_16x16x32_bf16 v[90:93], v[154:157], v[214:217], v[90:93]
	v_mfma_f32_16x16x32_bf16 v[86:89], v[158:161], v[210:213], v[86:89]
	v_mfma_f32_16x16x32_bf16 v[86:89], v[190:193], v[214:217], v[86:89]
	v_mfma_f32_16x16x32_bf16 v[70:73], v[158:161], v[218:221], v[70:73]
	v_mfma_f32_16x16x32_bf16 v[70:73], v[190:193], v[222:225], v[70:73]
	v_mfma_f32_16x16x32_bf16 v[74:77], v[150:153], v[218:221], v[74:77]
	v_mfma_f32_16x16x32_bf16 v[74:77], v[154:157], v[222:225], v[74:77]
	s_barrier
	s_add_i32 s86, s65, s33
	v_lshl_add_u64 v[226:227], s[36:37], 0, v[166:167]
	s_mov_b32 m0, s86
	ds_read_b128 v[194:197], v188 offset:16384
	ds_read_b128 v[198:201], v188 offset:17408
	ds_read_b128 v[202:205], v188 offset:18432
	ds_read_b128 v[206:209], v188 offset:19456
	ds_read_b128 v[210:213], v188 offset:20480
	ds_read_b128 v[214:217], v188 offset:21504
	ds_read_b128 v[218:221], v188 offset:22528
	ds_read_b128 v[222:225], v188 offset:23552
	global_load_lds_dwordx4 v[226:227], off
	s_add_i32 m0, s86, 0x2000
	s_add_u32 s86, s36, 0x100000
	v_lshl_add_u64 v[228:229], s[36:37], 0, v[170:171]
	s_addc_u32 s87, s37, 0
	s_add_i32 s88, s66, s33
	global_load_lds_dwordx4 v[228:229], off
	v_lshl_add_u64 v[4:5], s[86:87], 0, v[166:167]
	s_mov_b32 m0, s88
	v_lshl_add_u64 v[230:231], s[40:41], 0, v[164:165]
	global_load_lds_dwordx4 v[4:5], off
	v_lshl_add_u64 v[4:5], s[86:87], 0, v[170:171]
	s_add_i32 m0, s88, 0x2000
	v_lshl_add_u64 v[232:233], s[40:41], 0, v[168:169]
	global_load_lds_dwordx4 v[4:5], off
	s_mov_b32 m0, s42
	s_nop 0
	global_load_lds_dwordx4 v[230:231], off
	s_mov_b32 m0, s43
	s_nop 0
	global_load_lds_dwordx4 v[232:233], off
	s_waitcnt vmcnt(8)
	s_waitcnt lgkmcnt(0)
	s_barrier
; #define PG8_STAGE(bufoff, gbase, voff) do { _Pragma("unroll") for (int _i = 0; _i < 2; ++_i) \
;         __builtin_amdgcn_global_load_lds((const unsigned*)((const char*)(gbase) + (voff)[_i]), (PG8_LAS unsigned*)(lds + (bufoff) + ldsw + _i * 8192), 16, 0, 0); } while (0)
; #define PG8_LDA(dst, b, h) do { _Pragma("unroll") for (int m = 0; m < 4; ++m) _Pragma("unroll") for (int k = 0; k < 2; ++k) dst[m][k] = *(const PG8_LAS bf16x8*)(lds + PG8_SA(b, h) + aoff + m * 2048 + k * 1024); } while (0)
; #define PG8_LDB(dst, b, h) do { _Pragma("unroll") for (int n = 0; n < 2; ++n) _Pragma("unroll") for (int k = 0; k < 2; ++k) dst[n][k] = *(const PG8_LAS bf16x8*)(lds + PG8_SB(b, h) + boff + n * 2048 + k * 1024); } while (0)
; #define PG8_MMA(ai, bj, At, Bt) do { __builtin_amdgcn_s_setprio(3); _Pragma("unroll") for (int m = 0; m < 4; ++m) _Pragma("unroll") for (int n = 0; n < 2; ++n) _Pragma("unroll") for (int k = 0; k < 2; ++k) \
;         acc[ai][bj][m][n] = __builtin_amdgcn_mfma_f32_16x16x32_bf16(Bt[n][k], At[m][k], acc[ai][bj][m][n], 0, 0, 0); __builtin_amdgcn_s_setprio(0); } while (0)
; #define PG8_WAIT_V(n) asm volatile("s_waitcnt vmcnt(" #n ")" ::: "memory")
; #define PG8_WAIT_L(n) asm volatile("s_waitcnt lgkmcnt(" #n ")" ::: "memory")
; #define PG8_BAR __builtin_amdgcn_s_barrier()
; #define PG8_SCHED __builtin_amdgcn_sched_barrier(0)
; template <class Epi, class Sched, bool ALIGN_EPI = false, bool SP2 = false>
; __device__ __forceinline__ void gemm_phase(PG8_LAS unsigned char* lds, const Gemm g, const Sched& S, const Epi& E) {
;     ...
;             PG8_WAIT_V(8); PG8_WAIT_L(0); PG8_BAR; PG8_MMA(1, 0, At, B0); PG8_MMA(1, 1, At, B1); PG8_BAR; PG8_SCHED;
;             PG8_LDB(B0, 1, 0); PG8_LDB(B1, 1, 1); PG8_SCHED; PG8_LDA(At, 1, 0); PG8_STAGE(PG8_SA(0, 1), a2 + hstepA, voffA);
;             PG8_WAIT_V(8); PG8_WAIT_L(0); PG8_BAR; PG8_MMA(0, 0, At, B0); PG8_MMA(0, 1, At, B1); PG8_BAR; PG8_SCHED;
	v_mfma_f32_16x16x32_bf16 v[66:69], v[134:137], v[194:197], v[66:69]
	v_mfma_f32_16x16x32_bf16 v[66:69], v[138:141], v[198:201], v[66:69]
	v_mfma_f32_16x16x32_bf16 v[62:65], v[142:145], v[194:197], v[62:65]
	v_mfma_f32_16x16x32_bf16 v[62:65], v[146:149], v[198:201], v[62:65]
	v_mfma_f32_16x16x32_bf16 v[46:49], v[142:145], v[202:205], v[46:49]
	v_mfma_f32_16x16x32_bf16 v[46:49], v[146:149], v[206:209], v[46:49]
	v_mfma_f32_16x16x32_bf16 v[50:53], v[134:137], v[202:205], v[50:53]
	v_mfma_f32_16x16x32_bf16 v[50:53], v[138:141], v[206:209], v[50:53]
	v_mfma_f32_16x16x32_bf16 v[34:37], v[134:137], v[210:213], v[34:37]
	v_mfma_f32_16x16x32_bf16 v[34:37], v[138:141], v[214:217], v[34:37]
	v_mfma_f32_16x16x32_bf16 v[30:33], v[142:145], v[210:213], v[30:33]
	v_mfma_f32_16x16x32_bf16 v[30:33], v[146:149], v[214:217], v[30:33]
	v_mfma_f32_16x16x32_bf16 v[14:17], v[142:145], v[218:221], v[14:17]
	v_mfma_f32_16x16x32_bf16 v[14:17], v[146:149], v[222:225], v[14:17]
	v_mfma_f32_16x16x32_bf16 v[18:21], v[134:137], v[218:221], v[18:21]
	v_mfma_f32_16x16x32_bf16 v[18:21], v[138:141], v[222:225], v[18:21]
	v_mfma_f32_16x16x32_bf16 v[58:61], v[150:153], v[194:197], v[58:61]
	v_mfma_f32_16x16x32_bf16 v[58:61], v[154:157], v[198:201], v[58:61]
	v_mfma_f32_16x16x32_bf16 v[54:57], v[158:161], v[194:197], v[54:57]
	v_mfma_f32_16x16x32_bf16 v[54:57], v[190:193], v[198:201], v[54:57]
	v_mfma_f32_16x16x32_bf16 v[38:41], v[158:161], v[202:205], v[38:41]
	v_mfma_f32_16x16x32_bf16 v[38:41], v[190:193], v[206:209], v[38:41]
	v_mfma_f32_16x16x32_bf16 v[42:45], v[150:153], v[202:205], v[42:45]
	v_mfma_f32_16x16x32_bf16 v[42:45], v[154:157], v[206:209], v[42:45]
	v_mfma_f32_16x16x32_bf16 v[26:29], v[150:153], v[210:213], v[26:29]
	v_mfma_f32_16x16x32_bf16 v[26:29], v[154:157], v[214:217], v[26:29]
	v_mfma_f32_16x16x32_bf16 v[22:25], v[158:161], v[210:213], v[22:25]
	v_mfma_f32_16x16x32_bf16 v[22:25], v[190:193], v[214:217], v[22:25]
	v_mfma_f32_16x16x32_bf16 v[4:7], v[158:161], v[218:221], v[6:9]
	v_mfma_f32_16x16x32_bf16 v[4:7], v[190:193], v[222:225], v[4:7]
	v_mfma_f32_16x16x32_bf16 v[10:13], v[150:153], v[218:221], v[10:13]
	v_mfma_f32_16x16x32_bf16 v[10:13], v[154:157], v[222:225], v[10:13]
	s_barrier
	s_add_i32 s86, 0, 0x18000
	v_add_u32_e32 v3, s86, v186
	s_add_i32 s87, 0, 0x1c000
	ds_read_b128 v[134:137], v3
	ds_read_b128 v[138:141], v3 offset:1024
	ds_read_b128 v[142:145], v3 offset:2048
	ds_read_b128 v[146:149], v3 offset:3072
	v_add_u32_e32 v3, s87, v186
	ds_read_b128 v[150:153], v3
	ds_read_b128 v[154:157], v3 offset:1024
	ds_read_b128 v[158:161], v3 offset:2048
	ds_read_b128 v[190:193], v3 offset:3072
	s_add_u32 s40, s40, 0x100000
	s_addc_u32 s41, s41, 0
	s_mov_b32 m0, s44
	v_lshl_add_u64 v[8:9], s[40:41], 0, v[164:165]
	ds_read_b128 v[194:197], v188 offset:32768
	ds_read_b128 v[198:201], v188 offset:33792
	ds_read_b128 v[202:205], v188 offset:34816
	ds_read_b128 v[206:209], v188 offset:35840
	ds_read_b128 v[210:213], v188 offset:36864
	ds_read_b128 v[214:217], v188 offset:37888
	ds_read_b128 v[218:221], v188 offset:38912
	ds_read_b128 v[222:225], v188 offset:39936
	global_load_lds_dwordx4 v[8:9], off
	v_lshl_add_u64 v[8:9], s[40:41], 0, v[168:169]
	s_mov_b32 m0, s45
	s_nop 0
	global_load_lds_dwordx4 v[8:9], off
	s_waitcnt vmcnt(8)
	s_waitcnt lgkmcnt(0)
	s_barrier
	v_mfma_f32_16x16x32_bf16 v[130:133], v[134:137], v[194:197], v[130:133]
	v_mfma_f32_16x16x32_bf16 v[130:133], v[138:141], v[198:201], v[130:133]
	v_mfma_f32_16x16x32_bf16 v[126:129], v[142:145], v[194:197], v[126:129]
	v_mfma_f32_16x16x32_bf16 v[126:129], v[146:149], v[198:201], v[126:129]
	v_mfma_f32_16x16x32_bf16 v[110:113], v[142:145], v[202:205], v[110:113]
	v_mfma_f32_16x16x32_bf16 v[110:113], v[146:149], v[206:209], v[110:113]
	v_mfma_f32_16x16x32_bf16 v[114:117], v[134:137], v[202:205], v[114:117]
	v_mfma_f32_16x16x32_bf16 v[114:117], v[138:141], v[206:209], v[114:117]
	v_mfma_f32_16x16x32_bf16 v[98:101], v[134:137], v[210:213], v[98:101]
	v_mfma_f32_16x16x32_bf16 v[98:101], v[138:141], v[214:217], v[98:101]
	v_mfma_f32_16x16x32_bf16 v[94:97], v[142:145], v[210:213], v[94:97]
	v_mfma_f32_16x16x32_bf16 v[94:97], v[146:149], v[214:217], v[94:97]
	v_mfma_f32_16x16x32_bf16 v[78:81], v[142:145], v[218:221], v[78:81]
	v_mfma_f32_16x16x32_bf16 v[78:81], v[146:149], v[222:225], v[78:81]
	v_mfma_f32_16x16x32_bf16 v[82:85], v[134:137], v[218:221], v[82:85]
	v_mfma_f32_16x16x32_bf16 v[82:85], v[138:141], v[222:225], v[82:85]
	v_mfma_f32_16x16x32_bf16 v[122:125], v[150:153], v[194:197], v[122:125]
	v_mfma_f32_16x16x32_bf16 v[122:125], v[154:157], v[198:201], v[122:125]
	v_mfma_f32_16x16x32_bf16 v[118:121], v[158:161], v[194:197], v[118:121]
	v_mfma_f32_16x16x32_bf16 v[118:121], v[190:193], v[198:201], v[118:121]
	v_mfma_f32_16x16x32_bf16 v[102:105], v[158:161], v[202:205], v[102:105]
	v_mfma_f32_16x16x32_bf16 v[102:105], v[190:193], v[206:209], v[102:105]
	v_mfma_f32_16x16x32_bf16 v[106:109], v[150:153], v[202:205], v[106:109]
	v_mfma_f32_16x16x32_bf16 v[106:109], v[154:157], v[206:209], v[106:109]
	v_mfma_f32_16x16x32_bf16 v[90:93], v[150:153], v[210:213], v[90:93]
	v_mfma_f32_16x16x32_bf16 v[90:93], v[154:157], v[214:217], v[90:93]
	v_mfma_f32_16x16x32_bf16 v[86:89], v[158:161], v[210:213], v[86:89]
	v_mfma_f32_16x16x32_bf16 v[86:89], v[190:193], v[214:217], v[86:89]
	v_mfma_f32_16x16x32_bf16 v[70:73], v[158:161], v[218:221], v[70:73]
	v_mfma_f32_16x16x32_bf16 v[70:73], v[190:193], v[222:225], v[70:73]
	v_mfma_f32_16x16x32_bf16 v[74:77], v[150:153], v[218:221], v[74:77]
	v_mfma_f32_16x16x32_bf16 v[74:77], v[154:157], v[222:225], v[74:77]
	s_barrier
; #define PG8_STAGE(bufoff, gbase, voff) do { _Pragma("unroll") for (int _i = 0; _i < 2; ++_i) \
;         __builtin_amdgcn_global_load_lds((const unsigned*)((const char*)(gbase) + (voff)[_i]), (PG8_LAS unsigned*)(lds + (bufoff) + ldsw + _i * 8192), 16, 0, 0); } while (0)
; #define PG8_LDA(dst, b, h) do { _Pragma("unroll") for (int m = 0; m < 4; ++m) _Pragma("unroll") for (int k = 0; k < 2; ++k) dst[m][k] = *(const PG8_LAS bf16x8*)(lds + PG8_SA(b, h) + aoff + m * 2048 + k * 1024); } while (0)
; #define PG8_MMA(ai, bj, At, Bt) do { __builtin_amdgcn_s_setprio(3); _Pragma("unroll") for (int m = 0; m < 4; ++m) _Pragma("unroll") for (int n = 0; n < 2; ++n) _Pragma("unroll") for (int k = 0; k < 2; ++k) \
;         acc[ai][bj][m][n] = __builtin_amdgcn_mfma_f32_16x16x32_bf16(Bt[n][k], At[m][k], acc[ai][bj][m][n], 0, 0, 0); __builtin_amdgcn_s_setprio(0); } while (0)
; #define PG8_WAIT_V(n) asm volatile("s_waitcnt vmcnt(" #n ")" ::: "memory")
; #define PG8_WAIT_L(n) asm volatile("s_waitcnt lgkmcnt(" #n ")" ::: "memory")
; #define PG8_BAR __builtin_amdgcn_s_barrier()
; #define PG8_SCHED __builtin_amdgcn_sched_barrier(0)
; template <class Epi, class Sched, bool ALIGN_EPI = false, bool SP2 = false>
; __device__ __forceinline__ void gemm_phase(PG8_LAS unsigned char* lds, const Gemm g, const Sched& S, const Epi& E) {
;     ...
;             PG8_LDA(At, 1, 1); PG8_STAGE(PG8_SB(1, 0), b3, voffB); PG8_STAGE(PG8_SB(1, 1), b3 + hstepB, voffB); PG8_STAGE(PG8_SA(1, 0), a3, voffA);
;             PG8_WAIT_V(8); PG8_WAIT_L(0); PG8_BAR; PG8_MMA(1, 0, At, B0); PG8_MMA(1, 1, At, B1); PG8_BAR; PG8_SCHED;
	s_add_i32 s40, s86, s33
	v_lshl_add_u64 v[8:9], v[226:227], 0, s[10:11]
	s_mov_b32 m0, s40
	ds_read_b128 v[194:197], v188 offset:49152
	ds_read_b128 v[198:201], v188 offset:50176
	ds_read_b128 v[202:205], v188 offset:51200
	ds_read_b128 v[206:209], v188 offset:52224
	ds_read_b128 v[210:213], v188 offset:53248
	ds_read_b128 v[214:217], v188 offset:54272
	ds_read_b128 v[218:221], v188 offset:55296
	ds_read_b128 v[222:225], v188 offset:56320
	global_load_lds_dwordx4 v[8:9], off
	s_add_i32 m0, s40, 0x2000
	s_add_u32 s36, s36, 0x100080
	v_lshl_add_u64 v[8:9], v[228:229], 0, s[10:11]
	s_addc_u32 s37, s37, 0
	s_add_i32 s40, s87, s33
	global_load_lds_dwordx4 v[8:9], off
	v_lshl_add_u64 v[8:9], s[36:37], 0, v[166:167]
	s_mov_b32 m0, s40
	s_nop 0
	global_load_lds_dwordx4 v[8:9], off
	v_lshl_add_u64 v[8:9], s[36:37], 0, v[170:171]
	s_add_i32 m0, s40, 0x2000
	s_nop 0
	global_load_lds_dwordx4 v[8:9], off
	v_lshl_add_u64 v[8:9], v[230:231], 0, s[10:11]
	s_mov_b32 m0, s60
	s_nop 0
	global_load_lds_dwordx4 v[8:9], off
	v_lshl_add_u64 v[8:9], v[232:233], 0, s[10:11]
	s_mov_b32 m0, s61
	s_nop 0
	global_load_lds_dwordx4 v[8:9], off
	s_waitcnt vmcnt(8)
	s_waitcnt lgkmcnt(0)
	s_barrier
	v_mfma_f32_16x16x32_bf16 v[66:69], v[134:137], v[194:197], v[66:69]
	v_mfma_f32_16x16x32_bf16 v[66:69], v[138:141], v[198:201], v[66:69]
	v_mfma_f32_16x16x32_bf16 v[62:65], v[142:145], v[194:197], v[62:65]
	v_mfma_f32_16x16x32_bf16 v[62:65], v[146:149], v[198:201], v[62:65]
	v_mfma_f32_16x16x32_bf16 v[46:49], v[142:145], v[202:205], v[46:49]
	v_mfma_f32_16x16x32_bf16 v[46:49], v[146:149], v[206:209], v[46:49]
	v_mfma_f32_16x16x32_bf16 v[50:53], v[134:137], v[202:205], v[50:53]
	v_mfma_f32_16x16x32_bf16 v[50:53], v[138:141], v[206:209], v[50:53]
	v_mfma_f32_16x16x32_bf16 v[34:37], v[134:137], v[210:213], v[34:37]
	v_mfma_f32_16x16x32_bf16 v[34:37], v[138:141], v[214:217], v[34:37]
	v_mfma_f32_16x16x32_bf16 v[30:33], v[142:145], v[210:213], v[30:33]
	v_mfma_f32_16x16x32_bf16 v[30:33], v[146:149], v[214:217], v[30:33]
	v_mfma_f32_16x16x32_bf16 v[14:17], v[142:145], v[218:221], v[14:17]
	v_mfma_f32_16x16x32_bf16 v[14:17], v[146:149], v[222:225], v[14:17]
	v_mfma_f32_16x16x32_bf16 v[18:21], v[134:137], v[218:221], v[18:21]
	v_mfma_f32_16x16x32_bf16 v[18:21], v[138:141], v[222:225], v[18:21]
	v_mfma_f32_16x16x32_bf16 v[58:61], v[150:153], v[194:197], v[58:61]
	v_mfma_f32_16x16x32_bf16 v[54:57], v[158:161], v[194:197], v[54:57]
	v_mfma_f32_16x16x32_bf16 v[42:45], v[150:153], v[202:205], v[42:45]
	v_mfma_f32_16x16x32_bf16 v[38:41], v[158:161], v[202:205], v[38:41]
	v_mfma_f32_16x16x32_bf16 v[26:29], v[150:153], v[210:213], v[26:29]
	v_mfma_f32_16x16x32_bf16 v[22:25], v[158:161], v[210:213], v[22:25]
	v_mfma_f32_16x16x32_bf16 v[8:11], v[150:153], v[218:221], v[10:13]
	v_mfma_f32_16x16x32_bf16 v[4:7], v[158:161], v[218:221], v[4:7]
	v_mfma_f32_16x16x32_bf16 v[58:61], v[154:157], v[198:201], v[58:61]
	v_mfma_f32_16x16x32_bf16 v[54:57], v[190:193], v[198:201], v[54:57]
	v_mfma_f32_16x16x32_bf16 v[42:45], v[154:157], v[206:209], v[42:45]
	v_mfma_f32_16x16x32_bf16 v[38:41], v[190:193], v[206:209], v[38:41]
	v_mfma_f32_16x16x32_bf16 v[26:29], v[154:157], v[214:217], v[26:29]
	v_mfma_f32_16x16x32_bf16 v[22:25], v[190:193], v[214:217], v[22:25]
	v_mfma_f32_16x16x32_bf16 v[10:13], v[154:157], v[222:225], v[8:11]
	v_mfma_f32_16x16x32_bf16 v[6:9], v[190:193], v[222:225], v[4:7]
	s_barrier
	s_add_i32 s85, s85, 2
	s_add_u32 s30, s30, 0x100
	s_addc_u32 s31, s31, 0
	s_cmp_gt_u32 s85, 61
	s_cbranch_scc1 .LBB0_811

; #define PG8_STAGE(bufoff, gbase, voff) do { _Pragma("unroll") for (int _i = 0; _i < 2; ++_i) \
;         __builtin_amdgcn_global_load_lds((const unsigned*)((const char*)(gbase) + (voff)[_i]), (PG8_LAS unsigned*)(lds + (bufoff) + ldsw + _i * 8192), 16, 0, 0); } while (0)
; #define PG8_LDA(dst, b, h) do { _Pragma("unroll") for (int m = 0; m < 4; ++m) _Pragma("unroll") for (int k = 0; k < 2; ++k) dst[m][k] = *(const PG8_LAS bf16x8*)(lds + PG8_SA(b, h) + aoff + m * 2048 + k * 1024); } while (0)
; #define PG8_LDB(dst, b, h) do { _Pragma("unroll") for (int n = 0; n < 2; ++n) _Pragma("unroll") for (int k = 0; k < 2; ++k) dst[n][k] = *(const PG8_LAS bf16x8*)(lds + PG8_SB(b, h) + boff + n * 2048 + k * 1024); } while (0)
; #define PG8_MMA(ai, bj, At, Bt) do { __builtin_amdgcn_s_setprio(3); _Pragma("unroll") for (int m = 0; m < 4; ++m) _Pragma("unroll") for (int n = 0; n < 2; ++n) _Pragma("unroll") for (int k = 0; k < 2; ++k) \
;         acc[ai][bj][m][n] = __builtin_amdgcn_mfma_f32_16x16x32_bf16(Bt[n][k], At[m][k], acc[ai][bj][m][n], 0, 0, 0); __builtin_amdgcn_s_setprio(0); } while (0)
; #define PG8_WAIT_V(n) asm volatile("s_waitcnt vmcnt(" #n ")" ::: "memory")
; #define PG8_WAIT_L(n) asm volatile("s_waitcnt lgkmcnt(" #n ")" ::: "memory")
; #define PG8_BAR __builtin_amdgcn_s_barrier()
; template <class Epi, class Sched, bool ALIGN_EPI = false, bool SP2 = false>
; __device__ __forceinline__ void gemm_phase(PG8_LAS unsigned char* lds, const Gemm g, const Sched& S, const Epi& E) {
;     ...
;             const bool last = (t == nt - 2);
;             const char* a1 = cA + (size_t)(t + 1) * kstep;
;             const char* a2 = last ? nA : cA + (size_t)(t + 2) * kstep; const char* b2 = last ? nB : cB + (size_t)(t + 2) * kstep;
;             const char* a3 = a2 + kstep; const char* b3 = b2 + kstep;
;             if (last && has_next) S.a_ready(nxt);
;             if constexpr (Epi::MIDK) { if (t == E.midk_step(nt)) E.midk(acc, cur, wr, wc, fr, fq); }
;             if constexpr (SP2) {
;             PG8_LDB(B0, 0, 0); PG8_LDB(B1, 0, 1); PG8_SCHED; PG8_LDA(At, 0, 0); PG8_STAGE(PG8_SA(1, 1), a1 + hstepA, voffA);
;             PG8_WAIT_V(8); PG8_WAIT_L(0); PG8_BAR; PG8_MMA(0, 0, At, B0); PG8_MMA(0, 1, At, B1); PG8_BAR; PG8_SCHED;
;             PG8_LDA(At, 0, 1); PG8_STAGE(PG8_SB(0, 0), b2, voffB); PG8_STAGE(PG8_SB(0, 1), b2 + hstepB, voffB); PG8_STAGE(PG8_SA(0, 0), a2, voffA);
.LBB0_908:
	ds_read_b128 v[158:161], v155
	ds_read_b128 v[164:167], v155 offset:1024
	ds_read_b128 v[168:171], v155 offset:2048
	ds_read_b128 v[172:175], v155 offset:3072
	ds_read_b128 v[176:179], v156
	ds_read_b128 v[180:183], v156 offset:1024
	ds_read_b128 v[184:187], v156 offset:2048
	ds_read_b128 v[188:191], v156 offset:3072
	s_add_u32 s26, s24, 0xfff00080
	s_addc_u32 s27, s25, -1
	s_cmp_eq_u32 s55, 60
	s_cselect_b32 s29, s17, s27
	s_cselect_b32 s28, s47, s26
	s_cselect_b32 s27, s15, s54
	s_cselect_b32 s26, s52, s53
	v_lshl_add_u64 v[146:147], s[24:25], 0, v[138:139]
	s_add_i32 m0, s23, 0xc000
	ds_read_b128 v[192:195], v157
	ds_read_b128 v[196:199], v157 offset:1024
	ds_read_b128 v[200:203], v157 offset:2048
	ds_read_b128 v[204:207], v157 offset:3072
	ds_read_b128 v[208:211], v157 offset:4096
	ds_read_b128 v[212:215], v157 offset:5120
	ds_read_b128 v[216:219], v157 offset:6144
	ds_read_b128 v[220:223], v157 offset:7168
	global_load_lds_dwordx4 v[146:147], off
	v_lshl_add_u64 v[146:147], s[24:25], 0, v[140:141]
	s_add_i32 m0, s23, 0xe000
	s_nop 0
	global_load_lds_dwordx4 v[146:147], off
	s_waitcnt vmcnt(8)
	s_waitcnt lgkmcnt(0)
	s_barrier
	v_mfma_f32_16x16x32_bf16 v[126:129], v[158:161], v[192:195], v[126:129]
	v_mfma_f32_16x16x32_bf16 v[126:129], v[164:167], v[196:199], v[126:129]
	v_mfma_f32_16x16x32_bf16 v[122:125], v[168:171], v[192:195], v[122:125]
	v_mfma_f32_16x16x32_bf16 v[122:125], v[172:175], v[196:199], v[122:125]
	v_mfma_f32_16x16x32_bf16 v[106:109], v[168:171], v[200:203], v[106:109]
	v_mfma_f32_16x16x32_bf16 v[106:109], v[172:175], v[204:207], v[106:109]
	v_mfma_f32_16x16x32_bf16 v[114:117], v[158:161], v[200:203], v[114:117]
	v_mfma_f32_16x16x32_bf16 v[114:117], v[164:167], v[204:207], v[114:117]
	v_mfma_f32_16x16x32_bf16 v[98:101], v[158:161], v[208:211], v[98:101]
	v_mfma_f32_16x16x32_bf16 v[98:101], v[164:167], v[212:215], v[98:101]
	v_mfma_f32_16x16x32_bf16 v[90:93], v[168:171], v[208:211], v[90:93]
	v_mfma_f32_16x16x32_bf16 v[90:93], v[172:175], v[212:215], v[90:93]
	v_mfma_f32_16x16x32_bf16 v[74:77], v[168:171], v[216:219], v[74:77]
	v_mfma_f32_16x16x32_bf16 v[74:77], v[172:175], v[220:223], v[74:77]
	v_mfma_f32_16x16x32_bf16 v[82:85], v[158:161], v[216:219], v[82:85]
	v_mfma_f32_16x16x32_bf16 v[82:85], v[164:167], v[220:223], v[82:85]
	v_mfma_f32_16x16x32_bf16 v[118:121], v[176:179], v[192:195], v[118:121]
	v_mfma_f32_16x16x32_bf16 v[118:121], v[180:183], v[196:199], v[118:121]
	v_mfma_f32_16x16x32_bf16 v[110:113], v[184:187], v[192:195], v[110:113]
	v_mfma_f32_16x16x32_bf16 v[110:113], v[188:191], v[196:199], v[110:113]
	v_mfma_f32_16x16x32_bf16 v[94:97], v[184:187], v[200:203], v[94:97]
	v_mfma_f32_16x16x32_bf16 v[94:97], v[188:191], v[204:207], v[94:97]
	v_mfma_f32_16x16x32_bf16 v[102:105], v[176:179], v[200:203], v[102:105]
	v_mfma_f32_16x16x32_bf16 v[102:105], v[180:183], v[204:207], v[102:105]
	v_mfma_f32_16x16x32_bf16 v[86:89], v[176:179], v[208:211], v[86:89]
	v_mfma_f32_16x16x32_bf16 v[86:89], v[180:183], v[212:215], v[86:89]
	v_mfma_f32_16x16x32_bf16 v[78:81], v[184:187], v[208:211], v[78:81]
	v_mfma_f32_16x16x32_bf16 v[78:81], v[188:191], v[212:215], v[78:81]
	v_mfma_f32_16x16x32_bf16 v[66:69], v[184:187], v[216:219], v[66:69]
	v_mfma_f32_16x16x32_bf16 v[66:69], v[188:191], v[220:223], v[66:69]
	v_mfma_f32_16x16x32_bf16 v[70:73], v[176:179], v[216:219], v[70:73]
	v_mfma_f32_16x16x32_bf16 v[70:73], v[180:183], v[220:223], v[70:73]
	s_barrier
	s_add_i32 s56, s42, s30
	v_lshl_add_u64 v[146:147], s[26:27], 0, v[134:135]
	s_mov_b32 m0, s56
	ds_read_b128 v[192:195], v157 offset:16384
	ds_read_b128 v[196:199], v157 offset:17408
	ds_read_b128 v[200:203], v157 offset:18432
	ds_read_b128 v[204:207], v157 offset:19456
	ds_read_b128 v[208:211], v157 offset:20480
	ds_read_b128 v[212:215], v157 offset:21504
	ds_read_b128 v[216:219], v157 offset:22528
	ds_read_b128 v[220:223], v157 offset:23552
	global_load_lds_dwordx4 v[146:147], off
	s_add_i32 m0, s56, 0x2000
	s_add_u32 s56, s26, 0x100000
	v_lshl_add_u64 v[224:225], s[26:27], 0, v[130:131]
	s_addc_u32 s57, s27, 0
	s_add_i32 s58, s43, s30
	global_load_lds_dwordx4 v[224:225], off
	v_lshl_add_u64 v[226:227], s[56:57], 0, v[134:135]
	s_mov_b32 m0, s58
	v_lshl_add_u64 v[228:229], s[28:29], 0, v[132:133]
	global_load_lds_dwordx4 v[226:227], off
	v_lshl_add_u64 v[226:227], s[56:57], 0, v[130:131]
	s_add_i32 m0, s58, 0x2000
	s_nop 0
	global_load_lds_dwordx4 v[226:227], off
	v_lshl_add_u64 v[226:227], s[28:29], 0, v[136:137]
	s_mov_b32 m0, s23
	s_nop 0
	global_load_lds_dwordx4 v[226:227], off
	s_mov_b32 m0, s33
	s_nop 0
	global_load_lds_dwordx4 v[228:229], off
	s_waitcnt vmcnt(8)
	s_waitcnt lgkmcnt(0)
	s_barrier
; #define PG8_STAGE(bufoff, gbase, voff) do { _Pragma("unroll") for (int _i = 0; _i < 2; ++_i) \
;         __builtin_amdgcn_global_load_lds((const unsigned*)((const char*)(gbase) + (voff)[_i]), (PG8_LAS unsigned*)(lds + (bufoff) + ldsw + _i * 8192), 16, 0, 0); } while (0)
; #define PG8_LDA(dst, b, h) do { _Pragma("unroll") for (int m = 0; m < 4; ++m) _Pragma("unroll") for (int k = 0; k < 2; ++k) dst[m][k] = *(const PG8_LAS bf16x8*)(lds + PG8_SA(b, h) + aoff + m * 2048 + k * 1024); } while (0)
; #define PG8_LDB(dst, b, h) do { _Pragma("unroll") for (int n = 0; n < 2; ++n) _Pragma("unroll") for (int k = 0; k < 2; ++k) dst[n][k] = *(const PG8_LAS bf16x8*)(lds + PG8_SB(b, h) + boff + n * 2048 + k * 1024); } while (0)
; #define PG8_MMA(ai, bj, At, Bt) do { __builtin_amdgcn_s_setprio(3); _Pragma("unroll") for (int m = 0; m < 4; ++m) _Pragma("unroll") for (int n = 0; n < 2; ++n) _Pragma("unroll") for (int k = 0; k < 2; ++k) \
;         acc[ai][bj][m][n] = __builtin_amdgcn_mfma_f32_16x16x32_bf16(Bt[n][k], At[m][k], acc[ai][bj][m][n], 0, 0, 0); __builtin_amdgcn_s_setprio(0); } while (0)
; #define PG8_WAIT_V(n) asm volatile("s_waitcnt vmcnt(" #n ")" ::: "memory")
; #define PG8_WAIT_L(n) asm volatile("s_waitcnt lgkmcnt(" #n ")" ::: "memory")
; #define PG8_BAR __builtin_amdgcn_s_barrier()
; #define PG8_SCHED __builtin_amdgcn_sched_barrier(0)
; template <class Epi, class Sched, bool ALIGN_EPI = false, bool SP2 = false>
; __device__ __forceinline__ void gemm_phase(PG8_LAS unsigned char* lds, const Gemm g, const Sched& S, const Epi& E) {
;     ...
;             PG8_WAIT_V(8); PG8_WAIT_L(0); PG8_BAR; PG8_MMA(1, 0, At, B0); PG8_MMA(1, 1, At, B1); PG8_BAR; PG8_SCHED;
;             PG8_LDB(B0, 1, 0); PG8_LDB(B1, 1, 1); PG8_SCHED; PG8_LDA(At, 1, 0); PG8_STAGE(PG8_SA(0, 1), a2 + hstepA, voffA);
;             PG8_WAIT_V(8); PG8_WAIT_L(0); PG8_BAR; PG8_MMA(0, 0, At, B0); PG8_MMA(0, 1, At, B1); PG8_BAR; PG8_SCHED;
	v_mfma_f32_16x16x32_bf16 v[62:65], v[158:161], v[192:195], v[62:65]
	v_mfma_f32_16x16x32_bf16 v[62:65], v[164:167], v[196:199], v[62:65]
	v_mfma_f32_16x16x32_bf16 v[58:61], v[168:171], v[192:195], v[58:61]
	v_mfma_f32_16x16x32_bf16 v[58:61], v[172:175], v[196:199], v[58:61]
	v_mfma_f32_16x16x32_bf16 v[42:45], v[168:171], v[200:203], v[42:45]
	v_mfma_f32_16x16x32_bf16 v[42:45], v[172:175], v[204:207], v[42:45]
	v_mfma_f32_16x16x32_bf16 v[50:53], v[158:161], v[200:203], v[50:53]
	v_mfma_f32_16x16x32_bf16 v[50:53], v[164:167], v[204:207], v[50:53]
	v_mfma_f32_16x16x32_bf16 v[34:37], v[158:161], v[208:211], v[34:37]
	v_mfma_f32_16x16x32_bf16 v[34:37], v[164:167], v[212:215], v[34:37]
	v_mfma_f32_16x16x32_bf16 v[26:29], v[168:171], v[208:211], v[26:29]
	v_mfma_f32_16x16x32_bf16 v[26:29], v[172:175], v[212:215], v[26:29]
	v_mfma_f32_16x16x32_bf16 v[10:13], v[168:171], v[216:219], v[10:13]
	v_mfma_f32_16x16x32_bf16 v[10:13], v[172:175], v[220:223], v[10:13]
	v_mfma_f32_16x16x32_bf16 v[14:17], v[158:161], v[216:219], v[14:17]
	v_mfma_f32_16x16x32_bf16 v[14:17], v[164:167], v[220:223], v[14:17]
	v_mfma_f32_16x16x32_bf16 v[54:57], v[176:179], v[192:195], v[54:57]
	v_mfma_f32_16x16x32_bf16 v[54:57], v[180:183], v[196:199], v[54:57]
	v_mfma_f32_16x16x32_bf16 v[46:49], v[184:187], v[192:195], v[46:49]
	v_mfma_f32_16x16x32_bf16 v[46:49], v[188:191], v[196:199], v[46:49]
	v_mfma_f32_16x16x32_bf16 v[30:33], v[184:187], v[200:203], v[30:33]
	v_mfma_f32_16x16x32_bf16 v[30:33], v[188:191], v[204:207], v[30:33]
	v_mfma_f32_16x16x32_bf16 v[38:41], v[176:179], v[200:203], v[38:41]
	v_mfma_f32_16x16x32_bf16 v[38:41], v[180:183], v[204:207], v[38:41]
	v_mfma_f32_16x16x32_bf16 v[22:25], v[176:179], v[208:211], v[22:25]
	v_mfma_f32_16x16x32_bf16 v[22:25], v[180:183], v[212:215], v[22:25]
	v_mfma_f32_16x16x32_bf16 v[18:21], v[184:187], v[208:211], v[18:21]
	v_mfma_f32_16x16x32_bf16 v[18:21], v[188:191], v[212:215], v[18:21]
	v_mfma_f32_16x16x32_bf16 v[2:5], v[184:187], v[216:219], v[2:5]
	v_mfma_f32_16x16x32_bf16 v[2:5], v[188:191], v[220:223], v[2:5]
	v_mfma_f32_16x16x32_bf16 v[6:9], v[176:179], v[216:219], v[6:9]
	v_mfma_f32_16x16x32_bf16 v[6:9], v[180:183], v[220:223], v[6:9]
	s_barrier
	s_add_i32 s56, 0, 0x18000
	v_add_u32_e32 v148, s56, v151
	s_add_i32 s57, 0, 0x1c000
	ds_read_b128 v[158:161], v148
	ds_read_b128 v[164:167], v148 offset:1024
	ds_read_b128 v[168:171], v148 offset:2048
	ds_read_b128 v[172:175], v148 offset:3072
	v_add_u32_e32 v148, s57, v151
	ds_read_b128 v[176:179], v148
	ds_read_b128 v[180:183], v148 offset:1024
	ds_read_b128 v[184:187], v148 offset:2048
	ds_read_b128 v[188:191], v148 offset:3072
	s_add_u32 s28, s28, 0x100000
	s_addc_u32 s29, s29, 0
	s_mov_b32 m0, s36
	v_lshl_add_u64 v[230:231], s[28:29], 0, v[136:137]
	ds_read_b128 v[192:195], v157 offset:32768
	ds_read_b128 v[196:199], v157 offset:33792
	ds_read_b128 v[200:203], v157 offset:34816
	ds_read_b128 v[204:207], v157 offset:35840
	ds_read_b128 v[208:211], v157 offset:36864
	ds_read_b128 v[212:215], v157 offset:37888
	ds_read_b128 v[216:219], v157 offset:38912
	ds_read_b128 v[220:223], v157 offset:39936
	global_load_lds_dwordx4 v[230:231], off
	v_lshl_add_u64 v[230:231], s[28:29], 0, v[132:133]
	s_mov_b32 m0, s37
	s_nop 0
	global_load_lds_dwordx4 v[230:231], off
	s_waitcnt vmcnt(8)
	s_waitcnt lgkmcnt(0)
	s_barrier
	v_mfma_f32_16x16x32_bf16 v[126:129], v[158:161], v[192:195], v[126:129]
	v_mfma_f32_16x16x32_bf16 v[126:129], v[164:167], v[196:199], v[126:129]
	v_mfma_f32_16x16x32_bf16 v[122:125], v[168:171], v[192:195], v[122:125]
	v_mfma_f32_16x16x32_bf16 v[122:125], v[172:175], v[196:199], v[122:125]
	v_mfma_f32_16x16x32_bf16 v[106:109], v[168:171], v[200:203], v[106:109]
	v_mfma_f32_16x16x32_bf16 v[106:109], v[172:175], v[204:207], v[106:109]
	v_mfma_f32_16x16x32_bf16 v[114:117], v[158:161], v[200:203], v[114:117]
	v_mfma_f32_16x16x32_bf16 v[114:117], v[164:167], v[204:207], v[114:117]
	v_mfma_f32_16x16x32_bf16 v[98:101], v[158:161], v[208:211], v[98:101]
	v_mfma_f32_16x16x32_bf16 v[98:101], v[164:167], v[212:215], v[98:101]
	v_mfma_f32_16x16x32_bf16 v[90:93], v[168:171], v[208:211], v[90:93]
	v_mfma_f32_16x16x32_bf16 v[90:93], v[172:175], v[212:215], v[90:93]
	v_mfma_f32_16x16x32_bf16 v[74:77], v[168:171], v[216:219], v[74:77]
	v_mfma_f32_16x16x32_bf16 v[74:77], v[172:175], v[220:223], v[74:77]
	v_mfma_f32_16x16x32_bf16 v[82:85], v[158:161], v[216:219], v[82:85]
	v_mfma_f32_16x16x32_bf16 v[82:85], v[164:167], v[220:223], v[82:85]
	v_mfma_f32_16x16x32_bf16 v[118:121], v[176:179], v[192:195], v[118:121]
	v_mfma_f32_16x16x32_bf16 v[118:121], v[180:183], v[196:199], v[118:121]
	v_mfma_f32_16x16x32_bf16 v[110:113], v[184:187], v[192:195], v[110:113]
	v_mfma_f32_16x16x32_bf16 v[110:113], v[188:191], v[196:199], v[110:113]
	v_mfma_f32_16x16x32_bf16 v[94:97], v[184:187], v[200:203], v[94:97]
	v_mfma_f32_16x16x32_bf16 v[94:97], v[188:191], v[204:207], v[94:97]
	v_mfma_f32_16x16x32_bf16 v[102:105], v[176:179], v[200:203], v[102:105]
	v_mfma_f32_16x16x32_bf16 v[102:105], v[180:183], v[204:207], v[102:105]
	v_mfma_f32_16x16x32_bf16 v[86:89], v[176:179], v[208:211], v[86:89]
	v_mfma_f32_16x16x32_bf16 v[86:89], v[180:183], v[212:215], v[86:89]
	v_mfma_f32_16x16x32_bf16 v[78:81], v[184:187], v[208:211], v[78:81]
	v_mfma_f32_16x16x32_bf16 v[78:81], v[188:191], v[212:215], v[78:81]
	v_mfma_f32_16x16x32_bf16 v[66:69], v[184:187], v[216:219], v[66:69]
	v_mfma_f32_16x16x32_bf16 v[66:69], v[188:191], v[220:223], v[66:69]
	v_mfma_f32_16x16x32_bf16 v[70:73], v[176:179], v[216:219], v[70:73]
	v_mfma_f32_16x16x32_bf16 v[70:73], v[180:183], v[220:223], v[70:73]
	s_barrier
; #define PG8_STAGE(bufoff, gbase, voff) do { _Pragma("unroll") for (int _i = 0; _i < 2; ++_i) \
;         __builtin_amdgcn_global_load_lds((const unsigned*)((const char*)(gbase) + (voff)[_i]), (PG8_LAS unsigned*)(lds + (bufoff) + ldsw + _i * 8192), 16, 0, 0); } while (0)
; #define PG8_LDA(dst, b, h) do { _Pragma("unroll") for (int m = 0; m < 4; ++m) _Pragma("unroll") for (int k = 0; k < 2; ++k) dst[m][k] = *(const PG8_LAS bf16x8*)(lds + PG8_SA(b, h) + aoff + m * 2048 + k * 1024); } while (0)
; #define PG8_MMA(ai, bj, At, Bt) do { __builtin_amdgcn_s_setprio(3); _Pragma("unroll") for (int m = 0; m < 4; ++m) _Pragma("unroll") for (int n = 0; n < 2; ++n) _Pragma("unroll") for (int k = 0; k < 2; ++k) \
;         acc[ai][bj][m][n] = __builtin_amdgcn_mfma_f32_16x16x32_bf16(Bt[n][k], At[m][k], acc[ai][bj][m][n], 0, 0, 0); __builtin_amdgcn_s_setprio(0); } while (0)
; #define PG8_WAIT_V(n) asm volatile("s_waitcnt vmcnt(" #n ")" ::: "memory")
; #define PG8_WAIT_L(n) asm volatile("s_waitcnt lgkmcnt(" #n ")" ::: "memory")
; #define PG8_BAR __builtin_amdgcn_s_barrier()
; #define PG8_SCHED __builtin_amdgcn_sched_barrier(0)
; template <class Epi, class Sched, bool ALIGN_EPI = false, bool SP2 = false>
; __device__ __forceinline__ void gemm_phase(PG8_LAS unsigned char* lds, const Gemm g, const Sched& S, const Epi& E) {
;     ...
;             PG8_LDA(At, 1, 1); PG8_STAGE(PG8_SB(1, 0), b3, voffB); PG8_STAGE(PG8_SB(1, 1), b3 + hstepB, voffB); PG8_STAGE(PG8_SA(1, 0), a3, voffA);
;             PG8_WAIT_V(8); PG8_WAIT_L(0); PG8_BAR; PG8_MMA(1, 0, At, B0); PG8_MMA(1, 1, At, B1); PG8_BAR; PG8_SCHED;
	s_add_i32 s28, s56, s30
	v_lshl_add_u64 v[146:147], v[146:147], 0, s[12:13]
	s_mov_b32 m0, s28
	ds_read_b128 v[192:195], v157 offset:49152
	ds_read_b128 v[196:199], v157 offset:50176
	ds_read_b128 v[200:203], v157 offset:51200
	ds_read_b128 v[204:207], v157 offset:52224
	ds_read_b128 v[208:211], v157 offset:53248
	ds_read_b128 v[212:215], v157 offset:54272
	ds_read_b128 v[216:219], v157 offset:55296
	ds_read_b128 v[220:223], v157 offset:56320
	global_load_lds_dwordx4 v[146:147], off
	s_add_i32 m0, s28, 0x2000
	s_add_u32 s26, s26, 0x100080
	v_lshl_add_u64 v[146:147], v[224:225], 0, s[12:13]
	s_addc_u32 s27, s27, 0
	s_add_i32 s28, s57, s30
	global_load_lds_dwordx4 v[146:147], off
	v_lshl_add_u64 v[146:147], s[26:27], 0, v[134:135]
	s_mov_b32 m0, s28
	s_nop 0
	global_load_lds_dwordx4 v[146:147], off
	v_lshl_add_u64 v[146:147], s[26:27], 0, v[130:131]
	s_add_i32 m0, s28, 0x2000
	s_nop 0
	global_load_lds_dwordx4 v[146:147], off
	v_lshl_add_u64 v[146:147], v[226:227], 0, s[12:13]
	s_mov_b32 m0, s39
	s_nop 0
	global_load_lds_dwordx4 v[146:147], off
	v_lshl_add_u64 v[146:147], v[228:229], 0, s[12:13]
	s_mov_b32 m0, s40
	s_nop 0
	global_load_lds_dwordx4 v[146:147], off
	s_waitcnt vmcnt(8)
	s_waitcnt lgkmcnt(0)
	s_barrier
	v_mfma_f32_16x16x32_bf16 v[62:65], v[158:161], v[192:195], v[62:65]
	v_mfma_f32_16x16x32_bf16 v[62:65], v[164:167], v[196:199], v[62:65]
	v_mfma_f32_16x16x32_bf16 v[58:61], v[168:171], v[192:195], v[58:61]
	v_mfma_f32_16x16x32_bf16 v[58:61], v[172:175], v[196:199], v[58:61]
	v_mfma_f32_16x16x32_bf16 v[42:45], v[168:171], v[200:203], v[42:45]
	v_mfma_f32_16x16x32_bf16 v[42:45], v[172:175], v[204:207], v[42:45]
	v_mfma_f32_16x16x32_bf16 v[50:53], v[158:161], v[200:203], v[50:53]
	v_mfma_f32_16x16x32_bf16 v[50:53], v[164:167], v[204:207], v[50:53]
	v_mfma_f32_16x16x32_bf16 v[34:37], v[158:161], v[208:211], v[34:37]
	v_mfma_f32_16x16x32_bf16 v[34:37], v[164:167], v[212:215], v[34:37]
	v_mfma_f32_16x16x32_bf16 v[26:29], v[168:171], v[208:211], v[26:29]
	v_mfma_f32_16x16x32_bf16 v[26:29], v[172:175], v[212:215], v[26:29]
	v_mfma_f32_16x16x32_bf16 v[10:13], v[168:171], v[216:219], v[10:13]
	v_mfma_f32_16x16x32_bf16 v[10:13], v[172:175], v[220:223], v[10:13]
	v_mfma_f32_16x16x32_bf16 v[14:17], v[158:161], v[216:219], v[14:17]
	v_mfma_f32_16x16x32_bf16 v[14:17], v[164:167], v[220:223], v[14:17]
	v_mfma_f32_16x16x32_bf16 v[54:57], v[176:179], v[192:195], v[54:57]
	v_mfma_f32_16x16x32_bf16 v[54:57], v[180:183], v[196:199], v[54:57]
	v_mfma_f32_16x16x32_bf16 v[46:49], v[184:187], v[192:195], v[46:49]
	v_mfma_f32_16x16x32_bf16 v[46:49], v[188:191], v[196:199], v[46:49]
	v_mfma_f32_16x16x32_bf16 v[30:33], v[184:187], v[200:203], v[30:33]
	v_mfma_f32_16x16x32_bf16 v[30:33], v[188:191], v[204:207], v[30:33]
	v_mfma_f32_16x16x32_bf16 v[38:41], v[176:179], v[200:203], v[38:41]
	v_mfma_f32_16x16x32_bf16 v[38:41], v[180:183], v[204:207], v[38:41]
	v_mfma_f32_16x16x32_bf16 v[22:25], v[176:179], v[208:211], v[22:25]
	v_mfma_f32_16x16x32_bf16 v[22:25], v[180:183], v[212:215], v[22:25]
	v_mfma_f32_16x16x32_bf16 v[18:21], v[184:187], v[208:211], v[18:21]
	v_mfma_f32_16x16x32_bf16 v[18:21], v[188:191], v[212:215], v[18:21]
	v_mfma_f32_16x16x32_bf16 v[2:5], v[184:187], v[216:219], v[2:5]
	v_mfma_f32_16x16x32_bf16 v[2:5], v[188:191], v[220:223], v[2:5]
	v_mfma_f32_16x16x32_bf16 v[6:9], v[176:179], v[216:219], v[6:9]
	v_mfma_f32_16x16x32_bf16 v[6:9], v[180:183], v[220:223], v[6:9]
	s_barrier
	s_add_i32 s55, s55, 2
	s_add_u32 s24, s24, 0x100
	s_addc_u32 s25, s25, 0
	s_add_u32 s53, s53, 0x100
	s_addc_u32 s54, s54, 0
	s_cmp_gt_u32 s55, 61
	s_cbranch_scc0 .LBB0_908
	s_and_b64 vcc, exec, s[0:1]
	s_cbranch_vccz .LBB0_911
	s_barrier

; #define PG8_STAGE(bufoff, gbase, voff) do { _Pragma("unroll") for (int _i = 0; _i < 2; ++_i) \
;         __builtin_amdgcn_global_load_lds((const unsigned*)((const char*)(gbase) + (voff)[_i]), (PG8_LAS unsigned*)(lds + (bufoff) + ldsw + _i * 8192), 16, 0, 0); } while (0)
; #define PG8_LDA(dst, b, h) do { _Pragma("unroll") for (int m = 0; m < 4; ++m) _Pragma("unroll") for (int k = 0; k < 2; ++k) dst[m][k] = *(const PG8_LAS bf16x8*)(lds + PG8_SA(b, h) + aoff + m * 2048 + k * 1024); } while (0)
; #define PG8_LDB(dst, b, h) do { _Pragma("unroll") for (int n = 0; n < 2; ++n) _Pragma("unroll") for (int k = 0; k < 2; ++k) dst[n][k] = *(const PG8_LAS bf16x8*)(lds + PG8_SB(b, h) + boff + n * 2048 + k * 1024); } while (0)
; #define PG8_MMA(ai, bj, At, Bt) do { __builtin_amdgcn_s_setprio(3); _Pragma("unroll") for (int m = 0; m < 4; ++m) _Pragma("unroll") for (int n = 0; n < 2; ++n) _Pragma("unroll") for (int k = 0; k < 2; ++k) \
;         acc[ai][bj][m][n] = __builtin_amdgcn_mfma_f32_16x16x32_bf16(Bt[n][k], At[m][k], acc[ai][bj][m][n], 0, 0, 0); __builtin_amdgcn_s_setprio(0); } while (0)
; #define PG8_WAIT_V(n) asm volatile("s_waitcnt vmcnt(" #n ")" ::: "memory")
; #define PG8_WAIT_L(n) asm volatile("s_waitcnt lgkmcnt(" #n ")" ::: "memory")
; #define PG8_BAR __builtin_amdgcn_s_barrier()
; template <class Epi, class Sched, bool ALIGN_EPI = false, bool SP2 = false>
; __device__ __forceinline__ void gemm_phase(PG8_LAS unsigned char* lds, const Gemm g, const Sched& S, const Epi& E) {
;     ...
;             const bool last = (t == nt - 2);
;             const char* a1 = cA + (size_t)(t + 1) * kstep;
;             const char* a2 = last ? nA : cA + (size_t)(t + 2) * kstep; const char* b2 = last ? nB : cB + (size_t)(t + 2) * kstep;
;             const char* a3 = a2 + kstep; const char* b3 = b2 + kstep;
;             if (last && has_next) S.a_ready(nxt);
;             if constexpr (Epi::MIDK) { if (t == E.midk_step(nt)) E.midk(acc, cur, wr, wc, fr, fq); }
;             if constexpr (SP2) {
;             PG8_LDB(B0, 0, 0); PG8_LDB(B1, 0, 1); PG8_SCHED; PG8_LDA(At, 0, 0); PG8_STAGE(PG8_SA(1, 1), a1 + hstepA, voffA);
;             PG8_WAIT_V(8); PG8_WAIT_L(0); PG8_BAR; PG8_MMA(0, 0, At, B0); PG8_MMA(0, 1, At, B1); PG8_BAR; PG8_SCHED;
;             PG8_LDA(At, 0, 1); PG8_STAGE(PG8_SB(0, 0), b2, voffB); PG8_STAGE(PG8_SB(0, 1), b2 + hstepB, voffB); PG8_STAGE(PG8_SA(0, 0), a2, voffA);
.LBB0_975:
	v_add_u32_e32 v144, s46, v206
	v_add_u32_e32 v160, s47, v206
	s_add_u32 s28, s2, s12
	ds_read_b128 v[132:135], v144
	ds_read_b128 v[136:139], v144 offset:1024
	ds_read_b128 v[140:143], v144 offset:2048
	ds_read_b128 v[144:147], v144 offset:3072
	ds_read_b128 v[148:151], v160
	ds_read_b128 v[152:155], v160 offset:1024
	ds_read_b128 v[156:159], v160 offset:2048
	ds_read_b128 v[160:163], v160 offset:3072
	s_addc_u32 s29, s3, s13
	s_add_u32 s28, s28, 0x21500100
	s_addc_u32 s29, s29, 0
	s_add_u32 s81, s44, s12
	s_addc_u32 s82, s45, s13
	s_cmpk_eq_i32 s12, 0x5500
	s_cselect_b32 s31, s1, s29
	s_cselect_b32 s30, s0, s28
	s_cselect_b32 s29, s11, s82
	s_cselect_b32 s28, s10, s81
	s_mov_b32 m0, s71
	v_lshl_add_u64 v[234:235], v[2:3], 0, s[12:13]
	ds_read_b128 v[164:167], v207
	ds_read_b128 v[168:171], v207 offset:1024
	ds_read_b128 v[210:213], v207 offset:2048
	ds_read_b128 v[214:217], v207 offset:3072
	ds_read_b128 v[218:221], v207 offset:4096
	ds_read_b128 v[222:225], v207 offset:5120
	ds_read_b128 v[226:229], v207 offset:6144
	ds_read_b128 v[230:233], v207 offset:7168
	global_load_lds_dwordx4 v[234:235], off
	v_lshl_add_u64 v[234:235], v[200:201], 0, s[12:13]
	s_mov_b32 m0, s72
	s_nop 0
	global_load_lds_dwordx4 v[234:235], off
	s_waitcnt vmcnt(8)
	s_waitcnt lgkmcnt(0)
	s_barrier
	v_mfma_f32_16x16x32_bf16 v[128:131], v[132:135], v[164:167], v[128:131]
	v_mfma_f32_16x16x32_bf16 v[128:131], v[136:139], v[168:171], v[128:131]
	v_mfma_f32_16x16x32_bf16 v[124:127], v[140:143], v[164:167], v[124:127]
	v_mfma_f32_16x16x32_bf16 v[124:127], v[144:147], v[168:171], v[124:127]
	v_mfma_f32_16x16x32_bf16 v[96:99], v[140:143], v[210:213], v[96:99]
	v_mfma_f32_16x16x32_bf16 v[96:99], v[144:147], v[214:217], v[96:99]
	v_mfma_f32_16x16x32_bf16 v[100:103], v[132:135], v[210:213], v[100:103]
	v_mfma_f32_16x16x32_bf16 v[100:103], v[136:139], v[214:217], v[100:103]
	v_mfma_f32_16x16x32_bf16 v[112:115], v[132:135], v[218:221], v[112:115]
	v_mfma_f32_16x16x32_bf16 v[112:115], v[136:139], v[222:225], v[112:115]
	v_mfma_f32_16x16x32_bf16 v[108:111], v[140:143], v[218:221], v[108:111]
	v_mfma_f32_16x16x32_bf16 v[108:111], v[144:147], v[222:225], v[108:111]
	v_mfma_f32_16x16x32_bf16 v[76:79], v[140:143], v[226:229], v[76:79]
	v_mfma_f32_16x16x32_bf16 v[76:79], v[144:147], v[230:233], v[76:79]
	v_mfma_f32_16x16x32_bf16 v[80:83], v[132:135], v[226:229], v[80:83]
	v_mfma_f32_16x16x32_bf16 v[80:83], v[136:139], v[230:233], v[80:83]
	v_mfma_f32_16x16x32_bf16 v[120:123], v[148:151], v[164:167], v[120:123]
	v_mfma_f32_16x16x32_bf16 v[120:123], v[152:155], v[168:171], v[120:123]
	v_mfma_f32_16x16x32_bf16 v[116:119], v[156:159], v[164:167], v[116:119]
	v_mfma_f32_16x16x32_bf16 v[116:119], v[160:163], v[168:171], v[116:119]
	v_mfma_f32_16x16x32_bf16 v[88:91], v[156:159], v[210:213], v[88:91]
	v_mfma_f32_16x16x32_bf16 v[88:91], v[160:163], v[214:217], v[88:91]
	v_mfma_f32_16x16x32_bf16 v[92:95], v[148:151], v[210:213], v[92:95]
	v_mfma_f32_16x16x32_bf16 v[92:95], v[152:155], v[214:217], v[92:95]
	v_mfma_f32_16x16x32_bf16 v[104:107], v[148:151], v[218:221], v[104:107]
	v_mfma_f32_16x16x32_bf16 v[104:107], v[152:155], v[222:225], v[104:107]
	v_mfma_f32_16x16x32_bf16 v[84:87], v[156:159], v[218:221], v[84:87]
	v_mfma_f32_16x16x32_bf16 v[84:87], v[160:163], v[222:225], v[84:87]
	v_mfma_f32_16x16x32_bf16 v[68:71], v[156:159], v[226:229], v[68:71]
	v_mfma_f32_16x16x32_bf16 v[68:71], v[160:163], v[230:233], v[68:71]
	v_mfma_f32_16x16x32_bf16 v[72:75], v[148:151], v[226:229], v[72:75]
	v_mfma_f32_16x16x32_bf16 v[72:75], v[152:155], v[230:233], v[72:75]
	s_barrier
	s_mov_b32 m0, s73
	v_lshl_add_u64 v[234:235], s[28:29], 0, v[174:175]
	s_add_u32 s82, s28, 0x2b0000
	ds_read_b128 v[164:167], v207 offset:16384
	ds_read_b128 v[168:171], v207 offset:17408
	ds_read_b128 v[210:213], v207 offset:18432
	ds_read_b128 v[214:217], v207 offset:19456
	ds_read_b128 v[218:221], v207 offset:20480
	ds_read_b128 v[222:225], v207 offset:21504
	ds_read_b128 v[226:229], v207 offset:22528
	ds_read_b128 v[230:233], v207 offset:23552
	global_load_lds_dwordx4 v[234:235], off
	v_lshl_add_u64 v[236:237], s[28:29], 0, v[178:179]
	s_mov_b32 m0, s74
	s_addc_u32 s83, s29, 0
	global_load_lds_dwordx4 v[236:237], off
	v_lshl_add_u64 v[238:239], s[82:83], 0, v[174:175]
	s_mov_b32 m0, s75
	v_lshl_add_u64 v[240:241], s[30:31], 0, v[176:177]
	global_load_lds_dwordx4 v[238:239], off
	v_lshl_add_u64 v[238:239], s[82:83], 0, v[178:179]
	s_mov_b32 m0, s76
	s_nop 0
	global_load_lds_dwordx4 v[238:239], off
	v_lshl_add_u64 v[238:239], s[30:31], 0, v[172:173]
	s_mov_b32 m0, s42
	s_nop 0
	global_load_lds_dwordx4 v[238:239], off
	s_mov_b32 m0, s54
	s_nop 0
	global_load_lds_dwordx4 v[240:241], off
	s_waitcnt vmcnt(8)
	s_waitcnt lgkmcnt(0)
	s_barrier
; #define PG8_STAGE(bufoff, gbase, voff) do { _Pragma("unroll") for (int _i = 0; _i < 2; ++_i) \
;         __builtin_amdgcn_global_load_lds((const unsigned*)((const char*)(gbase) + (voff)[_i]), (PG8_LAS unsigned*)(lds + (bufoff) + ldsw + _i * 8192), 16, 0, 0); } while (0)
; #define PG8_LDA(dst, b, h) do { _Pragma("unroll") for (int m = 0; m < 4; ++m) _Pragma("unroll") for (int k = 0; k < 2; ++k) dst[m][k] = *(const PG8_LAS bf16x8*)(lds + PG8_SA(b, h) + aoff + m * 2048 + k * 1024); } while (0)
; #define PG8_LDB(dst, b, h) do { _Pragma("unroll") for (int n = 0; n < 2; ++n) _Pragma("unroll") for (int k = 0; k < 2; ++k) dst[n][k] = *(const PG8_LAS bf16x8*)(lds + PG8_SB(b, h) + boff + n * 2048 + k * 1024); } while (0)
; #define PG8_MMA(ai, bj, At, Bt) do { __builtin_amdgcn_s_setprio(3); _Pragma("unroll") for (int m = 0; m < 4; ++m) _Pragma("unroll") for (int n = 0; n < 2; ++n) _Pragma("unroll") for (int k = 0; k < 2; ++k) \
;         acc[ai][bj][m][n] = __builtin_amdgcn_mfma_f32_16x16x32_bf16(Bt[n][k], At[m][k], acc[ai][bj][m][n], 0, 0, 0); __builtin_amdgcn_s_setprio(0); } while (0)
; #define PG8_WAIT_V(n) asm volatile("s_waitcnt vmcnt(" #n ")" ::: "memory")
; #define PG8_WAIT_L(n) asm volatile("s_waitcnt lgkmcnt(" #n ")" ::: "memory")
; #define PG8_BAR __builtin_amdgcn_s_barrier()
; #define PG8_SCHED __builtin_amdgcn_sched_barrier(0)
; template <class Epi, class Sched, bool ALIGN_EPI = false, bool SP2 = false>
; __device__ __forceinline__ void gemm_phase(PG8_LAS unsigned char* lds, const Gemm g, const Sched& S, const Epi& E) {
;     ...
;             PG8_WAIT_V(8); PG8_WAIT_L(0); PG8_BAR; PG8_MMA(1, 0, At, B0); PG8_MMA(1, 1, At, B1); PG8_BAR; PG8_SCHED;
;             PG8_LDB(B0, 1, 0); PG8_LDB(B1, 1, 1); PG8_SCHED; PG8_LDA(At, 1, 0); PG8_STAGE(PG8_SA(0, 1), a2 + hstepA, voffA);
;             PG8_WAIT_V(8); PG8_WAIT_L(0); PG8_BAR; PG8_MMA(0, 0, At, B0); PG8_MMA(0, 1, At, B1); PG8_BAR; PG8_SCHED;
	v_mfma_f32_16x16x32_bf16 v[64:67], v[132:135], v[164:167], v[64:67]
	v_mfma_f32_16x16x32_bf16 v[64:67], v[136:139], v[168:171], v[64:67]
	v_mfma_f32_16x16x32_bf16 v[60:63], v[140:143], v[164:167], v[60:63]
	v_mfma_f32_16x16x32_bf16 v[60:63], v[144:147], v[168:171], v[60:63]
	v_mfma_f32_16x16x32_bf16 v[44:47], v[140:143], v[210:213], v[44:47]
	v_mfma_f32_16x16x32_bf16 v[44:47], v[144:147], v[214:217], v[44:47]
	v_mfma_f32_16x16x32_bf16 v[48:51], v[132:135], v[210:213], v[48:51]
	v_mfma_f32_16x16x32_bf16 v[48:51], v[136:139], v[214:217], v[48:51]
	v_mfma_f32_16x16x32_bf16 v[32:35], v[132:135], v[218:221], v[32:35]
	v_mfma_f32_16x16x32_bf16 v[32:35], v[136:139], v[222:225], v[32:35]
	v_mfma_f32_16x16x32_bf16 v[28:31], v[140:143], v[218:221], v[28:31]
	v_mfma_f32_16x16x32_bf16 v[28:31], v[144:147], v[222:225], v[28:31]
	v_mfma_f32_16x16x32_bf16 v[12:15], v[140:143], v[226:229], v[12:15]
	v_mfma_f32_16x16x32_bf16 v[12:15], v[144:147], v[230:233], v[12:15]
	v_mfma_f32_16x16x32_bf16 v[16:19], v[132:135], v[226:229], v[16:19]
	v_mfma_f32_16x16x32_bf16 v[16:19], v[136:139], v[230:233], v[16:19]
	v_mfma_f32_16x16x32_bf16 v[56:59], v[148:151], v[164:167], v[56:59]
	v_mfma_f32_16x16x32_bf16 v[56:59], v[152:155], v[168:171], v[56:59]
	v_mfma_f32_16x16x32_bf16 v[52:55], v[156:159], v[164:167], v[52:55]
	v_mfma_f32_16x16x32_bf16 v[52:55], v[160:163], v[168:171], v[52:55]
	v_mfma_f32_16x16x32_bf16 v[36:39], v[156:159], v[210:213], v[36:39]
	v_mfma_f32_16x16x32_bf16 v[36:39], v[160:163], v[214:217], v[36:39]
	v_mfma_f32_16x16x32_bf16 v[40:43], v[148:151], v[210:213], v[40:43]
	v_mfma_f32_16x16x32_bf16 v[40:43], v[152:155], v[214:217], v[40:43]
	v_mfma_f32_16x16x32_bf16 v[24:27], v[148:151], v[218:221], v[24:27]
	v_mfma_f32_16x16x32_bf16 v[24:27], v[152:155], v[222:225], v[24:27]
	v_mfma_f32_16x16x32_bf16 v[20:23], v[156:159], v[218:221], v[20:23]
	v_mfma_f32_16x16x32_bf16 v[20:23], v[160:163], v[222:225], v[20:23]
	v_mfma_f32_16x16x32_bf16 v[4:7], v[156:159], v[226:229], v[4:7]
	v_mfma_f32_16x16x32_bf16 v[4:7], v[160:163], v[230:233], v[4:7]
	v_mfma_f32_16x16x32_bf16 v[8:11], v[148:151], v[226:229], v[8:11]
	v_mfma_f32_16x16x32_bf16 v[8:11], v[152:155], v[230:233], v[8:11]
	s_barrier
	v_add_u32_e32 v144, s52, v206
	v_add_u32_e32 v160, s53, v206
	ds_read_b128 v[132:135], v144
	ds_read_b128 v[136:139], v144 offset:1024
	ds_read_b128 v[140:143], v144 offset:2048
	ds_read_b128 v[144:147], v144 offset:3072
	ds_read_b128 v[148:151], v160
	ds_read_b128 v[152:155], v160 offset:1024
	ds_read_b128 v[156:159], v160 offset:2048
	ds_read_b128 v[160:163], v160 offset:3072
	s_add_u32 s30, s30, 0x2b0000
	s_addc_u32 s31, s31, 0
	s_mov_b32 m0, s55
	v_lshl_add_u64 v[242:243], s[30:31], 0, v[172:173]
	ds_read_b128 v[164:167], v207 offset:32768
	ds_read_b128 v[168:171], v207 offset:33792
	ds_read_b128 v[210:213], v207 offset:34816
	ds_read_b128 v[214:217], v207 offset:35840
	ds_read_b128 v[218:221], v207 offset:36864
	ds_read_b128 v[222:225], v207 offset:37888
	ds_read_b128 v[226:229], v207 offset:38912
	ds_read_b128 v[230:233], v207 offset:39936
	global_load_lds_dwordx4 v[242:243], off
	v_lshl_add_u64 v[242:243], s[30:31], 0, v[176:177]
	s_mov_b32 m0, s56
	s_nop 0
	global_load_lds_dwordx4 v[242:243], off
	s_waitcnt vmcnt(8)
	s_waitcnt lgkmcnt(0)
	s_barrier
	v_mfma_f32_16x16x32_bf16 v[128:131], v[132:135], v[164:167], v[128:131]
	v_mfma_f32_16x16x32_bf16 v[128:131], v[136:139], v[168:171], v[128:131]
	v_mfma_f32_16x16x32_bf16 v[124:127], v[140:143], v[164:167], v[124:127]
	v_mfma_f32_16x16x32_bf16 v[124:127], v[144:147], v[168:171], v[124:127]
	v_mfma_f32_16x16x32_bf16 v[96:99], v[140:143], v[210:213], v[96:99]
	v_mfma_f32_16x16x32_bf16 v[96:99], v[144:147], v[214:217], v[96:99]
	v_mfma_f32_16x16x32_bf16 v[100:103], v[132:135], v[210:213], v[100:103]
	v_mfma_f32_16x16x32_bf16 v[100:103], v[136:139], v[214:217], v[100:103]
	v_mfma_f32_16x16x32_bf16 v[112:115], v[132:135], v[218:221], v[112:115]
	v_mfma_f32_16x16x32_bf16 v[112:115], v[136:139], v[222:225], v[112:115]
	v_mfma_f32_16x16x32_bf16 v[108:111], v[140:143], v[218:221], v[108:111]
	v_mfma_f32_16x16x32_bf16 v[108:111], v[144:147], v[222:225], v[108:111]
	v_mfma_f32_16x16x32_bf16 v[76:79], v[140:143], v[226:229], v[76:79]
	v_mfma_f32_16x16x32_bf16 v[76:79], v[144:147], v[230:233], v[76:79]
	v_mfma_f32_16x16x32_bf16 v[80:83], v[132:135], v[226:229], v[80:83]
	v_mfma_f32_16x16x32_bf16 v[80:83], v[136:139], v[230:233], v[80:83]
	v_mfma_f32_16x16x32_bf16 v[120:123], v[148:151], v[164:167], v[120:123]
	v_mfma_f32_16x16x32_bf16 v[120:123], v[152:155], v[168:171], v[120:123]
	v_mfma_f32_16x16x32_bf16 v[116:119], v[156:159], v[164:167], v[116:119]
	v_mfma_f32_16x16x32_bf16 v[116:119], v[160:163], v[168:171], v[116:119]
	v_mfma_f32_16x16x32_bf16 v[88:91], v[156:159], v[210:213], v[88:91]
	v_mfma_f32_16x16x32_bf16 v[88:91], v[160:163], v[214:217], v[88:91]
	v_mfma_f32_16x16x32_bf16 v[92:95], v[148:151], v[210:213], v[92:95]
	v_mfma_f32_16x16x32_bf16 v[92:95], v[152:155], v[214:217], v[92:95]
	v_mfma_f32_16x16x32_bf16 v[104:107], v[148:151], v[218:221], v[104:107]
	v_mfma_f32_16x16x32_bf16 v[104:107], v[152:155], v[222:225], v[104:107]
	v_mfma_f32_16x16x32_bf16 v[84:87], v[156:159], v[218:221], v[84:87]
	v_mfma_f32_16x16x32_bf16 v[84:87], v[160:163], v[222:225], v[84:87]
	v_mfma_f32_16x16x32_bf16 v[68:71], v[156:159], v[226:229], v[68:71]
	v_mfma_f32_16x16x32_bf16 v[68:71], v[160:163], v[230:233], v[68:71]
	v_mfma_f32_16x16x32_bf16 v[72:75], v[148:151], v[226:229], v[72:75]
	v_mfma_f32_16x16x32_bf16 v[72:75], v[152:155], v[230:233], v[72:75]
	s_barrier
; #define PG8_STAGE(bufoff, gbase, voff) do { _Pragma("unroll") for (int _i = 0; _i < 2; ++_i) \
;         __builtin_amdgcn_global_load_lds((const unsigned*)((const char*)(gbase) + (voff)[_i]), (PG8_LAS unsigned*)(lds + (bufoff) + ldsw + _i * 8192), 16, 0, 0); } while (0)
; #define PG8_LDA(dst, b, h) do { _Pragma("unroll") for (int m = 0; m < 4; ++m) _Pragma("unroll") for (int k = 0; k < 2; ++k) dst[m][k] = *(const PG8_LAS bf16x8*)(lds + PG8_SA(b, h) + aoff + m * 2048 + k * 1024); } while (0)
; #define PG8_MMA(ai, bj, At, Bt) do { __builtin_amdgcn_s_setprio(3); _Pragma("unroll") for (int m = 0; m < 4; ++m) _Pragma("unroll") for (int n = 0; n < 2; ++n) _Pragma("unroll") for (int k = 0; k < 2; ++k) \
;         acc[ai][bj][m][n] = __builtin_amdgcn_mfma_f32_16x16x32_bf16(Bt[n][k], At[m][k], acc[ai][bj][m][n], 0, 0, 0); __builtin_amdgcn_s_setprio(0); } while (0)
; #define PG8_WAIT_V(n) asm volatile("s_waitcnt vmcnt(" #n ")" ::: "memory")
; #define PG8_WAIT_L(n) asm volatile("s_waitcnt lgkmcnt(" #n ")" ::: "memory")
; #define PG8_BAR __builtin_amdgcn_s_barrier()
; #define PG8_SCHED __builtin_amdgcn_sched_barrier(0)
; template <class Epi, class Sched, bool ALIGN_EPI = false, bool SP2 = false>
; __device__ __forceinline__ void gemm_phase(PG8_LAS unsigned char* lds, const Gemm g, const Sched& S, const Epi& E) {
;     ...
;             PG8_LDA(At, 1, 1); PG8_STAGE(PG8_SB(1, 0), b3, voffB); PG8_STAGE(PG8_SB(1, 1), b3 + hstepB, voffB); PG8_STAGE(PG8_SA(1, 0), a3, voffA);
;             PG8_WAIT_V(8); PG8_WAIT_L(0); PG8_BAR; PG8_MMA(1, 0, At, B0); PG8_MMA(1, 1, At, B1); PG8_BAR; PG8_SCHED;
	s_mov_b32 m0, s77
	v_lshl_add_u64 v[234:235], v[234:235], 0, s[4:5]
	s_add_u32 s28, s28, 0x2b0080
	ds_read_b128 v[164:167], v207 offset:49152
	ds_read_b128 v[168:171], v207 offset:50176
	ds_read_b128 v[210:213], v207 offset:51200
	ds_read_b128 v[214:217], v207 offset:52224
	ds_read_b128 v[218:221], v207 offset:53248
	ds_read_b128 v[222:225], v207 offset:54272
	ds_read_b128 v[226:229], v207 offset:55296
	ds_read_b128 v[230:233], v207 offset:56320
	global_load_lds_dwordx4 v[234:235], off
	v_lshl_add_u64 v[234:235], v[236:237], 0, s[4:5]
	s_mov_b32 m0, s78
	s_addc_u32 s29, s29, 0
	global_load_lds_dwordx4 v[234:235], off
	v_lshl_add_u64 v[234:235], s[28:29], 0, v[174:175]
	s_mov_b32 m0, s79
	s_nop 0
	global_load_lds_dwordx4 v[234:235], off
	v_lshl_add_u64 v[234:235], s[28:29], 0, v[178:179]
	s_mov_b32 m0, s80
	s_nop 0
	global_load_lds_dwordx4 v[234:235], off
	v_lshl_add_u64 v[234:235], v[238:239], 0, s[4:5]
	s_mov_b32 m0, s57
	s_nop 0
	global_load_lds_dwordx4 v[234:235], off
	v_lshl_add_u64 v[234:235], v[240:241], 0, s[4:5]
	s_mov_b32 m0, s58
	s_nop 0
	global_load_lds_dwordx4 v[234:235], off
	s_waitcnt vmcnt(8)
	s_waitcnt lgkmcnt(0)
	s_barrier
	v_mfma_f32_16x16x32_bf16 v[64:67], v[132:135], v[164:167], v[64:67]
	v_mfma_f32_16x16x32_bf16 v[64:67], v[136:139], v[168:171], v[64:67]
	v_mfma_f32_16x16x32_bf16 v[60:63], v[140:143], v[164:167], v[60:63]
	v_mfma_f32_16x16x32_bf16 v[60:63], v[144:147], v[168:171], v[60:63]
	v_mfma_f32_16x16x32_bf16 v[44:47], v[140:143], v[210:213], v[44:47]
	v_mfma_f32_16x16x32_bf16 v[44:47], v[144:147], v[214:217], v[44:47]
	v_mfma_f32_16x16x32_bf16 v[48:51], v[132:135], v[210:213], v[48:51]
	v_mfma_f32_16x16x32_bf16 v[48:51], v[136:139], v[214:217], v[48:51]
	v_mfma_f32_16x16x32_bf16 v[32:35], v[132:135], v[218:221], v[32:35]
	v_mfma_f32_16x16x32_bf16 v[32:35], v[136:139], v[222:225], v[32:35]
	v_mfma_f32_16x16x32_bf16 v[28:31], v[140:143], v[218:221], v[28:31]
	v_mfma_f32_16x16x32_bf16 v[28:31], v[144:147], v[222:225], v[28:31]
	v_mfma_f32_16x16x32_bf16 v[12:15], v[140:143], v[226:229], v[12:15]
	v_mfma_f32_16x16x32_bf16 v[12:15], v[144:147], v[230:233], v[12:15]
	v_mfma_f32_16x16x32_bf16 v[16:19], v[132:135], v[226:229], v[16:19]
	v_mfma_f32_16x16x32_bf16 v[16:19], v[136:139], v[230:233], v[16:19]
	v_mfma_f32_16x16x32_bf16 v[56:59], v[148:151], v[164:167], v[56:59]
	v_mfma_f32_16x16x32_bf16 v[56:59], v[152:155], v[168:171], v[56:59]
	v_mfma_f32_16x16x32_bf16 v[52:55], v[156:159], v[164:167], v[52:55]
	v_mfma_f32_16x16x32_bf16 v[52:55], v[160:163], v[168:171], v[52:55]
	v_mfma_f32_16x16x32_bf16 v[36:39], v[156:159], v[210:213], v[36:39]
	v_mfma_f32_16x16x32_bf16 v[36:39], v[160:163], v[214:217], v[36:39]
	v_mfma_f32_16x16x32_bf16 v[40:43], v[148:151], v[210:213], v[40:43]
	v_mfma_f32_16x16x32_bf16 v[40:43], v[152:155], v[214:217], v[40:43]
	v_mfma_f32_16x16x32_bf16 v[24:27], v[148:151], v[218:221], v[24:27]
	v_mfma_f32_16x16x32_bf16 v[24:27], v[152:155], v[222:225], v[24:27]
	v_mfma_f32_16x16x32_bf16 v[20:23], v[156:159], v[218:221], v[20:23]
	v_mfma_f32_16x16x32_bf16 v[20:23], v[160:163], v[222:225], v[20:23]
	v_mfma_f32_16x16x32_bf16 v[4:7], v[156:159], v[226:229], v[4:7]
	v_mfma_f32_16x16x32_bf16 v[4:7], v[160:163], v[230:233], v[4:7]
	v_mfma_f32_16x16x32_bf16 v[8:11], v[148:151], v[226:229], v[8:11]
	v_mfma_f32_16x16x32_bf16 v[8:11], v[152:155], v[230:233], v[8:11]
	s_barrier
	s_add_i32 s61, s61, 2
	s_add_u32 s12, s12, 0x100
	s_addc_u32 s13, s13, 0
	s_cmpk_gt_u32 s61, 0xa9
	s_cbranch_scc1 .LBB0_978

; #define PG8_STAGE(bufoff, gbase, voff) do { _Pragma("unroll") for (int _i = 0; _i < 2; ++_i) \
;         __builtin_amdgcn_global_load_lds((const unsigned*)((const char*)(gbase) + (voff)[_i]), (PG8_LAS unsigned*)(lds + (bufoff) + ldsw + _i * 8192), 16, 0, 0); } while (0)
; #define PG8_LDA(dst, b, h) do { _Pragma("unroll") for (int m = 0; m < 4; ++m) _Pragma("unroll") for (int k = 0; k < 2; ++k) dst[m][k] = *(const PG8_LAS bf16x8*)(lds + PG8_SA(b, h) + aoff + m * 2048 + k * 1024); } while (0)
; #define PG8_LDB(dst, b, h) do { _Pragma("unroll") for (int n = 0; n < 2; ++n) _Pragma("unroll") for (int k = 0; k < 2; ++k) dst[n][k] = *(const PG8_LAS bf16x8*)(lds + PG8_SB(b, h) + boff + n * 2048 + k * 1024); } while (0)
; #define PG8_MMA(ai, bj, At, Bt) do { __builtin_amdgcn_s_setprio(3); _Pragma("unroll") for (int m = 0; m < 4; ++m) _Pragma("unroll") for (int n = 0; n < 2; ++n) _Pragma("unroll") for (int k = 0; k < 2; ++k) \
;         acc[ai][bj][m][n] = __builtin_amdgcn_mfma_f32_16x16x32_bf16(Bt[n][k], At[m][k], acc[ai][bj][m][n], 0, 0, 0); __builtin_amdgcn_s_setprio(0); } while (0)
; #define PG8_WAIT_V(n) asm volatile("s_waitcnt vmcnt(" #n ")" ::: "memory")
; #define PG8_WAIT_L(n) asm volatile("s_waitcnt lgkmcnt(" #n ")" ::: "memory")
; #define PG8_BAR __builtin_amdgcn_s_barrier()
; template <class Epi, class Sched, bool ALIGN_EPI = false, bool SP2 = false>
; __device__ __forceinline__ void gemm_phase(PG8_LAS unsigned char* lds, const Gemm g, const Sched& S, const Epi& E) {
;     ...
;             const bool last = (t == nt - 2);
;             const char* a1 = cA + (size_t)(t + 1) * kstep;
;             const char* a2 = last ? nA : cA + (size_t)(t + 2) * kstep; const char* b2 = last ? nB : cB + (size_t)(t + 2) * kstep;
;             const char* a3 = a2 + kstep; const char* b3 = b2 + kstep;
;             if (last && has_next) S.a_ready(nxt);
;             if constexpr (Epi::MIDK) { if (t == E.midk_step(nt)) E.midk(acc, cur, wr, wc, fr, fq); }
;             if constexpr (SP2) {
;             PG8_LDB(B0, 0, 0); PG8_LDB(B1, 0, 1); PG8_SCHED; PG8_LDA(At, 0, 0); PG8_STAGE(PG8_SA(1, 1), a1 + hstepA, voffA);
;             PG8_WAIT_V(8); PG8_WAIT_L(0); PG8_BAR; PG8_MMA(0, 0, At, B0); PG8_MMA(0, 1, At, B1); PG8_BAR; PG8_SCHED;
;             PG8_LDA(At, 0, 1); PG8_STAGE(PG8_SB(0, 0), b2, voffB); PG8_STAGE(PG8_SB(0, 1), b2 + hstepB, voffB); PG8_STAGE(PG8_SA(0, 0), a2, voffA);
.LBB0_1018:
	v_add_u32_e32 v142, s46, v189
	v_add_u32_e32 v158, s47, v189
	s_add_u32 s40, s20, s22
	ds_read_b128 v[130:133], v142
	ds_read_b128 v[134:137], v142 offset:1024
	ds_read_b128 v[138:141], v142 offset:2048
	ds_read_b128 v[142:145], v142 offset:3072
	ds_read_b128 v[146:149], v158
	ds_read_b128 v[150:153], v158 offset:1024
	ds_read_b128 v[154:157], v158 offset:2048
	ds_read_b128 v[158:161], v158 offset:3072
	s_addc_u32 s41, s21, s23
	s_add_u32 s40, s40, 0x21500100
	s_addc_u32 s41, s41, 0
	s_add_u32 s87, s44, s22
	s_addc_u32 s88, s45, s23
	s_cmpk_eq_i32 s22, 0x5500
	s_cselect_b32 s43, s17, s41
	s_cselect_b32 s42, s16, s40
	s_cselect_b32 s41, s11, s88
	s_cselect_b32 s40, s10, s87
	s_mov_b32 m0, s77
	v_lshl_add_u64 v[186:187], v[0:1], 0, s[22:23]
	ds_read_b128 v[162:165], v180
	ds_read_b128 v[166:169], v180 offset:1024
	ds_read_b128 v[182:185], v180 offset:2048
	ds_read_b128 v[190:193], v180 offset:3072
	ds_read_b128 v[194:197], v180 offset:4096
	ds_read_b128 v[208:211], v180 offset:5120
	ds_read_b128 v[212:215], v180 offset:6144
	ds_read_b128 v[216:219], v180 offset:7168
	global_load_lds_dwordx4 v[186:187], off
	v_lshl_add_u64 v[186:187], v[170:171], 0, s[22:23]
	s_mov_b32 m0, s78
	s_nop 0
	global_load_lds_dwordx4 v[186:187], off
	s_waitcnt vmcnt(8)
	s_waitcnt lgkmcnt(0)
	s_barrier
	v_mfma_f32_16x16x32_bf16 v[126:129], v[130:133], v[162:165], v[126:129]
	v_mfma_f32_16x16x32_bf16 v[126:129], v[134:137], v[166:169], v[126:129]
	v_mfma_f32_16x16x32_bf16 v[122:125], v[138:141], v[162:165], v[122:125]
	v_mfma_f32_16x16x32_bf16 v[122:125], v[142:145], v[166:169], v[122:125]
	v_mfma_f32_16x16x32_bf16 v[94:97], v[138:141], v[182:185], v[94:97]
	v_mfma_f32_16x16x32_bf16 v[94:97], v[142:145], v[190:193], v[94:97]
	v_mfma_f32_16x16x32_bf16 v[98:101], v[130:133], v[182:185], v[98:101]
	v_mfma_f32_16x16x32_bf16 v[98:101], v[134:137], v[190:193], v[98:101]
	v_mfma_f32_16x16x32_bf16 v[110:113], v[130:133], v[194:197], v[110:113]
	v_mfma_f32_16x16x32_bf16 v[110:113], v[134:137], v[208:211], v[110:113]
	v_mfma_f32_16x16x32_bf16 v[106:109], v[138:141], v[194:197], v[106:109]
	v_mfma_f32_16x16x32_bf16 v[106:109], v[142:145], v[208:211], v[106:109]
	v_mfma_f32_16x16x32_bf16 v[74:77], v[138:141], v[212:215], v[74:77]
	v_mfma_f32_16x16x32_bf16 v[74:77], v[142:145], v[216:219], v[74:77]
	v_mfma_f32_16x16x32_bf16 v[78:81], v[130:133], v[212:215], v[78:81]
	v_mfma_f32_16x16x32_bf16 v[78:81], v[134:137], v[216:219], v[78:81]
	v_mfma_f32_16x16x32_bf16 v[118:121], v[146:149], v[162:165], v[118:121]
	v_mfma_f32_16x16x32_bf16 v[118:121], v[150:153], v[166:169], v[118:121]
	v_mfma_f32_16x16x32_bf16 v[114:117], v[154:157], v[162:165], v[114:117]
	v_mfma_f32_16x16x32_bf16 v[114:117], v[158:161], v[166:169], v[114:117]
	v_mfma_f32_16x16x32_bf16 v[86:89], v[154:157], v[182:185], v[86:89]
	v_mfma_f32_16x16x32_bf16 v[86:89], v[158:161], v[190:193], v[86:89]
	v_mfma_f32_16x16x32_bf16 v[90:93], v[146:149], v[182:185], v[90:93]
	v_mfma_f32_16x16x32_bf16 v[90:93], v[150:153], v[190:193], v[90:93]
	v_mfma_f32_16x16x32_bf16 v[102:105], v[146:149], v[194:197], v[102:105]
	v_mfma_f32_16x16x32_bf16 v[102:105], v[150:153], v[208:211], v[102:105]
	v_mfma_f32_16x16x32_bf16 v[82:85], v[154:157], v[194:197], v[82:85]
	v_mfma_f32_16x16x32_bf16 v[82:85], v[158:161], v[208:211], v[82:85]
	v_mfma_f32_16x16x32_bf16 v[66:69], v[154:157], v[212:215], v[66:69]
	v_mfma_f32_16x16x32_bf16 v[66:69], v[158:161], v[216:219], v[66:69]
	v_mfma_f32_16x16x32_bf16 v[70:73], v[146:149], v[212:215], v[70:73]
	v_mfma_f32_16x16x32_bf16 v[70:73], v[150:153], v[216:219], v[70:73]
	s_barrier
	s_mov_b32 m0, s79
	v_lshl_add_u64 v[186:187], s[40:41], 0, v[174:175]
	s_add_u32 s88, s40, 0x2b0000
	ds_read_b128 v[162:165], v180 offset:16384
	ds_read_b128 v[166:169], v180 offset:17408
	ds_read_b128 v[182:185], v180 offset:18432
	ds_read_b128 v[190:193], v180 offset:19456
	ds_read_b128 v[194:197], v180 offset:20480
	ds_read_b128 v[208:211], v180 offset:21504
	ds_read_b128 v[212:215], v180 offset:22528
	ds_read_b128 v[216:219], v180 offset:23552
	global_load_lds_dwordx4 v[186:187], off
	v_lshl_add_u64 v[198:199], s[40:41], 0, v[178:179]
	s_mov_b32 m0, s80
	s_addc_u32 s89, s41, 0
	global_load_lds_dwordx4 v[198:199], off
	v_lshl_add_u64 v[204:205], s[88:89], 0, v[174:175]
	s_mov_b32 m0, s81
	v_lshl_add_u64 v[220:221], s[42:43], 0, v[176:177]
	global_load_lds_dwordx4 v[204:205], off
	v_lshl_add_u64 v[204:205], s[88:89], 0, v[178:179]
	s_mov_b32 m0, s82
	s_nop 0
	global_load_lds_dwordx4 v[204:205], off
	v_lshl_add_u64 v[204:205], s[42:43], 0, v[172:173]
	s_mov_b32 m0, s58
	s_nop 0
	global_load_lds_dwordx4 v[204:205], off
	s_mov_b32 m0, s60
	s_nop 0
	global_load_lds_dwordx4 v[220:221], off
	s_waitcnt vmcnt(8)
	s_waitcnt lgkmcnt(0)
	s_barrier
; #define PG8_STAGE(bufoff, gbase, voff) do { _Pragma("unroll") for (int _i = 0; _i < 2; ++_i) \
;         __builtin_amdgcn_global_load_lds((const unsigned*)((const char*)(gbase) + (voff)[_i]), (PG8_LAS unsigned*)(lds + (bufoff) + ldsw + _i * 8192), 16, 0, 0); } while (0)
; #define PG8_LDA(dst, b, h) do { _Pragma("unroll") for (int m = 0; m < 4; ++m) _Pragma("unroll") for (int k = 0; k < 2; ++k) dst[m][k] = *(const PG8_LAS bf16x8*)(lds + PG8_SA(b, h) + aoff + m * 2048 + k * 1024); } while (0)
; #define PG8_LDB(dst, b, h) do { _Pragma("unroll") for (int n = 0; n < 2; ++n) _Pragma("unroll") for (int k = 0; k < 2; ++k) dst[n][k] = *(const PG8_LAS bf16x8*)(lds + PG8_SB(b, h) + boff + n * 2048 + k * 1024); } while (0)
; #define PG8_MMA(ai, bj, At, Bt) do { __builtin_amdgcn_s_setprio(3); _Pragma("unroll") for (int m = 0; m < 4; ++m) _Pragma("unroll") for (int n = 0; n < 2; ++n) _Pragma("unroll") for (int k = 0; k < 2; ++k) \
;         acc[ai][bj][m][n] = __builtin_amdgcn_mfma_f32_16x16x32_bf16(Bt[n][k], At[m][k], acc[ai][bj][m][n], 0, 0, 0); __builtin_amdgcn_s_setprio(0); } while (0)
; #define PG8_WAIT_V(n) asm volatile("s_waitcnt vmcnt(" #n ")" ::: "memory")
; #define PG8_WAIT_L(n) asm volatile("s_waitcnt lgkmcnt(" #n ")" ::: "memory")
; #define PG8_BAR __builtin_amdgcn_s_barrier()
; #define PG8_SCHED __builtin_amdgcn_sched_barrier(0)
; template <class Epi, class Sched, bool ALIGN_EPI = false, bool SP2 = false>
; __device__ __forceinline__ void gemm_phase(PG8_LAS unsigned char* lds, const Gemm g, const Sched& S, const Epi& E) {
;     ...
;             PG8_WAIT_V(8); PG8_WAIT_L(0); PG8_BAR; PG8_MMA(1, 0, At, B0); PG8_MMA(1, 1, At, B1); PG8_BAR; PG8_SCHED;
;             PG8_LDB(B0, 1, 0); PG8_LDB(B1, 1, 1); PG8_SCHED; PG8_LDA(At, 1, 0); PG8_STAGE(PG8_SA(0, 1), a2 + hstepA, voffA);
;             PG8_WAIT_V(8); PG8_WAIT_L(0); PG8_BAR; PG8_MMA(0, 0, At, B0); PG8_MMA(0, 1, At, B1); PG8_BAR; PG8_SCHED;
	v_mfma_f32_16x16x32_bf16 v[62:65], v[130:133], v[162:165], v[62:65]
	v_mfma_f32_16x16x32_bf16 v[62:65], v[134:137], v[166:169], v[62:65]
	v_mfma_f32_16x16x32_bf16 v[58:61], v[138:141], v[162:165], v[58:61]
	v_mfma_f32_16x16x32_bf16 v[58:61], v[142:145], v[166:169], v[58:61]
	v_mfma_f32_16x16x32_bf16 v[42:45], v[138:141], v[182:185], v[42:45]
	v_mfma_f32_16x16x32_bf16 v[42:45], v[142:145], v[190:193], v[42:45]
	v_mfma_f32_16x16x32_bf16 v[46:49], v[130:133], v[182:185], v[46:49]
	v_mfma_f32_16x16x32_bf16 v[46:49], v[134:137], v[190:193], v[46:49]
	v_mfma_f32_16x16x32_bf16 v[30:33], v[130:133], v[194:197], v[30:33]
	v_mfma_f32_16x16x32_bf16 v[30:33], v[134:137], v[208:211], v[30:33]
	v_mfma_f32_16x16x32_bf16 v[26:29], v[138:141], v[194:197], v[26:29]
	v_mfma_f32_16x16x32_bf16 v[26:29], v[142:145], v[208:211], v[26:29]
	v_mfma_f32_16x16x32_bf16 v[10:13], v[138:141], v[212:215], v[10:13]
	v_mfma_f32_16x16x32_bf16 v[10:13], v[142:145], v[216:219], v[10:13]
	v_mfma_f32_16x16x32_bf16 v[14:17], v[130:133], v[212:215], v[14:17]
	v_mfma_f32_16x16x32_bf16 v[14:17], v[134:137], v[216:219], v[14:17]
	v_mfma_f32_16x16x32_bf16 v[54:57], v[146:149], v[162:165], v[54:57]
	v_mfma_f32_16x16x32_bf16 v[54:57], v[150:153], v[166:169], v[54:57]
	v_mfma_f32_16x16x32_bf16 v[50:53], v[154:157], v[162:165], v[50:53]
	v_mfma_f32_16x16x32_bf16 v[50:53], v[158:161], v[166:169], v[50:53]
	v_mfma_f32_16x16x32_bf16 v[34:37], v[154:157], v[182:185], v[34:37]
	v_mfma_f32_16x16x32_bf16 v[34:37], v[158:161], v[190:193], v[34:37]
	v_mfma_f32_16x16x32_bf16 v[38:41], v[146:149], v[182:185], v[38:41]
	v_mfma_f32_16x16x32_bf16 v[38:41], v[150:153], v[190:193], v[38:41]
	v_mfma_f32_16x16x32_bf16 v[22:25], v[146:149], v[194:197], v[22:25]
	v_mfma_f32_16x16x32_bf16 v[22:25], v[150:153], v[208:211], v[22:25]
	v_mfma_f32_16x16x32_bf16 v[18:21], v[154:157], v[194:197], v[18:21]
	v_mfma_f32_16x16x32_bf16 v[18:21], v[158:161], v[208:211], v[18:21]
	v_mfma_f32_16x16x32_bf16 v[2:5], v[154:157], v[212:215], v[2:5]
	v_mfma_f32_16x16x32_bf16 v[2:5], v[158:161], v[216:219], v[2:5]
	v_mfma_f32_16x16x32_bf16 v[6:9], v[146:149], v[212:215], v[6:9]
	v_mfma_f32_16x16x32_bf16 v[6:9], v[150:153], v[216:219], v[6:9]
	s_barrier
	v_add_u32_e32 v142, s52, v189
	v_add_u32_e32 v158, s53, v189
	ds_read_b128 v[130:133], v142
	ds_read_b128 v[134:137], v142 offset:1024
	ds_read_b128 v[138:141], v142 offset:2048
	ds_read_b128 v[142:145], v142 offset:3072
	ds_read_b128 v[146:149], v158
	ds_read_b128 v[150:153], v158 offset:1024
	ds_read_b128 v[154:157], v158 offset:2048
	ds_read_b128 v[158:161], v158 offset:3072
	s_add_u32 s42, s42, 0x2b0000
	s_addc_u32 s43, s43, 0
	s_mov_b32 m0, s61
	v_lshl_add_u64 v[222:223], s[42:43], 0, v[172:173]
	ds_read_b128 v[162:165], v180 offset:32768
	ds_read_b128 v[166:169], v180 offset:33792
	ds_read_b128 v[182:185], v180 offset:34816
	ds_read_b128 v[190:193], v180 offset:35840
	ds_read_b128 v[194:197], v180 offset:36864
	ds_read_b128 v[208:211], v180 offset:37888
	ds_read_b128 v[212:215], v180 offset:38912
	ds_read_b128 v[216:219], v180 offset:39936
	global_load_lds_dwordx4 v[222:223], off
	v_lshl_add_u64 v[222:223], s[42:43], 0, v[176:177]
	s_mov_b32 m0, s62
	s_nop 0
	global_load_lds_dwordx4 v[222:223], off
	s_waitcnt vmcnt(8)
	s_waitcnt lgkmcnt(0)
	s_barrier
	v_mfma_f32_16x16x32_bf16 v[126:129], v[130:133], v[162:165], v[126:129]
	v_mfma_f32_16x16x32_bf16 v[126:129], v[134:137], v[166:169], v[126:129]
	v_mfma_f32_16x16x32_bf16 v[122:125], v[138:141], v[162:165], v[122:125]
	v_mfma_f32_16x16x32_bf16 v[122:125], v[142:145], v[166:169], v[122:125]
	v_mfma_f32_16x16x32_bf16 v[94:97], v[138:141], v[182:185], v[94:97]
	v_mfma_f32_16x16x32_bf16 v[94:97], v[142:145], v[190:193], v[94:97]
	v_mfma_f32_16x16x32_bf16 v[98:101], v[130:133], v[182:185], v[98:101]
	v_mfma_f32_16x16x32_bf16 v[98:101], v[134:137], v[190:193], v[98:101]
	v_mfma_f32_16x16x32_bf16 v[110:113], v[130:133], v[194:197], v[110:113]
	v_mfma_f32_16x16x32_bf16 v[110:113], v[134:137], v[208:211], v[110:113]
	v_mfma_f32_16x16x32_bf16 v[106:109], v[138:141], v[194:197], v[106:109]
	v_mfma_f32_16x16x32_bf16 v[106:109], v[142:145], v[208:211], v[106:109]
	v_mfma_f32_16x16x32_bf16 v[74:77], v[138:141], v[212:215], v[74:77]
	v_mfma_f32_16x16x32_bf16 v[74:77], v[142:145], v[216:219], v[74:77]
	v_mfma_f32_16x16x32_bf16 v[78:81], v[130:133], v[212:215], v[78:81]
	v_mfma_f32_16x16x32_bf16 v[78:81], v[134:137], v[216:219], v[78:81]
	v_mfma_f32_16x16x32_bf16 v[118:121], v[146:149], v[162:165], v[118:121]
	v_mfma_f32_16x16x32_bf16 v[118:121], v[150:153], v[166:169], v[118:121]
	v_mfma_f32_16x16x32_bf16 v[114:117], v[154:157], v[162:165], v[114:117]
	v_mfma_f32_16x16x32_bf16 v[114:117], v[158:161], v[166:169], v[114:117]
	v_mfma_f32_16x16x32_bf16 v[86:89], v[154:157], v[182:185], v[86:89]
	v_mfma_f32_16x16x32_bf16 v[86:89], v[158:161], v[190:193], v[86:89]
	v_mfma_f32_16x16x32_bf16 v[90:93], v[146:149], v[182:185], v[90:93]
	v_mfma_f32_16x16x32_bf16 v[90:93], v[150:153], v[190:193], v[90:93]
	v_mfma_f32_16x16x32_bf16 v[102:105], v[146:149], v[194:197], v[102:105]
	v_mfma_f32_16x16x32_bf16 v[102:105], v[150:153], v[208:211], v[102:105]
	v_mfma_f32_16x16x32_bf16 v[82:85], v[154:157], v[194:197], v[82:85]
	v_mfma_f32_16x16x32_bf16 v[82:85], v[158:161], v[208:211], v[82:85]
	v_mfma_f32_16x16x32_bf16 v[66:69], v[154:157], v[212:215], v[66:69]
	v_mfma_f32_16x16x32_bf16 v[66:69], v[158:161], v[216:219], v[66:69]
	v_mfma_f32_16x16x32_bf16 v[70:73], v[146:149], v[212:215], v[70:73]
	v_mfma_f32_16x16x32_bf16 v[70:73], v[150:153], v[216:219], v[70:73]
	s_barrier
; #define PG8_STAGE(bufoff, gbase, voff) do { _Pragma("unroll") for (int _i = 0; _i < 2; ++_i) \
;         __builtin_amdgcn_global_load_lds((const unsigned*)((const char*)(gbase) + (voff)[_i]), (PG8_LAS unsigned*)(lds + (bufoff) + ldsw + _i * 8192), 16, 0, 0); } while (0)
; #define PG8_LDA(dst, b, h) do { _Pragma("unroll") for (int m = 0; m < 4; ++m) _Pragma("unroll") for (int k = 0; k < 2; ++k) dst[m][k] = *(const PG8_LAS bf16x8*)(lds + PG8_SA(b, h) + aoff + m * 2048 + k * 1024); } while (0)
; #define PG8_MMA(ai, bj, At, Bt) do { __builtin_amdgcn_s_setprio(3); _Pragma("unroll") for (int m = 0; m < 4; ++m) _Pragma("unroll") for (int n = 0; n < 2; ++n) _Pragma("unroll") for (int k = 0; k < 2; ++k) \
;         acc[ai][bj][m][n] = __builtin_amdgcn_mfma_f32_16x16x32_bf16(Bt[n][k], At[m][k], acc[ai][bj][m][n], 0, 0, 0); __builtin_amdgcn_s_setprio(0); } while (0)
; #define PG8_WAIT_V(n) asm volatile("s_waitcnt vmcnt(" #n ")" ::: "memory")
; #define PG8_WAIT_L(n) asm volatile("s_waitcnt lgkmcnt(" #n ")" ::: "memory")
; #define PG8_BAR __builtin_amdgcn_s_barrier()
; #define PG8_SCHED __builtin_amdgcn_sched_barrier(0)
; template <class Epi, class Sched, bool ALIGN_EPI = false, bool SP2 = false>
; __device__ __forceinline__ void gemm_phase(PG8_LAS unsigned char* lds, const Gemm g, const Sched& S, const Epi& E) {
;     ...
;             PG8_LDA(At, 1, 1); PG8_STAGE(PG8_SB(1, 0), b3, voffB); PG8_STAGE(PG8_SB(1, 1), b3 + hstepB, voffB); PG8_STAGE(PG8_SA(1, 0), a3, voffA);
;             PG8_WAIT_V(8); PG8_WAIT_L(0); PG8_BAR; PG8_MMA(1, 0, At, B0); PG8_MMA(1, 1, At, B1); PG8_BAR; PG8_SCHED;
	s_mov_b32 m0, s83
	v_lshl_add_u64 v[186:187], v[186:187], 0, s[18:19]
	s_add_u32 s40, s40, 0x2b0080
	ds_read_b128 v[162:165], v180 offset:49152
	ds_read_b128 v[166:169], v180 offset:50176
	ds_read_b128 v[182:185], v180 offset:51200
	ds_read_b128 v[190:193], v180 offset:52224
	ds_read_b128 v[194:197], v180 offset:53248
	ds_read_b128 v[208:211], v180 offset:54272
	ds_read_b128 v[212:215], v180 offset:55296
	ds_read_b128 v[216:219], v180 offset:56320
	global_load_lds_dwordx4 v[186:187], off
	v_lshl_add_u64 v[186:187], v[198:199], 0, s[18:19]
	s_mov_b32 m0, s84
	s_addc_u32 s41, s41, 0
	global_load_lds_dwordx4 v[186:187], off
	v_lshl_add_u64 v[186:187], s[40:41], 0, v[174:175]
	s_mov_b32 m0, s85
	s_nop 0
	global_load_lds_dwordx4 v[186:187], off
	v_lshl_add_u64 v[186:187], s[40:41], 0, v[178:179]
	s_mov_b32 m0, s86
	s_nop 0
	global_load_lds_dwordx4 v[186:187], off
	v_lshl_add_u64 v[186:187], v[204:205], 0, s[18:19]
	s_mov_b32 m0, s63
	s_nop 0
	global_load_lds_dwordx4 v[186:187], off
	v_lshl_add_u64 v[186:187], v[220:221], 0, s[18:19]
	s_mov_b32 m0, s64
	s_nop 0
	global_load_lds_dwordx4 v[186:187], off
	s_waitcnt vmcnt(8)
	s_waitcnt lgkmcnt(0)
	s_barrier
	v_mfma_f32_16x16x32_bf16 v[62:65], v[130:133], v[162:165], v[62:65]
	v_mfma_f32_16x16x32_bf16 v[62:65], v[134:137], v[166:169], v[62:65]
	v_mfma_f32_16x16x32_bf16 v[58:61], v[138:141], v[162:165], v[58:61]
	v_mfma_f32_16x16x32_bf16 v[58:61], v[142:145], v[166:169], v[58:61]
	v_mfma_f32_16x16x32_bf16 v[42:45], v[138:141], v[182:185], v[42:45]
	v_mfma_f32_16x16x32_bf16 v[42:45], v[142:145], v[190:193], v[42:45]
	v_mfma_f32_16x16x32_bf16 v[46:49], v[130:133], v[182:185], v[46:49]
	v_mfma_f32_16x16x32_bf16 v[46:49], v[134:137], v[190:193], v[46:49]
	v_mfma_f32_16x16x32_bf16 v[30:33], v[130:133], v[194:197], v[30:33]
	v_mfma_f32_16x16x32_bf16 v[30:33], v[134:137], v[208:211], v[30:33]
	v_mfma_f32_16x16x32_bf16 v[26:29], v[138:141], v[194:197], v[26:29]
	v_mfma_f32_16x16x32_bf16 v[26:29], v[142:145], v[208:211], v[26:29]
	v_mfma_f32_16x16x32_bf16 v[10:13], v[138:141], v[212:215], v[10:13]
	v_mfma_f32_16x16x32_bf16 v[10:13], v[142:145], v[216:219], v[10:13]
	v_mfma_f32_16x16x32_bf16 v[14:17], v[130:133], v[212:215], v[14:17]
	v_mfma_f32_16x16x32_bf16 v[14:17], v[134:137], v[216:219], v[14:17]
	v_mfma_f32_16x16x32_bf16 v[54:57], v[146:149], v[162:165], v[54:57]
	v_mfma_f32_16x16x32_bf16 v[54:57], v[150:153], v[166:169], v[54:57]
	v_mfma_f32_16x16x32_bf16 v[50:53], v[154:157], v[162:165], v[50:53]
	v_mfma_f32_16x16x32_bf16 v[50:53], v[158:161], v[166:169], v[50:53]
	v_mfma_f32_16x16x32_bf16 v[34:37], v[154:157], v[182:185], v[34:37]
	v_mfma_f32_16x16x32_bf16 v[34:37], v[158:161], v[190:193], v[34:37]
	v_mfma_f32_16x16x32_bf16 v[38:41], v[146:149], v[182:185], v[38:41]
	v_mfma_f32_16x16x32_bf16 v[38:41], v[150:153], v[190:193], v[38:41]
	v_mfma_f32_16x16x32_bf16 v[22:25], v[146:149], v[194:197], v[22:25]
	v_mfma_f32_16x16x32_bf16 v[22:25], v[150:153], v[208:211], v[22:25]
	v_mfma_f32_16x16x32_bf16 v[18:21], v[154:157], v[194:197], v[18:21]
	v_mfma_f32_16x16x32_bf16 v[18:21], v[158:161], v[208:211], v[18:21]
	v_mfma_f32_16x16x32_bf16 v[2:5], v[154:157], v[212:215], v[2:5]
	v_mfma_f32_16x16x32_bf16 v[2:5], v[158:161], v[216:219], v[2:5]
	v_mfma_f32_16x16x32_bf16 v[6:9], v[146:149], v[212:215], v[6:9]
	v_mfma_f32_16x16x32_bf16 v[6:9], v[150:153], v[216:219], v[6:9]
	s_barrier
	s_add_i32 s67, s67, 2
	s_add_u32 s22, s22, 0x100
	s_addc_u32 s23, s23, 0
	s_cmpk_gt_u32 s67, 0xa9
	s_cbranch_scc1 .LBB0_1021
